# zeroing-free tile loops extended to the memkv, phase 6, 7, 9 and 11 GEMM loops; on v079
# baseline (speedup 1.0000x reference)
.LBB0_341:
	s_ashr_i32 s9, s8, 31
	v_cmp_lt_i64_e64 s[48:49], s[10:11], 64
	s_lshl_b64 s[10:11], s[8:9], 19
	s_add_u32 s10, s82, s10
	s_addc_u32 s11, s83, s11
	s_and_b64 s[12:13], s[48:49], exec
	s_cselect_b32 s9, s11, s45
	s_cselect_b32 s63, s10, s44
	s_ashr_i32 s7, s6, 31
	s_lshl_b64 s[12:13], s[6:7], 19
	s_add_u32 s12, s80, s12
	s_addc_u32 s13, s81, s13
	s_and_b64 s[48:49], s[48:49], exec
	s_cselect_b32 s7, s13, s47
	s_cselect_b32 s64, s12, s46
	s_add_u32 s44, s44, 0x40080
	s_addc_u32 s45, s45, 0
	s_add_u32 s65, s46, 0x100
	s_addc_u32 s66, s47, 0
	s_mov_b32 s67, -2
.LBB0_342:
	ds_read_b128 v[146:149], v143
	ds_read_b128 v[150:153], v143 offset:1024
	ds_read_b128 v[154:157], v143 offset:2048
	ds_read_b128 v[158:161], v143 offset:3072
	s_add_u32 s46, s44, 0xfffc0080
	s_addc_u32 s47, s45, -1
	s_cmp_eq_u32 s67, 12
	s_cselect_b32 s49, s9, s47
	s_cselect_b32 s48, s63, s46
	s_cselect_b32 s47, s7, s66
	s_cselect_b32 s46, s64, s65
	v_lshl_add_u64 v[190:191], s[44:45], 0, v[136:137]
	s_add_i32 m0, s43, 0xc000
	ds_read_b128 v[162:165], v144
	ds_read_b128 v[166:169], v144 offset:1024
	ds_read_b128 v[170:173], v144 offset:2048
	ds_read_b128 v[174:177], v144 offset:3072
	ds_read_b128 v[178:181], v144 offset:4096
	ds_read_b128 v[182:185], v144 offset:5120
	ds_read_b128 v[186:189], v144 offset:6144
	ds_read_b128 v[196:199], v144 offset:7168
	global_load_lds_dwordx4 v[190:191], off
	v_lshl_add_u64 v[190:191], s[44:45], 0, v[138:139]
	s_add_i32 m0, s43, 0xe000
	s_nop 0
	global_load_lds_dwordx4 v[190:191], off
	s_waitcnt lgkmcnt(8)
	s_barrier
	s_waitcnt lgkmcnt(0)
	s_setprio 1
	s_waitcnt lgkmcnt(0)
	s_cmp_eq_u32 s67, -2
	s_cbranch_scc1 .Lzmk_0_first
	v_mfma_f32_16x16x32_bf16 v[124:127], v[146:149], v[162:165], v[124:127]
	v_mfma_f32_16x16x32_bf16 v[120:123], v[154:157], v[162:165], v[120:123]
	v_mfma_f32_16x16x32_bf16 v[108:111], v[146:149], v[170:173], v[108:111]
	v_mfma_f32_16x16x32_bf16 v[104:107], v[154:157], v[170:173], v[104:107]
	v_mfma_f32_16x16x32_bf16 v[92:95], v[146:149], v[178:181], v[92:95]
	v_mfma_f32_16x16x32_bf16 v[88:91], v[154:157], v[178:181], v[88:91]
	v_mfma_f32_16x16x32_bf16 v[76:79], v[146:149], v[186:189], v[76:79]
	v_mfma_f32_16x16x32_bf16 v[72:75], v[154:157], v[186:189], v[72:75]
	v_mfma_f32_16x16x32_bf16 v[124:127], v[150:153], v[166:169], v[124:127]
	v_mfma_f32_16x16x32_bf16 v[120:123], v[158:161], v[166:169], v[120:123]
	v_mfma_f32_16x16x32_bf16 v[108:111], v[150:153], v[174:177], v[108:111]
	v_mfma_f32_16x16x32_bf16 v[104:107], v[158:161], v[174:177], v[104:107]
	v_mfma_f32_16x16x32_bf16 v[92:95], v[150:153], v[182:185], v[92:95]
	v_mfma_f32_16x16x32_bf16 v[88:91], v[158:161], v[182:185], v[88:91]
	v_mfma_f32_16x16x32_bf16 v[76:79], v[150:153], v[196:199], v[76:79]
	v_mfma_f32_16x16x32_bf16 v[72:75], v[158:161], v[196:199], v[72:75]
.Lzmk_0_join:
	s_setprio 0
	s_barrier
	s_add_i32 s84, s60, s50
	v_lshl_add_u64 v[190:191], s[46:47], 0, v[132:133]
	s_mov_b32 m0, s84
	ds_read_b128 v[200:203], v145
	ds_read_b128 v[204:207], v145 offset:1024
	ds_read_b128 v[208:211], v145 offset:2048
	ds_read_b128 v[212:215], v145 offset:3072
	global_load_lds_dwordx4 v[190:191], off
	v_lshl_add_u64 v[216:217], s[46:47], 0, v[128:129]
	s_add_i32 m0, s84, 0x2000
	s_nop 0
	global_load_lds_dwordx4 v[216:217], off
	s_barrier
	s_waitcnt lgkmcnt(0)
	s_setprio 1
	s_waitcnt lgkmcnt(0)
	s_cmp_eq_u32 s67, -2
	s_cbranch_scc1 .Lzmk_1_first
	v_mfma_f32_16x16x32_bf16 v[116:119], v[200:203], v[162:165], v[116:119]
	v_mfma_f32_16x16x32_bf16 v[112:115], v[208:211], v[162:165], v[112:115]
	v_mfma_f32_16x16x32_bf16 v[100:103], v[200:203], v[170:173], v[100:103]
	v_mfma_f32_16x16x32_bf16 v[96:99], v[208:211], v[170:173], v[96:99]
	v_mfma_f32_16x16x32_bf16 v[84:87], v[200:203], v[178:181], v[84:87]
	v_mfma_f32_16x16x32_bf16 v[80:83], v[208:211], v[178:181], v[80:83]
	v_mfma_f32_16x16x32_bf16 v[68:71], v[200:203], v[186:189], v[68:71]
	v_mfma_f32_16x16x32_bf16 v[64:67], v[208:211], v[186:189], v[64:67]
	v_mfma_f32_16x16x32_bf16 v[116:119], v[204:207], v[166:169], v[116:119]
	v_mfma_f32_16x16x32_bf16 v[112:115], v[212:215], v[166:169], v[112:115]
	v_mfma_f32_16x16x32_bf16 v[100:103], v[204:207], v[174:177], v[100:103]
	v_mfma_f32_16x16x32_bf16 v[96:99], v[212:215], v[174:177], v[96:99]
	v_mfma_f32_16x16x32_bf16 v[84:87], v[204:207], v[182:185], v[84:87]
	v_mfma_f32_16x16x32_bf16 v[80:83], v[212:215], v[182:185], v[80:83]
	v_mfma_f32_16x16x32_bf16 v[68:71], v[204:207], v[196:199], v[68:71]
	v_mfma_f32_16x16x32_bf16 v[64:67], v[212:215], v[196:199], v[64:67]
.Lzmk_1_join:
	s_setprio 0
	s_mov_b32 m0, s43
	v_lshl_add_u64 v[218:219], s[48:49], 0, v[134:135]
	s_barrier
	ds_read_b128 v[162:165], v144 offset:16384
	ds_read_b128 v[166:169], v144 offset:17408
	ds_read_b128 v[170:173], v144 offset:18432
	ds_read_b128 v[174:177], v144 offset:19456
	ds_read_b128 v[178:181], v144 offset:20480
	ds_read_b128 v[182:185], v144 offset:21504
	ds_read_b128 v[186:189], v144 offset:22528
	ds_read_b128 v[196:199], v144 offset:23552
	global_load_lds_dwordx4 v[218:219], off
	v_lshl_add_u64 v[220:221], s[48:49], 0, v[130:131]
	s_mov_b32 m0, s52
	s_nop 0
	global_load_lds_dwordx4 v[220:221], off
	s_barrier
	s_waitcnt lgkmcnt(0)
	s_setprio 1
	s_waitcnt lgkmcnt(0)
	s_cmp_eq_u32 s67, -2
	s_cbranch_scc1 .Lzmk_2_first
	v_mfma_f32_16x16x32_bf16 v[60:63], v[146:149], v[162:165], v[60:63]
	v_mfma_f32_16x16x32_bf16 v[56:59], v[154:157], v[162:165], v[56:59]
	v_mfma_f32_16x16x32_bf16 v[44:47], v[146:149], v[170:173], v[44:47]
	v_mfma_f32_16x16x32_bf16 v[40:43], v[154:157], v[170:173], v[40:43]
	v_mfma_f32_16x16x32_bf16 v[28:31], v[146:149], v[178:181], v[28:31]
	v_mfma_f32_16x16x32_bf16 v[24:27], v[154:157], v[178:181], v[24:27]
	v_mfma_f32_16x16x32_bf16 v[12:15], v[146:149], v[186:189], v[12:15]
	v_mfma_f32_16x16x32_bf16 v[8:11], v[154:157], v[186:189], v[8:11]
	v_mfma_f32_16x16x32_bf16 v[60:63], v[150:153], v[166:169], v[60:63]
	v_mfma_f32_16x16x32_bf16 v[56:59], v[158:161], v[166:169], v[56:59]
	v_mfma_f32_16x16x32_bf16 v[44:47], v[150:153], v[174:177], v[44:47]
	v_mfma_f32_16x16x32_bf16 v[40:43], v[158:161], v[174:177], v[40:43]
	v_mfma_f32_16x16x32_bf16 v[28:31], v[150:153], v[182:185], v[28:31]
	v_mfma_f32_16x16x32_bf16 v[24:27], v[158:161], v[182:185], v[24:27]
	v_mfma_f32_16x16x32_bf16 v[12:15], v[150:153], v[196:199], v[12:15]
	v_mfma_f32_16x16x32_bf16 v[8:11], v[158:161], v[196:199], v[8:11]
.Lzmk_2_join:
	s_setprio 0
	s_barrier
	s_add_u32 s84, s46, 0x10000
	s_addc_u32 s85, s47, 0
	s_add_i32 s89, s61, s50
	v_lshl_add_u64 v[146:147], s[84:85], 0, v[132:133]
	s_mov_b32 m0, s89
	s_nop 0
	global_load_lds_dwordx4 v[146:147], off
	v_lshl_add_u64 v[146:147], s[84:85], 0, v[128:129]
	s_add_i32 m0, s89, 0x2000
	s_nop 0
	global_load_lds_dwordx4 v[146:147], off
	s_waitcnt vmcnt(6)
	s_barrier
	s_setprio 1
	s_cmp_eq_u32 s67, -2
	s_cbranch_scc1 .Lzmk_3_first
	v_mfma_f32_16x16x32_bf16 v[52:55], v[200:203], v[162:165], v[52:55]
	v_mfma_f32_16x16x32_bf16 v[48:51], v[208:211], v[162:165], v[48:51]
	v_mfma_f32_16x16x32_bf16 v[36:39], v[200:203], v[170:173], v[36:39]
	v_mfma_f32_16x16x32_bf16 v[32:35], v[208:211], v[170:173], v[32:35]
	v_mfma_f32_16x16x32_bf16 v[20:23], v[200:203], v[178:181], v[20:23]
	v_mfma_f32_16x16x32_bf16 v[16:19], v[208:211], v[178:181], v[16:19]
	v_mfma_f32_16x16x32_bf16 v[4:7], v[200:203], v[186:189], v[4:7]
	v_mfma_f32_16x16x32_bf16 v[0:3], v[208:211], v[186:189], v[0:3]
	v_mfma_f32_16x16x32_bf16 v[52:55], v[204:207], v[166:169], v[52:55]
	v_mfma_f32_16x16x32_bf16 v[48:51], v[212:215], v[166:169], v[48:51]
	v_mfma_f32_16x16x32_bf16 v[36:39], v[204:207], v[174:177], v[36:39]
	v_mfma_f32_16x16x32_bf16 v[32:35], v[212:215], v[174:177], v[32:35]
	v_mfma_f32_16x16x32_bf16 v[20:23], v[204:207], v[182:185], v[20:23]
	v_mfma_f32_16x16x32_bf16 v[16:19], v[212:215], v[182:185], v[16:19]
	v_mfma_f32_16x16x32_bf16 v[4:7], v[204:207], v[196:199], v[4:7]
	v_mfma_f32_16x16x32_bf16 v[0:3], v[212:215], v[196:199], v[0:3]
.Lzmk_3_join:
	s_setprio 0
	s_add_i32 s84, 0, 0x18000
	v_add_u32_e32 v158, s84, v141
	s_barrier
	ds_read_b128 v[146:149], v158
	ds_read_b128 v[150:153], v158 offset:1024
	ds_read_b128 v[154:157], v158 offset:2048
	ds_read_b128 v[158:161], v158 offset:3072
	s_add_u32 s48, s48, 0x40000
	s_addc_u32 s49, s49, 0
	s_mov_b32 m0, s53
	v_lshl_add_u64 v[200:201], s[48:49], 0, v[134:135]
	ds_read_b128 v[162:165], v144 offset:32768
	ds_read_b128 v[166:169], v144 offset:33792
	ds_read_b128 v[170:173], v144 offset:34816
	ds_read_b128 v[174:177], v144 offset:35840
	ds_read_b128 v[178:181], v144 offset:36864
	ds_read_b128 v[182:185], v144 offset:37888
	ds_read_b128 v[186:189], v144 offset:38912
	ds_read_b128 v[196:199], v144 offset:39936
	global_load_lds_dwordx4 v[200:201], off
	v_lshl_add_u64 v[200:201], s[48:49], 0, v[130:131]
	s_mov_b32 m0, s54
	s_nop 0
	global_load_lds_dwordx4 v[200:201], off
	s_waitcnt lgkmcnt(8)
	s_barrier
	s_waitcnt lgkmcnt(0)
	s_setprio 1
	s_waitcnt lgkmcnt(0)
	v_mfma_f32_16x16x32_bf16 v[124:127], v[146:149], v[162:165], v[124:127]
	v_mfma_f32_16x16x32_bf16 v[120:123], v[154:157], v[162:165], v[120:123]
	v_mfma_f32_16x16x32_bf16 v[108:111], v[146:149], v[170:173], v[108:111]
	v_mfma_f32_16x16x32_bf16 v[104:107], v[154:157], v[170:173], v[104:107]
	v_mfma_f32_16x16x32_bf16 v[92:95], v[146:149], v[178:181], v[92:95]
	v_mfma_f32_16x16x32_bf16 v[88:91], v[154:157], v[178:181], v[88:91]
	v_mfma_f32_16x16x32_bf16 v[76:79], v[146:149], v[186:189], v[76:79]
	v_mfma_f32_16x16x32_bf16 v[72:75], v[154:157], v[186:189], v[72:75]
	v_mfma_f32_16x16x32_bf16 v[124:127], v[150:153], v[166:169], v[124:127]
	v_mfma_f32_16x16x32_bf16 v[120:123], v[158:161], v[166:169], v[120:123]
	v_mfma_f32_16x16x32_bf16 v[108:111], v[150:153], v[174:177], v[108:111]
	v_mfma_f32_16x16x32_bf16 v[104:107], v[158:161], v[174:177], v[104:107]
	v_mfma_f32_16x16x32_bf16 v[92:95], v[150:153], v[182:185], v[92:95]
	v_mfma_f32_16x16x32_bf16 v[88:91], v[158:161], v[182:185], v[88:91]
	v_mfma_f32_16x16x32_bf16 v[76:79], v[150:153], v[196:199], v[76:79]
	v_mfma_f32_16x16x32_bf16 v[72:75], v[158:161], v[196:199], v[72:75]
	s_setprio 0
	s_barrier
	s_add_i32 s48, 0, 0x1c000
	s_add_i32 s49, s84, s50
	v_add_u32_e32 v195, s48, v141
	v_lshl_add_u64 v[190:191], v[190:191], 0, s[0:1]
	s_mov_b32 m0, s49
	ds_read_b128 v[200:203], v195
	ds_read_b128 v[204:207], v195 offset:1024
	ds_read_b128 v[208:211], v195 offset:2048
	ds_read_b128 v[212:215], v195 offset:3072
	global_load_lds_dwordx4 v[190:191], off
	v_lshl_add_u64 v[190:191], v[216:217], 0, s[0:1]
	s_add_i32 m0, s49, 0x2000
	s_nop 0
	global_load_lds_dwordx4 v[190:191], off
	s_barrier
	s_waitcnt lgkmcnt(0)
	s_setprio 1
	s_waitcnt lgkmcnt(0)
	v_mfma_f32_16x16x32_bf16 v[116:119], v[200:203], v[162:165], v[116:119]
	v_mfma_f32_16x16x32_bf16 v[112:115], v[208:211], v[162:165], v[112:115]
	v_mfma_f32_16x16x32_bf16 v[100:103], v[200:203], v[170:173], v[100:103]
	v_mfma_f32_16x16x32_bf16 v[96:99], v[208:211], v[170:173], v[96:99]
	v_mfma_f32_16x16x32_bf16 v[84:87], v[200:203], v[178:181], v[84:87]
	v_mfma_f32_16x16x32_bf16 v[80:83], v[208:211], v[178:181], v[80:83]
	v_mfma_f32_16x16x32_bf16 v[68:71], v[200:203], v[186:189], v[68:71]
	v_mfma_f32_16x16x32_bf16 v[64:67], v[208:211], v[186:189], v[64:67]
	v_mfma_f32_16x16x32_bf16 v[116:119], v[204:207], v[166:169], v[116:119]
	v_mfma_f32_16x16x32_bf16 v[112:115], v[212:215], v[166:169], v[112:115]
	v_mfma_f32_16x16x32_bf16 v[100:103], v[204:207], v[174:177], v[100:103]
	v_mfma_f32_16x16x32_bf16 v[96:99], v[212:215], v[174:177], v[96:99]
	v_mfma_f32_16x16x32_bf16 v[84:87], v[204:207], v[182:185], v[84:87]
	v_mfma_f32_16x16x32_bf16 v[80:83], v[212:215], v[182:185], v[80:83]
	v_mfma_f32_16x16x32_bf16 v[68:71], v[204:207], v[196:199], v[68:71]
	v_mfma_f32_16x16x32_bf16 v[64:67], v[212:215], v[196:199], v[64:67]
	s_setprio 0
	s_mov_b32 m0, s57
	v_lshl_add_u64 v[190:191], v[218:219], 0, s[0:1]
	s_barrier
	ds_read_b128 v[162:165], v144 offset:49152
	ds_read_b128 v[166:169], v144 offset:50176
	ds_read_b128 v[170:173], v144 offset:51200
	ds_read_b128 v[174:177], v144 offset:52224
	ds_read_b128 v[178:181], v144 offset:53248
	ds_read_b128 v[182:185], v144 offset:54272
	ds_read_b128 v[186:189], v144 offset:55296
	ds_read_b128 v[196:199], v144 offset:56320
	global_load_lds_dwordx4 v[190:191], off
	v_lshl_add_u64 v[190:191], v[220:221], 0, s[0:1]
	s_mov_b32 m0, s58
	s_nop 0
	global_load_lds_dwordx4 v[190:191], off
	s_barrier
	s_waitcnt lgkmcnt(0)
	s_setprio 1
	s_waitcnt lgkmcnt(0)
	v_mfma_f32_16x16x32_bf16 v[60:63], v[146:149], v[162:165], v[60:63]
	v_mfma_f32_16x16x32_bf16 v[56:59], v[154:157], v[162:165], v[56:59]
	v_mfma_f32_16x16x32_bf16 v[44:47], v[146:149], v[170:173], v[44:47]
	v_mfma_f32_16x16x32_bf16 v[40:43], v[154:157], v[170:173], v[40:43]
	v_mfma_f32_16x16x32_bf16 v[28:31], v[146:149], v[178:181], v[28:31]
	v_mfma_f32_16x16x32_bf16 v[24:27], v[154:157], v[178:181], v[24:27]
	v_mfma_f32_16x16x32_bf16 v[12:15], v[146:149], v[186:189], v[12:15]
	v_mfma_f32_16x16x32_bf16 v[8:11], v[154:157], v[186:189], v[8:11]
	v_mfma_f32_16x16x32_bf16 v[60:63], v[150:153], v[166:169], v[60:63]
	v_mfma_f32_16x16x32_bf16 v[56:59], v[158:161], v[166:169], v[56:59]
	v_mfma_f32_16x16x32_bf16 v[44:47], v[150:153], v[174:177], v[44:47]
	v_mfma_f32_16x16x32_bf16 v[40:43], v[158:161], v[174:177], v[40:43]
	v_mfma_f32_16x16x32_bf16 v[28:31], v[150:153], v[182:185], v[28:31]
	v_mfma_f32_16x16x32_bf16 v[24:27], v[158:161], v[182:185], v[24:27]
	v_mfma_f32_16x16x32_bf16 v[12:15], v[150:153], v[196:199], v[12:15]
	v_mfma_f32_16x16x32_bf16 v[8:11], v[158:161], v[196:199], v[8:11]
	s_setprio 0
	s_barrier
	s_add_u32 s46, s46, 0x10080
	s_addc_u32 s47, s47, 0
	s_add_i32 s48, s48, s50
	v_lshl_add_u64 v[146:147], s[46:47], 0, v[132:133]
	s_mov_b32 m0, s48
	s_nop 0
	global_load_lds_dwordx4 v[146:147], off
	v_lshl_add_u64 v[146:147], s[46:47], 0, v[128:129]
	s_add_i32 m0, s48, 0x2000
	s_nop 0
	global_load_lds_dwordx4 v[146:147], off
	s_waitcnt vmcnt(6)
	s_barrier
	s_setprio 1
	v_mfma_f32_16x16x32_bf16 v[52:55], v[200:203], v[162:165], v[52:55]
	v_mfma_f32_16x16x32_bf16 v[48:51], v[208:211], v[162:165], v[48:51]
	v_mfma_f32_16x16x32_bf16 v[36:39], v[200:203], v[170:173], v[36:39]
	v_mfma_f32_16x16x32_bf16 v[32:35], v[208:211], v[170:173], v[32:35]
	v_mfma_f32_16x16x32_bf16 v[20:23], v[200:203], v[178:181], v[20:23]
	v_mfma_f32_16x16x32_bf16 v[16:19], v[208:211], v[178:181], v[16:19]
	v_mfma_f32_16x16x32_bf16 v[4:7], v[200:203], v[186:189], v[4:7]
	v_mfma_f32_16x16x32_bf16 v[0:3], v[208:211], v[186:189], v[0:3]
	v_mfma_f32_16x16x32_bf16 v[52:55], v[204:207], v[166:169], v[52:55]
	v_mfma_f32_16x16x32_bf16 v[48:51], v[212:215], v[166:169], v[48:51]
	v_mfma_f32_16x16x32_bf16 v[36:39], v[204:207], v[174:177], v[36:39]
	v_mfma_f32_16x16x32_bf16 v[32:35], v[212:215], v[174:177], v[32:35]
	v_mfma_f32_16x16x32_bf16 v[20:23], v[204:207], v[182:185], v[20:23]
	v_mfma_f32_16x16x32_bf16 v[16:19], v[212:215], v[182:185], v[16:19]
	v_mfma_f32_16x16x32_bf16 v[4:7], v[204:207], v[196:199], v[4:7]
	v_mfma_f32_16x16x32_bf16 v[0:3], v[212:215], v[196:199], v[0:3]
	s_setprio 0
	s_add_i32 s67, s67, 2
	s_add_u32 s44, s44, 0x100
	s_addc_u32 s45, s45, 0
	s_add_u32 s65, s65, 0x100
	s_addc_u32 s66, s66, 0
	s_cmp_gt_u32 s67, 13
	s_barrier
	s_cbranch_scc0 .LBB0_342
	s_branch .Lzmk_skip
.Lzmk_0_first:
	v_mfma_f32_16x16x32_bf16 v[124:127], v[146:149], v[162:165], 0
	v_mfma_f32_16x16x32_bf16 v[120:123], v[154:157], v[162:165], 0
	v_mfma_f32_16x16x32_bf16 v[108:111], v[146:149], v[170:173], 0
	v_mfma_f32_16x16x32_bf16 v[104:107], v[154:157], v[170:173], 0
	v_mfma_f32_16x16x32_bf16 v[92:95], v[146:149], v[178:181], 0
	v_mfma_f32_16x16x32_bf16 v[88:91], v[154:157], v[178:181], 0
	v_mfma_f32_16x16x32_bf16 v[76:79], v[146:149], v[186:189], 0
	v_mfma_f32_16x16x32_bf16 v[72:75], v[154:157], v[186:189], 0
	v_mfma_f32_16x16x32_bf16 v[124:127], v[150:153], v[166:169], v[124:127]
	v_mfma_f32_16x16x32_bf16 v[120:123], v[158:161], v[166:169], v[120:123]
	v_mfma_f32_16x16x32_bf16 v[108:111], v[150:153], v[174:177], v[108:111]
	v_mfma_f32_16x16x32_bf16 v[104:107], v[158:161], v[174:177], v[104:107]
	v_mfma_f32_16x16x32_bf16 v[92:95], v[150:153], v[182:185], v[92:95]
	v_mfma_f32_16x16x32_bf16 v[88:91], v[158:161], v[182:185], v[88:91]
	v_mfma_f32_16x16x32_bf16 v[76:79], v[150:153], v[196:199], v[76:79]
	v_mfma_f32_16x16x32_bf16 v[72:75], v[158:161], v[196:199], v[72:75]
	s_branch .Lzmk_0_join
.Lzmk_1_first:
	v_mfma_f32_16x16x32_bf16 v[116:119], v[200:203], v[162:165], 0
	v_mfma_f32_16x16x32_bf16 v[112:115], v[208:211], v[162:165], 0
	v_mfma_f32_16x16x32_bf16 v[100:103], v[200:203], v[170:173], 0
	v_mfma_f32_16x16x32_bf16 v[96:99], v[208:211], v[170:173], 0
	v_mfma_f32_16x16x32_bf16 v[84:87], v[200:203], v[178:181], 0
	v_mfma_f32_16x16x32_bf16 v[80:83], v[208:211], v[178:181], 0
	v_mfma_f32_16x16x32_bf16 v[68:71], v[200:203], v[186:189], 0
	v_mfma_f32_16x16x32_bf16 v[64:67], v[208:211], v[186:189], 0
	v_mfma_f32_16x16x32_bf16 v[116:119], v[204:207], v[166:169], v[116:119]
	v_mfma_f32_16x16x32_bf16 v[112:115], v[212:215], v[166:169], v[112:115]
	v_mfma_f32_16x16x32_bf16 v[100:103], v[204:207], v[174:177], v[100:103]
	v_mfma_f32_16x16x32_bf16 v[96:99], v[212:215], v[174:177], v[96:99]
	v_mfma_f32_16x16x32_bf16 v[84:87], v[204:207], v[182:185], v[84:87]
	v_mfma_f32_16x16x32_bf16 v[80:83], v[212:215], v[182:185], v[80:83]
	v_mfma_f32_16x16x32_bf16 v[68:71], v[204:207], v[196:199], v[68:71]
	v_mfma_f32_16x16x32_bf16 v[64:67], v[212:215], v[196:199], v[64:67]
	s_branch .Lzmk_1_join
.Lzmk_2_first:
	v_mfma_f32_16x16x32_bf16 v[60:63], v[146:149], v[162:165], 0
	v_mfma_f32_16x16x32_bf16 v[56:59], v[154:157], v[162:165], 0
	v_mfma_f32_16x16x32_bf16 v[44:47], v[146:149], v[170:173], 0
	v_mfma_f32_16x16x32_bf16 v[40:43], v[154:157], v[170:173], 0
	v_mfma_f32_16x16x32_bf16 v[28:31], v[146:149], v[178:181], 0
	v_mfma_f32_16x16x32_bf16 v[24:27], v[154:157], v[178:181], 0
	v_mfma_f32_16x16x32_bf16 v[12:15], v[146:149], v[186:189], 0
	v_mfma_f32_16x16x32_bf16 v[8:11], v[154:157], v[186:189], 0
	v_mfma_f32_16x16x32_bf16 v[60:63], v[150:153], v[166:169], v[60:63]
	v_mfma_f32_16x16x32_bf16 v[56:59], v[158:161], v[166:169], v[56:59]
	v_mfma_f32_16x16x32_bf16 v[44:47], v[150:153], v[174:177], v[44:47]
	v_mfma_f32_16x16x32_bf16 v[40:43], v[158:161], v[174:177], v[40:43]
	v_mfma_f32_16x16x32_bf16 v[28:31], v[150:153], v[182:185], v[28:31]
	v_mfma_f32_16x16x32_bf16 v[24:27], v[158:161], v[182:185], v[24:27]
	v_mfma_f32_16x16x32_bf16 v[12:15], v[150:153], v[196:199], v[12:15]
	v_mfma_f32_16x16x32_bf16 v[8:11], v[158:161], v[196:199], v[8:11]
	s_branch .Lzmk_2_join
.Lzmk_3_first:
	v_mfma_f32_16x16x32_bf16 v[52:55], v[200:203], v[162:165], 0
	v_mfma_f32_16x16x32_bf16 v[48:51], v[208:211], v[162:165], 0
	v_mfma_f32_16x16x32_bf16 v[36:39], v[200:203], v[170:173], 0
	v_mfma_f32_16x16x32_bf16 v[32:35], v[208:211], v[170:173], 0
	v_mfma_f32_16x16x32_bf16 v[20:23], v[200:203], v[178:181], 0
	v_mfma_f32_16x16x32_bf16 v[16:19], v[208:211], v[178:181], 0
	v_mfma_f32_16x16x32_bf16 v[4:7], v[200:203], v[186:189], 0
	v_mfma_f32_16x16x32_bf16 v[0:3], v[208:211], v[186:189], 0
	v_mfma_f32_16x16x32_bf16 v[52:55], v[204:207], v[166:169], v[52:55]
	v_mfma_f32_16x16x32_bf16 v[48:51], v[212:215], v[166:169], v[48:51]
	v_mfma_f32_16x16x32_bf16 v[36:39], v[204:207], v[174:177], v[36:39]
	v_mfma_f32_16x16x32_bf16 v[32:35], v[212:215], v[174:177], v[32:35]
	v_mfma_f32_16x16x32_bf16 v[20:23], v[204:207], v[182:185], v[20:23]
	v_mfma_f32_16x16x32_bf16 v[16:19], v[212:215], v[182:185], v[16:19]
	v_mfma_f32_16x16x32_bf16 v[4:7], v[204:207], v[196:199], v[4:7]
	v_mfma_f32_16x16x32_bf16 v[0:3], v[212:215], v[196:199], v[0:3]
	s_branch .Lzmk_3_join
.Lzmk_skip:
	v_cvt_pk_bf16_f32 v124, v124, v125
	v_cvt_pk_bf16_f32 v120, v120, v121
	v_cvt_pk_bf16_f32 v121, v122, v123
	v_cvt_pk_bf16_f32 v122, v116, v117
	v_cvt_pk_bf16_f32 v112, v112, v113
	v_cvt_pk_bf16_f32 v125, v126, v127
	v_cvt_pk_bf16_f32 v118, v118, v119
	v_cvt_pk_bf16_f32 v113, v114, v115
	v_cndmask_b32_e64 v114, v124, v122, s[2:3]
	v_mov_b32_e32 v123, 0
	v_cndmask_b32_e64 v115, v120, v112, s[2:3]
	v_mov_b32_e32 v126, 0
	v_lshl_add_u32 v148, s42, 8, v140
	v_mov_b32_dpp v123, v114 row_ror:8 row_mask:0xf bank_mask:0xf
	v_cndmask_b32_e64 v114, v125, v118, s[2:3]
	v_mov_b32_e32 v119, 0
	v_mov_b32_dpp v126, v115 row_ror:8 row_mask:0xf bank_mask:0xf
	v_mov_b32_e32 v127, 0
	v_mov_b32_dpp v119, v114 row_ror:8 row_mask:0xf bank_mask:0xf
	v_cndmask_b32_e64 v114, v121, v113, s[2:3]
	v_cndmask_b32_e64 v116, v126, v120, s[2:3]
	v_cndmask_b32_e64 v120, v112, v126, s[2:3]
	v_add_u32_e32 v112, -8, v148
	v_mov_b32_dpp v127, v114 row_ror:8 row_mask:0xf bank_mask:0xf
	v_cndmask_b32_e64 v112, v112, v148, s[2:3]
	v_lshl_or_b32 v146, s62, 8, v142
	v_cndmask_b32_e64 v117, v127, v121, s[2:3]
	v_cndmask_b32_e64 v121, v113, v127, s[2:3]
	v_ashrrev_i32_e32 v113, 31, v112
	v_ashrrev_i32_e32 v147, 31, v146
	v_lshlrev_b64 v[112:113], 11, v[112:113]
	v_cndmask_b32_e64 v115, v119, v125, s[2:3]
	v_cndmask_b32_e64 v114, v123, v124, s[2:3]
	v_cndmask_b32_e64 v119, v118, v119, s[2:3]
	v_cndmask_b32_e64 v118, v122, v123, s[2:3]
	v_lshl_add_u64 v[122:123], s[40:41], 0, v[112:113]
	v_lshlrev_b64 v[112:113], 1, v[146:147]
	v_lshl_add_u64 v[122:123], v[122:123], 0, v[112:113]
	global_store_dwordx4 v[122:123], v[114:117], off
	v_cvt_pk_bf16_f32 v108, v108, v109
	v_cvt_pk_bf16_f32 v100, v100, v101
	v_add_u32_e32 v116, 8, v148
	v_cndmask_b32_e64 v114, v148, v116, s[2:3]
	v_ashrrev_i32_e32 v115, 31, v114
	v_lshlrev_b64 v[114:115], 11, v[114:115]
	v_lshl_add_u64 v[114:115], s[40:41], 0, v[114:115]
	v_cvt_pk_bf16_f32 v109, v110, v111
	v_cvt_pk_bf16_f32 v104, v104, v105
	v_cvt_pk_bf16_f32 v105, v106, v107
	v_cvt_pk_bf16_f32 v101, v102, v103
	v_cvt_pk_bf16_f32 v102, v96, v97
	v_cndmask_b32_e64 v96, v108, v100, s[2:3]
	v_mov_b32_e32 v106, 0
	v_lshl_add_u64 v[114:115], v[114:115], 0, v[112:113]
	v_cvt_pk_bf16_f32 v103, v98, v99
	v_mov_b32_dpp v106, v96 row_ror:8 row_mask:0xf bank_mask:0xf
	v_cndmask_b32_e64 v96, v109, v101, s[2:3]
	v_mov_b32_e32 v107, 0
	v_cndmask_b32_e64 v97, v104, v102, s[2:3]
	v_mov_b32_e32 v110, 0
	global_store_dwordx4 v[114:115], v[118:121], off
	v_or_b32_e32 v114, 16, v148
	v_mov_b32_dpp v107, v96 row_ror:8 row_mask:0xf bank_mask:0xf
	v_cndmask_b32_e64 v96, v105, v103, s[2:3]
	v_mov_b32_dpp v110, v97 row_ror:8 row_mask:0xf bank_mask:0xf
	v_mov_b32_e32 v111, 0
	v_cndmask_b32_e64 v98, v110, v104, s[2:3]
	v_cndmask_b32_e64 v104, v116, v114, s[2:3]
	v_mov_b32_dpp v111, v96 row_ror:8 row_mask:0xf bank_mask:0xf
	v_cndmask_b32_e64 v99, v111, v105, s[2:3]
	v_ashrrev_i32_e32 v105, 31, v104
	v_lshlrev_b64 v[104:105], 11, v[104:105]
	v_lshl_add_u64 v[104:105], s[40:41], 0, v[104:105]
	v_cndmask_b32_e64 v97, v107, v109, s[2:3]
	v_cndmask_b32_e64 v96, v106, v108, s[2:3]
	v_lshl_add_u64 v[104:105], v[104:105], 0, v[112:113]
	global_store_dwordx4 v[104:105], v[96:99], off
	v_cvt_pk_bf16_f32 v92, v92, v93
	v_cvt_pk_bf16_f32 v84, v84, v85
	v_add_u32_e32 v98, 24, v148
	v_cndmask_b32_e64 v96, v114, v98, s[2:3]
	v_ashrrev_i32_e32 v97, 31, v96
	v_lshlrev_b64 v[96:97], 11, v[96:97]
	v_lshl_add_u64 v[96:97], s[40:41], 0, v[96:97]
	v_cvt_pk_bf16_f32 v93, v94, v95
	v_cvt_pk_bf16_f32 v88, v88, v89
	v_cvt_pk_bf16_f32 v89, v90, v91
	v_cvt_pk_bf16_f32 v85, v86, v87
	v_cvt_pk_bf16_f32 v86, v80, v81
	v_cndmask_b32_e64 v80, v92, v84, s[2:3]
	v_mov_b32_e32 v90, 0
	v_cndmask_b32_e64 v103, v103, v111, s[2:3]
	v_cndmask_b32_e64 v102, v102, v110, s[2:3]
	v_cndmask_b32_e64 v101, v101, v107, s[2:3]
	v_cndmask_b32_e64 v100, v100, v106, s[2:3]
	v_lshl_add_u64 v[96:97], v[96:97], 0, v[112:113]
	v_cvt_pk_bf16_f32 v87, v82, v83
	v_mov_b32_dpp v90, v80 row_ror:8 row_mask:0xf bank_mask:0xf
	v_cndmask_b32_e64 v80, v93, v85, s[2:3]
	v_mov_b32_e32 v91, 0
	v_cndmask_b32_e64 v81, v88, v86, s[2:3]
	v_mov_b32_e32 v94, 0
	global_store_dwordx4 v[96:97], v[100:103], off
	v_or_b32_e32 v96, 32, v148
	v_mov_b32_dpp v91, v80 row_ror:8 row_mask:0xf bank_mask:0xf
	v_cndmask_b32_e64 v80, v89, v87, s[2:3]
	v_mov_b32_dpp v94, v81 row_ror:8 row_mask:0xf bank_mask:0xf
	v_mov_b32_e32 v95, 0
	v_cndmask_b32_e64 v82, v94, v88, s[2:3]
	v_cndmask_b32_e64 v88, v98, v96, s[2:3]
	v_mov_b32_dpp v95, v80 row_ror:8 row_mask:0xf bank_mask:0xf
	v_cndmask_b32_e64 v83, v95, v89, s[2:3]
	v_ashrrev_i32_e32 v89, 31, v88
	v_lshlrev_b64 v[88:89], 11, v[88:89]
	v_lshl_add_u64 v[88:89], s[40:41], 0, v[88:89]
	v_cndmask_b32_e64 v81, v91, v93, s[2:3]
	v_cndmask_b32_e64 v80, v90, v92, s[2:3]
	v_lshl_add_u64 v[88:89], v[88:89], 0, v[112:113]
	global_store_dwordx4 v[88:89], v[80:83], off
	v_cvt_pk_bf16_f32 v76, v76, v77
	v_cvt_pk_bf16_f32 v68, v68, v69
	v_add_u32_e32 v82, 40, v148
	v_cndmask_b32_e64 v80, v96, v82, s[2:3]
	v_ashrrev_i32_e32 v81, 31, v80
	v_lshlrev_b64 v[80:81], 11, v[80:81]
	v_lshl_add_u64 v[80:81], s[40:41], 0, v[80:81]
	v_cvt_pk_bf16_f32 v77, v78, v79
	v_cvt_pk_bf16_f32 v72, v72, v73
	v_cvt_pk_bf16_f32 v73, v74, v75
	v_cvt_pk_bf16_f32 v69, v70, v71
	v_cvt_pk_bf16_f32 v70, v64, v65
	v_cndmask_b32_e64 v64, v76, v68, s[2:3]
	v_mov_b32_e32 v74, 0
	v_cndmask_b32_e64 v87, v87, v95, s[2:3]
	v_cndmask_b32_e64 v86, v86, v94, s[2:3]
	v_cndmask_b32_e64 v85, v85, v91, s[2:3]
	v_cndmask_b32_e64 v84, v84, v90, s[2:3]
	v_lshl_add_u64 v[80:81], v[80:81], 0, v[112:113]
	v_cvt_pk_bf16_f32 v71, v66, v67
	v_mov_b32_dpp v74, v64 row_ror:8 row_mask:0xf bank_mask:0xf
	v_cndmask_b32_e64 v64, v77, v69, s[2:3]
	v_mov_b32_e32 v75, 0
	v_cndmask_b32_e64 v65, v72, v70, s[2:3]
	v_mov_b32_e32 v78, 0
	global_store_dwordx4 v[80:81], v[84:87], off
	v_or_b32_e32 v80, 48, v148
	v_mov_b32_dpp v75, v64 row_ror:8 row_mask:0xf bank_mask:0xf
	v_cndmask_b32_e64 v64, v73, v71, s[2:3]
	v_mov_b32_dpp v78, v65 row_ror:8 row_mask:0xf bank_mask:0xf
	v_mov_b32_e32 v79, 0
	v_cndmask_b32_e64 v66, v78, v72, s[2:3]
	v_cndmask_b32_e64 v72, v82, v80, s[2:3]
	v_mov_b32_dpp v79, v64 row_ror:8 row_mask:0xf bank_mask:0xf
	v_cndmask_b32_e64 v67, v79, v73, s[2:3]
	v_ashrrev_i32_e32 v73, 31, v72
	v_lshlrev_b64 v[72:73], 11, v[72:73]
	v_lshl_add_u64 v[72:73], s[40:41], 0, v[72:73]
	v_cndmask_b32_e64 v65, v75, v77, s[2:3]
	v_cndmask_b32_e64 v64, v74, v76, s[2:3]
	v_lshl_add_u64 v[72:73], v[72:73], 0, v[112:113]
	global_store_dwordx4 v[72:73], v[64:67], off
	v_cvt_pk_bf16_f32 v60, v60, v61
	v_cvt_pk_bf16_f32 v56, v56, v57
	v_add_u32_e32 v64, 56, v148
	v_cndmask_b32_e64 v64, v80, v64, s[2:3]
	v_ashrrev_i32_e32 v65, 31, v64
	v_lshlrev_b64 v[64:65], 11, v[64:65]
	v_cvt_pk_bf16_f32 v52, v52, v53
	v_cvt_pk_bf16_f32 v53, v54, v55
	v_cvt_pk_bf16_f32 v54, v48, v49
	v_lshl_add_u64 v[64:65], s[40:41], 0, v[64:65]
	v_cvt_pk_bf16_f32 v61, v62, v63
	v_cvt_pk_bf16_f32 v57, v58, v59
	v_cndmask_b32_e64 v48, v60, v52, s[2:3]
	v_mov_b32_e32 v58, 0
	v_cndmask_b32_e64 v49, v56, v54, s[2:3]
	v_mov_b32_e32 v62, 0
	v_cndmask_b32_e64 v71, v71, v79, s[2:3]
	v_cndmask_b32_e64 v70, v70, v78, s[2:3]
	v_cndmask_b32_e64 v69, v69, v75, s[2:3]
	v_cndmask_b32_e64 v68, v68, v74, s[2:3]
	v_lshl_add_u64 v[64:65], v[64:65], 0, v[112:113]
	v_cvt_pk_bf16_f32 v55, v50, v51
	v_mov_b32_dpp v58, v48 row_ror:8 row_mask:0xf bank_mask:0xf
	v_cndmask_b32_e64 v48, v61, v53, s[2:3]
	v_mov_b32_e32 v59, 0
	v_mov_b32_dpp v62, v49 row_ror:8 row_mask:0xf bank_mask:0xf
	global_store_dwordx4 v[64:65], v[68:71], off
	v_add_u32_e32 v64, 0x80, v148
	v_mov_b32_dpp v59, v48 row_ror:8 row_mask:0xf bank_mask:0xf
	v_cndmask_b32_e64 v48, v57, v55, s[2:3]
	v_mov_b32_e32 v63, 0
	v_cndmask_b32_e64 v50, v62, v56, s[2:3]
	v_add_u32_e32 v56, 0x78, v148
	v_mov_b32_dpp v63, v48 row_ror:8 row_mask:0xf bank_mask:0xf
	v_cndmask_b32_e64 v56, v56, v64, s[2:3]
	v_cndmask_b32_e64 v51, v63, v57, s[2:3]
	v_ashrrev_i32_e32 v57, 31, v56
	v_lshlrev_b64 v[56:57], 11, v[56:57]
	v_lshl_add_u64 v[56:57], s[40:41], 0, v[56:57]
	v_cndmask_b32_e64 v49, v59, v61, s[2:3]
	v_cndmask_b32_e64 v48, v58, v60, s[2:3]
	v_lshl_add_u64 v[56:57], v[56:57], 0, v[112:113]
	global_store_dwordx4 v[56:57], v[48:51], off
	v_cvt_pk_bf16_f32 v44, v44, v45
	v_cvt_pk_bf16_f32 v36, v36, v37
	v_add_u32_e32 v50, 0x88, v148
	v_cndmask_b32_e64 v48, v64, v50, s[2:3]
	v_ashrrev_i32_e32 v49, 31, v48
	v_lshlrev_b64 v[48:49], 11, v[48:49]
	v_lshl_add_u64 v[48:49], s[40:41], 0, v[48:49]
	v_cvt_pk_bf16_f32 v45, v46, v47
	v_cvt_pk_bf16_f32 v40, v40, v41
	v_cvt_pk_bf16_f32 v41, v42, v43
	v_cvt_pk_bf16_f32 v37, v38, v39
	v_cvt_pk_bf16_f32 v38, v32, v33
	v_cndmask_b32_e64 v32, v44, v36, s[2:3]
	v_mov_b32_e32 v42, 0
	v_cndmask_b32_e64 v55, v55, v63, s[2:3]
	v_cndmask_b32_e64 v54, v54, v62, s[2:3]
	v_cndmask_b32_e64 v53, v53, v59, s[2:3]
	v_cndmask_b32_e64 v52, v52, v58, s[2:3]
	v_lshl_add_u64 v[48:49], v[48:49], 0, v[112:113]
	v_cvt_pk_bf16_f32 v39, v34, v35
	v_mov_b32_dpp v42, v32 row_ror:8 row_mask:0xf bank_mask:0xf
	v_cndmask_b32_e64 v32, v45, v37, s[2:3]
	v_mov_b32_e32 v43, 0
	v_cndmask_b32_e64 v33, v40, v38, s[2:3]
	v_mov_b32_e32 v46, 0
	global_store_dwordx4 v[48:49], v[52:55], off
	v_add_u32_e32 v48, 0x90, v148
	v_mov_b32_dpp v43, v32 row_ror:8 row_mask:0xf bank_mask:0xf
	v_cndmask_b32_e64 v32, v41, v39, s[2:3]
	v_mov_b32_dpp v46, v33 row_ror:8 row_mask:0xf bank_mask:0xf
	v_mov_b32_e32 v47, 0
	v_cndmask_b32_e64 v34, v46, v40, s[2:3]
	v_cndmask_b32_e64 v40, v50, v48, s[2:3]
	v_mov_b32_dpp v47, v32 row_ror:8 row_mask:0xf bank_mask:0xf
	v_cndmask_b32_e64 v35, v47, v41, s[2:3]
	v_ashrrev_i32_e32 v41, 31, v40
	v_lshlrev_b64 v[40:41], 11, v[40:41]
	v_lshl_add_u64 v[40:41], s[40:41], 0, v[40:41]
	v_cndmask_b32_e64 v33, v43, v45, s[2:3]
	v_cndmask_b32_e64 v32, v42, v44, s[2:3]
	v_lshl_add_u64 v[40:41], v[40:41], 0, v[112:113]
	global_store_dwordx4 v[40:41], v[32:35], off
	v_cvt_pk_bf16_f32 v28, v28, v29
	v_cvt_pk_bf16_f32 v20, v20, v21
	v_add_u32_e32 v34, 0x98, v148
	v_cndmask_b32_e64 v32, v48, v34, s[2:3]
	v_ashrrev_i32_e32 v33, 31, v32
	v_lshlrev_b64 v[32:33], 11, v[32:33]
	v_lshl_add_u64 v[32:33], s[40:41], 0, v[32:33]
	v_cvt_pk_bf16_f32 v29, v30, v31
	v_cvt_pk_bf16_f32 v24, v24, v25
	v_cvt_pk_bf16_f32 v25, v26, v27
	v_cvt_pk_bf16_f32 v21, v22, v23
	v_cvt_pk_bf16_f32 v22, v16, v17
	v_cndmask_b32_e64 v16, v28, v20, s[2:3]
	v_mov_b32_e32 v26, 0
	v_cndmask_b32_e64 v39, v39, v47, s[2:3]
	v_cndmask_b32_e64 v38, v38, v46, s[2:3]
	v_cndmask_b32_e64 v37, v37, v43, s[2:3]
	v_cndmask_b32_e64 v36, v36, v42, s[2:3]
	v_lshl_add_u64 v[32:33], v[32:33], 0, v[112:113]
	v_cvt_pk_bf16_f32 v23, v18, v19
	v_mov_b32_dpp v26, v16 row_ror:8 row_mask:0xf bank_mask:0xf
	v_cndmask_b32_e64 v16, v29, v21, s[2:3]
	v_mov_b32_e32 v27, 0
	v_cndmask_b32_e64 v17, v24, v22, s[2:3]
	v_mov_b32_e32 v30, 0
	global_store_dwordx4 v[32:33], v[36:39], off
	v_add_u32_e32 v32, 0xa0, v148
	v_mov_b32_dpp v27, v16 row_ror:8 row_mask:0xf bank_mask:0xf
	v_cndmask_b32_e64 v16, v25, v23, s[2:3]
	v_mov_b32_dpp v30, v17 row_ror:8 row_mask:0xf bank_mask:0xf
	v_mov_b32_e32 v31, 0
	v_cndmask_b32_e64 v18, v30, v24, s[2:3]
	v_cndmask_b32_e64 v24, v34, v32, s[2:3]
	v_mov_b32_dpp v31, v16 row_ror:8 row_mask:0xf bank_mask:0xf
	v_cndmask_b32_e64 v19, v31, v25, s[2:3]
	v_ashrrev_i32_e32 v25, 31, v24
	v_lshlrev_b64 v[24:25], 11, v[24:25]
	v_lshl_add_u64 v[24:25], s[40:41], 0, v[24:25]
	v_cndmask_b32_e64 v17, v27, v29, s[2:3]
	v_cndmask_b32_e64 v16, v26, v28, s[2:3]
	v_lshl_add_u64 v[24:25], v[24:25], 0, v[112:113]
	global_store_dwordx4 v[24:25], v[16:19], off
	v_cndmask_b32_e64 v23, v23, v31, s[2:3]
	v_cndmask_b32_e64 v22, v22, v30, s[2:3]
	v_add_u32_e32 v18, 0xa8, v148
	v_cndmask_b32_e64 v16, v32, v18, s[2:3]
	v_ashrrev_i32_e32 v17, 31, v16
	v_lshlrev_b64 v[16:17], 11, v[16:17]
	v_lshl_add_u64 v[16:17], s[40:41], 0, v[16:17]
	v_cndmask_b32_e64 v21, v21, v27, s[2:3]
	v_cndmask_b32_e64 v20, v20, v26, s[2:3]
	v_lshl_add_u64 v[16:17], v[16:17], 0, v[112:113]
	global_store_dwordx4 v[16:17], v[20:23], off
	v_add_u32_e32 v16, 0xb0, v148
	v_cvt_pk_bf16_f32 v12, v12, v13
	v_cvt_pk_bf16_f32 v8, v8, v9
	v_cvt_pk_bf16_f32 v9, v10, v11
	v_cvt_pk_bf16_f32 v10, v4, v5
	v_cvt_pk_bf16_f32 v13, v14, v15
	v_cvt_pk_bf16_f32 v6, v6, v7
	v_cvt_pk_bf16_f32 v7, v0, v1
	v_cndmask_b32_e64 v0, v12, v10, s[2:3]
	v_mov_b32_e32 v14, 0
	v_cndmask_b32_e64 v4, v18, v16, s[2:3]
	v_cvt_pk_bf16_f32 v11, v2, v3
	v_mov_b32_dpp v14, v0 row_ror:8 row_mask:0xf bank_mask:0xf
	v_cndmask_b32_e64 v0, v13, v6, s[2:3]
	v_mov_b32_e32 v15, 0
	v_ashrrev_i32_e32 v5, 31, v4
	v_cndmask_b32_e64 v1, v8, v7, s[2:3]
	v_mov_b32_dpp v15, v0 row_ror:8 row_mask:0xf bank_mask:0xf
	v_cndmask_b32_e64 v0, v9, v11, s[2:3]
	v_mov_b32_e32 v17, 0
	v_mov_b32_e32 v19, 0
	v_lshlrev_b64 v[4:5], 11, v[4:5]
	v_mov_b32_dpp v17, v1 row_ror:8 row_mask:0xf bank_mask:0xf
	v_mov_b32_dpp v19, v0 row_ror:8 row_mask:0xf bank_mask:0xf
	v_lshl_add_u64 v[4:5], s[40:41], 0, v[4:5]
	v_cndmask_b32_e64 v3, v19, v9, s[2:3]
	v_cndmask_b32_e64 v2, v17, v8, s[2:3]
	v_cndmask_b32_e64 v1, v15, v13, s[2:3]
	v_cndmask_b32_e64 v0, v14, v12, s[2:3]
	v_lshl_add_u64 v[4:5], v[4:5], 0, v[112:113]
	global_store_dwordx4 v[4:5], v[0:3], off
	s_and_b64 vcc, exec, s[4:5]
	s_mov_b32 s62, s6
	v_add_u32_e32 v0, 0xb8, v148
	v_cndmask_b32_e64 v0, v16, v0, s[2:3]
	v_ashrrev_i32_e32 v1, 31, v0
	v_lshlrev_b64 v[0:1], 11, v[0:1]
	v_lshl_add_u64 v[0:1], s[40:41], 0, v[0:1]
	v_lshl_add_u64 v[4:5], v[0:1], 0, v[112:113]
	v_cndmask_b32_e64 v3, v11, v19, s[2:3]
	v_cndmask_b32_e64 v2, v7, v17, s[2:3]
	v_cndmask_b32_e64 v1, v6, v15, s[2:3]
	v_cndmask_b32_e64 v0, v10, v14, s[2:3]
	s_mov_b32 s42, s8
	s_mov_b64 s[46:47], s[12:13]
	s_mov_b64 s[44:45], s[10:11]
	global_store_dwordx4 v[4:5], v[0:3], off
	s_cbranch_vccz .LBB0_335
	s_waitcnt vmcnt(0)
	s_cmpk_gt_u32 s17, 0xff
	s_cbranch_scc1 .LBB0_346
	s_barrier

.LBB0_739:
	s_ashr_i32 s57, s56, 31
	v_cmp_lt_i64_e32 vcc, s[58:59], v[208:209]
	s_lshl_b64 s[58:59], s[56:57], 19
	s_add_u32 s58, s68, s58
	s_addc_u32 s59, s69, s59
	s_and_b64 s[60:61], vcc, exec
	s_cselect_b32 s9, s59, s11
	s_cselect_b32 s13, s58, s10
	s_ashr_i32 s55, s54, 31
	s_lshl_b64 s[60:61], s[54:55], 19
	s_add_u32 s60, s76, s60
	s_addc_u32 s61, s77, s61
	s_and_b64 s[64:65], vcc, exec
	s_cselect_b32 s17, s61, s63
	s_cselect_b32 s44, s60, s62
	s_add_u32 s10, s10, 0x40080
	s_addc_u32 s11, s11, 0
	s_add_u32 s55, s62, 0x100
	s_addc_u32 s57, s63, 0
	s_mov_b32 s92, -2
	s_waitcnt lgkmcnt(0)
.LBB0_740:
	ds_read_b128 v[64:67], v221
	ds_read_b128 v[68:71], v221 offset:1024
	ds_read_b128 v[84:87], v221 offset:2048
	ds_read_b128 v[92:95], v221 offset:3072
	s_add_u32 s28, s10, 0xfffc0080
	s_addc_u32 s29, s11, -1
	s_cmp_eq_u32 s92, 12
	s_cselect_b32 s65, s9, s29
	s_cselect_b32 s64, s13, s28
	s_cselect_b32 s63, s17, s57
	s_cselect_b32 s62, s44, s55
	v_lshl_add_u64 v[176:177], s[10:11], 0, v[204:205]
	s_add_i32 m0, s78, 0xc000
	ds_read_b128 v[144:147], v222
	ds_read_b128 v[148:151], v222 offset:1024
	ds_read_b128 v[152:155], v222 offset:2048
	ds_read_b128 v[156:159], v222 offset:3072
	ds_read_b128 v[160:163], v222 offset:4096
	ds_read_b128 v[164:167], v222 offset:5120
	ds_read_b128 v[168:171], v222 offset:6144
	ds_read_b128 v[172:175], v222 offset:7168
	global_load_lds_dwordx4 v[176:177], off
	v_lshl_add_u64 v[176:177], s[10:11], 0, v[206:207]
	s_add_i32 m0, s78, 0xe000
	s_nop 0
	global_load_lds_dwordx4 v[176:177], off
	s_waitcnt lgkmcnt(8)
	s_barrier
	s_waitcnt lgkmcnt(0)
	s_setprio 1
	s_waitcnt lgkmcnt(0)
	s_cmp_eq_u32 s92, -2
	s_cbranch_scc1 .Lz6_0_first
	v_mfma_f32_16x16x32_bf16 v[140:143], v[64:67], v[144:147], v[140:143]
	v_mfma_f32_16x16x32_bf16 v[136:139], v[84:87], v[144:147], v[136:139]
	v_mfma_f32_16x16x32_bf16 v[124:127], v[64:67], v[152:155], v[124:127]
	v_mfma_f32_16x16x32_bf16 v[120:123], v[84:87], v[152:155], v[120:123]
	v_mfma_f32_16x16x32_bf16 v[108:111], v[64:67], v[160:163], v[108:111]
	v_mfma_f32_16x16x32_bf16 v[104:107], v[84:87], v[160:163], v[104:107]
	v_mfma_f32_16x16x32_bf16 v[88:91], v[64:67], v[168:171], v[88:91]
	v_mfma_f32_16x16x32_bf16 v[80:83], v[84:87], v[168:171], v[80:83]
	v_mfma_f32_16x16x32_bf16 v[140:143], v[68:71], v[148:151], v[140:143]
	v_mfma_f32_16x16x32_bf16 v[136:139], v[92:95], v[148:151], v[136:139]
	v_mfma_f32_16x16x32_bf16 v[124:127], v[68:71], v[156:159], v[124:127]
	v_mfma_f32_16x16x32_bf16 v[120:123], v[92:95], v[156:159], v[120:123]
	v_mfma_f32_16x16x32_bf16 v[108:111], v[68:71], v[164:167], v[108:111]
	v_mfma_f32_16x16x32_bf16 v[104:107], v[92:95], v[164:167], v[104:107]
	v_mfma_f32_16x16x32_bf16 v[88:91], v[68:71], v[172:175], v[88:91]
	v_mfma_f32_16x16x32_bf16 v[80:83], v[92:95], v[172:175], v[80:83]
.Lz6_0_join:
	s_setprio 0
	s_barrier
	s_add_i32 s28, s89, s67
	v_lshl_add_u64 v[212:213], s[62:63], 0, v[198:199]
	s_mov_b32 m0, s28
	ds_read_b128 v[176:179], v223
	ds_read_b128 v[180:183], v223 offset:1024
	ds_read_b128 v[184:187], v223 offset:2048
	ds_read_b128 v[188:191], v223 offset:3072
	global_load_lds_dwordx4 v[212:213], off
	v_lshl_add_u64 v[214:215], s[62:63], 0, v[202:203]
	s_add_i32 m0, s28, 0x2000
	s_nop 0
	global_load_lds_dwordx4 v[214:215], off
	s_barrier
	s_waitcnt lgkmcnt(0)
	s_setprio 1
	s_waitcnt lgkmcnt(0)
	s_cmp_eq_u32 s92, -2
	s_cbranch_scc1 .Lz6_1_first
	v_mfma_f32_16x16x32_bf16 v[132:135], v[176:179], v[144:147], v[132:135]
	v_mfma_f32_16x16x32_bf16 v[128:131], v[184:187], v[144:147], v[128:131]
	v_mfma_f32_16x16x32_bf16 v[116:119], v[176:179], v[152:155], v[116:119]
	v_mfma_f32_16x16x32_bf16 v[112:115], v[184:187], v[152:155], v[112:115]
	v_mfma_f32_16x16x32_bf16 v[100:103], v[176:179], v[160:163], v[100:103]
	v_mfma_f32_16x16x32_bf16 v[96:99], v[184:187], v[160:163], v[96:99]
	v_mfma_f32_16x16x32_bf16 v[76:79], v[176:179], v[168:171], v[76:79]
	v_mfma_f32_16x16x32_bf16 v[72:75], v[184:187], v[168:171], v[72:75]
	v_mfma_f32_16x16x32_bf16 v[132:135], v[180:183], v[148:151], v[132:135]
	v_mfma_f32_16x16x32_bf16 v[128:131], v[188:191], v[148:151], v[128:131]
	v_mfma_f32_16x16x32_bf16 v[116:119], v[180:183], v[156:159], v[116:119]
	v_mfma_f32_16x16x32_bf16 v[112:115], v[188:191], v[156:159], v[112:115]
	v_mfma_f32_16x16x32_bf16 v[100:103], v[180:183], v[164:167], v[100:103]
	v_mfma_f32_16x16x32_bf16 v[96:99], v[188:191], v[164:167], v[96:99]
	v_mfma_f32_16x16x32_bf16 v[76:79], v[180:183], v[172:175], v[76:79]
	v_mfma_f32_16x16x32_bf16 v[72:75], v[188:191], v[172:175], v[72:75]
.Lz6_1_join:
	s_setprio 0
	s_mov_b32 m0, s78
	v_lshl_add_u64 v[216:217], s[64:65], 0, v[196:197]
	s_barrier
	ds_read_b128 v[144:147], v222 offset:16384
	ds_read_b128 v[148:151], v222 offset:17408
	ds_read_b128 v[152:155], v222 offset:18432
	ds_read_b128 v[156:159], v222 offset:19456
	ds_read_b128 v[160:163], v222 offset:20480
	ds_read_b128 v[164:167], v222 offset:21504
	ds_read_b128 v[168:171], v222 offset:22528
	ds_read_b128 v[172:175], v222 offset:23552
	global_load_lds_dwordx4 v[216:217], off
	v_lshl_add_u64 v[226:227], s[64:65], 0, v[200:201]
	s_mov_b32 m0, s79
	s_nop 0
	global_load_lds_dwordx4 v[226:227], off
	s_barrier
	s_waitcnt lgkmcnt(0)
	s_setprio 1
	s_waitcnt lgkmcnt(0)
	s_cmp_eq_u32 s92, -2
	s_cbranch_scc1 .Lz6_2_first
	v_mfma_f32_16x16x32_bf16 v[60:63], v[64:67], v[144:147], v[60:63]
	v_mfma_f32_16x16x32_bf16 v[56:59], v[84:87], v[144:147], v[56:59]
	v_mfma_f32_16x16x32_bf16 v[44:47], v[64:67], v[152:155], v[44:47]
	v_mfma_f32_16x16x32_bf16 v[40:43], v[84:87], v[152:155], v[40:43]
	v_mfma_f32_16x16x32_bf16 v[28:31], v[64:67], v[160:163], v[28:31]
	v_mfma_f32_16x16x32_bf16 v[24:27], v[84:87], v[160:163], v[24:27]
	v_mfma_f32_16x16x32_bf16 v[12:15], v[64:67], v[168:171], v[12:15]
	v_mfma_f32_16x16x32_bf16 v[8:11], v[84:87], v[168:171], v[8:11]
	v_mfma_f32_16x16x32_bf16 v[60:63], v[68:71], v[148:151], v[60:63]
	v_mfma_f32_16x16x32_bf16 v[56:59], v[92:95], v[148:151], v[56:59]
	v_mfma_f32_16x16x32_bf16 v[44:47], v[68:71], v[156:159], v[44:47]
	v_mfma_f32_16x16x32_bf16 v[40:43], v[92:95], v[156:159], v[40:43]
	v_mfma_f32_16x16x32_bf16 v[28:31], v[68:71], v[164:167], v[28:31]
	v_mfma_f32_16x16x32_bf16 v[24:27], v[92:95], v[164:167], v[24:27]
	v_mfma_f32_16x16x32_bf16 v[12:15], v[68:71], v[172:175], v[12:15]
	v_mfma_f32_16x16x32_bf16 v[8:11], v[92:95], v[172:175], v[8:11]
.Lz6_2_join:
	s_setprio 0
	s_barrier
	s_add_u32 s94, s62, 0x10000
	s_addc_u32 s95, s63, 0
	s_add_i32 s28, s90, s67
	v_lshl_add_u64 v[64:65], s[94:95], 0, v[198:199]
	s_mov_b32 m0, s28
	s_nop 0
	global_load_lds_dwordx4 v[64:65], off
	v_lshl_add_u64 v[64:65], s[94:95], 0, v[202:203]
	s_add_i32 m0, s28, 0x2000
	s_nop 0
	global_load_lds_dwordx4 v[64:65], off
	s_waitcnt vmcnt(6)
	s_barrier
	s_setprio 1
	s_cmp_eq_u32 s92, -2
	s_cbranch_scc1 .Lz6_3_first
	v_mfma_f32_16x16x32_bf16 v[52:55], v[176:179], v[144:147], v[52:55]
	v_mfma_f32_16x16x32_bf16 v[48:51], v[184:187], v[144:147], v[48:51]
	v_mfma_f32_16x16x32_bf16 v[36:39], v[176:179], v[152:155], v[36:39]
	v_mfma_f32_16x16x32_bf16 v[32:35], v[184:187], v[152:155], v[32:35]
	v_mfma_f32_16x16x32_bf16 v[20:23], v[176:179], v[160:163], v[20:23]
	v_mfma_f32_16x16x32_bf16 v[16:19], v[184:187], v[160:163], v[16:19]
	v_mfma_f32_16x16x32_bf16 v[4:7], v[176:179], v[168:171], v[4:7]
	v_mfma_f32_16x16x32_bf16 v[0:3], v[184:187], v[168:171], v[0:3]
	v_mfma_f32_16x16x32_bf16 v[52:55], v[180:183], v[148:151], v[52:55]
	v_mfma_f32_16x16x32_bf16 v[48:51], v[188:191], v[148:151], v[48:51]
	v_mfma_f32_16x16x32_bf16 v[36:39], v[180:183], v[156:159], v[36:39]
	v_mfma_f32_16x16x32_bf16 v[32:35], v[188:191], v[156:159], v[32:35]
	v_mfma_f32_16x16x32_bf16 v[20:23], v[180:183], v[164:167], v[20:23]
	v_mfma_f32_16x16x32_bf16 v[16:19], v[188:191], v[164:167], v[16:19]
	v_mfma_f32_16x16x32_bf16 v[4:7], v[180:183], v[172:175], v[4:7]
	v_mfma_f32_16x16x32_bf16 v[0:3], v[188:191], v[172:175], v[0:3]
.Lz6_3_join:
	s_setprio 0
	s_add_i32 s28, 0, 0x18000
	v_add_u32_e32 v92, s28, v218
	s_barrier
	ds_read_b128 v[64:67], v92
	ds_read_b128 v[68:71], v92 offset:1024
	ds_read_b128 v[84:87], v92 offset:2048
	ds_read_b128 v[92:95], v92 offset:3072
	s_add_u32 s64, s64, 0x40000
	s_addc_u32 s65, s65, 0
	s_mov_b32 m0, s80
	v_lshl_add_u64 v[176:177], s[64:65], 0, v[196:197]
	ds_read_b128 v[144:147], v222 offset:32768
	ds_read_b128 v[148:151], v222 offset:33792
	ds_read_b128 v[152:155], v222 offset:34816
	ds_read_b128 v[156:159], v222 offset:35840
	ds_read_b128 v[160:163], v222 offset:36864
	ds_read_b128 v[164:167], v222 offset:37888
	ds_read_b128 v[168:171], v222 offset:38912
	ds_read_b128 v[172:175], v222 offset:39936
	global_load_lds_dwordx4 v[176:177], off
	v_lshl_add_u64 v[176:177], s[64:65], 0, v[200:201]
	s_mov_b32 m0, s81
	s_nop 0
	global_load_lds_dwordx4 v[176:177], off
	s_waitcnt lgkmcnt(8)
	s_barrier
	s_waitcnt lgkmcnt(0)
	s_setprio 1
	s_waitcnt lgkmcnt(0)
	v_mfma_f32_16x16x32_bf16 v[140:143], v[64:67], v[144:147], v[140:143]
	v_mfma_f32_16x16x32_bf16 v[136:139], v[84:87], v[144:147], v[136:139]
	v_mfma_f32_16x16x32_bf16 v[124:127], v[64:67], v[152:155], v[124:127]
	v_mfma_f32_16x16x32_bf16 v[120:123], v[84:87], v[152:155], v[120:123]
	v_mfma_f32_16x16x32_bf16 v[108:111], v[64:67], v[160:163], v[108:111]
	v_mfma_f32_16x16x32_bf16 v[104:107], v[84:87], v[160:163], v[104:107]
	v_mfma_f32_16x16x32_bf16 v[88:91], v[64:67], v[168:171], v[88:91]
	v_mfma_f32_16x16x32_bf16 v[80:83], v[84:87], v[168:171], v[80:83]
	v_mfma_f32_16x16x32_bf16 v[140:143], v[68:71], v[148:151], v[140:143]
	v_mfma_f32_16x16x32_bf16 v[136:139], v[92:95], v[148:151], v[136:139]
	v_mfma_f32_16x16x32_bf16 v[124:127], v[68:71], v[156:159], v[124:127]
	v_mfma_f32_16x16x32_bf16 v[120:123], v[92:95], v[156:159], v[120:123]
	v_mfma_f32_16x16x32_bf16 v[108:111], v[68:71], v[164:167], v[108:111]
	v_mfma_f32_16x16x32_bf16 v[104:107], v[92:95], v[164:167], v[104:107]
	v_mfma_f32_16x16x32_bf16 v[88:91], v[68:71], v[172:175], v[88:91]
	v_mfma_f32_16x16x32_bf16 v[80:83], v[92:95], v[172:175], v[80:83]
	s_setprio 0
	s_barrier
	s_add_i32 s29, 0, 0x1c000
	s_add_i32 s28, s28, s67
	v_add_u32_e32 v188, s29, v218
	v_lshl_add_u64 v[212:213], v[212:213], 0, s[52:53]
	s_mov_b32 m0, s28
	ds_read_b128 v[176:179], v188
	ds_read_b128 v[180:183], v188 offset:1024
	ds_read_b128 v[184:187], v188 offset:2048
	ds_read_b128 v[188:191], v188 offset:3072
	global_load_lds_dwordx4 v[212:213], off
	v_lshl_add_u64 v[212:213], v[214:215], 0, s[52:53]
	s_add_i32 m0, s28, 0x2000
	s_nop 0
	global_load_lds_dwordx4 v[212:213], off
	s_barrier
	s_waitcnt lgkmcnt(0)
	s_setprio 1
	s_waitcnt lgkmcnt(0)
	v_mfma_f32_16x16x32_bf16 v[132:135], v[176:179], v[144:147], v[132:135]
	v_mfma_f32_16x16x32_bf16 v[128:131], v[184:187], v[144:147], v[128:131]
	v_mfma_f32_16x16x32_bf16 v[116:119], v[176:179], v[152:155], v[116:119]
	v_mfma_f32_16x16x32_bf16 v[112:115], v[184:187], v[152:155], v[112:115]
	v_mfma_f32_16x16x32_bf16 v[100:103], v[176:179], v[160:163], v[100:103]
	v_mfma_f32_16x16x32_bf16 v[96:99], v[184:187], v[160:163], v[96:99]
	v_mfma_f32_16x16x32_bf16 v[76:79], v[176:179], v[168:171], v[76:79]
	v_mfma_f32_16x16x32_bf16 v[72:75], v[184:187], v[168:171], v[72:75]
	v_mfma_f32_16x16x32_bf16 v[132:135], v[180:183], v[148:151], v[132:135]
	v_mfma_f32_16x16x32_bf16 v[128:131], v[188:191], v[148:151], v[128:131]
	v_mfma_f32_16x16x32_bf16 v[116:119], v[180:183], v[156:159], v[116:119]
	v_mfma_f32_16x16x32_bf16 v[112:115], v[188:191], v[156:159], v[112:115]
	v_mfma_f32_16x16x32_bf16 v[100:103], v[180:183], v[164:167], v[100:103]
	v_mfma_f32_16x16x32_bf16 v[96:99], v[188:191], v[164:167], v[96:99]
	v_mfma_f32_16x16x32_bf16 v[76:79], v[180:183], v[172:175], v[76:79]
	v_mfma_f32_16x16x32_bf16 v[72:75], v[188:191], v[172:175], v[72:75]
	s_setprio 0
	s_mov_b32 m0, s85
	v_lshl_add_u64 v[212:213], v[216:217], 0, s[52:53]
	s_barrier
	ds_read_b128 v[144:147], v222 offset:49152
	ds_read_b128 v[148:151], v222 offset:50176
	ds_read_b128 v[152:155], v222 offset:51200
	ds_read_b128 v[156:159], v222 offset:52224
	ds_read_b128 v[160:163], v222 offset:53248
	ds_read_b128 v[164:167], v222 offset:54272
	ds_read_b128 v[168:171], v222 offset:55296
	ds_read_b128 v[172:175], v222 offset:56320
	global_load_lds_dwordx4 v[212:213], off
	v_lshl_add_u64 v[212:213], v[226:227], 0, s[52:53]
	s_mov_b32 m0, s87
	s_nop 0
	global_load_lds_dwordx4 v[212:213], off
	s_barrier
	s_waitcnt lgkmcnt(0)
	s_setprio 1
	s_waitcnt lgkmcnt(0)
	v_mfma_f32_16x16x32_bf16 v[60:63], v[64:67], v[144:147], v[60:63]
	v_mfma_f32_16x16x32_bf16 v[56:59], v[84:87], v[144:147], v[56:59]
	v_mfma_f32_16x16x32_bf16 v[44:47], v[64:67], v[152:155], v[44:47]
	v_mfma_f32_16x16x32_bf16 v[40:43], v[84:87], v[152:155], v[40:43]
	v_mfma_f32_16x16x32_bf16 v[28:31], v[64:67], v[160:163], v[28:31]
	v_mfma_f32_16x16x32_bf16 v[24:27], v[84:87], v[160:163], v[24:27]
	v_mfma_f32_16x16x32_bf16 v[12:15], v[64:67], v[168:171], v[12:15]
	v_mfma_f32_16x16x32_bf16 v[8:11], v[84:87], v[168:171], v[8:11]
	v_mfma_f32_16x16x32_bf16 v[60:63], v[68:71], v[148:151], v[60:63]
	v_mfma_f32_16x16x32_bf16 v[56:59], v[92:95], v[148:151], v[56:59]
	v_mfma_f32_16x16x32_bf16 v[44:47], v[68:71], v[156:159], v[44:47]
	v_mfma_f32_16x16x32_bf16 v[40:43], v[92:95], v[156:159], v[40:43]
	v_mfma_f32_16x16x32_bf16 v[28:31], v[68:71], v[164:167], v[28:31]
	v_mfma_f32_16x16x32_bf16 v[24:27], v[92:95], v[164:167], v[24:27]
	v_mfma_f32_16x16x32_bf16 v[12:15], v[68:71], v[172:175], v[12:15]
	v_mfma_f32_16x16x32_bf16 v[8:11], v[92:95], v[172:175], v[8:11]
	s_setprio 0
	s_barrier
	s_add_u32 s62, s62, 0x10080
	s_addc_u32 s63, s63, 0
	s_add_i32 s28, s29, s67
	v_lshl_add_u64 v[64:65], s[62:63], 0, v[198:199]
	s_mov_b32 m0, s28
	s_nop 0
	global_load_lds_dwordx4 v[64:65], off
	v_lshl_add_u64 v[64:65], s[62:63], 0, v[202:203]
	s_add_i32 m0, s28, 0x2000
	s_nop 0
	global_load_lds_dwordx4 v[64:65], off
	s_waitcnt vmcnt(6)
	s_barrier
	s_setprio 1
	v_mfma_f32_16x16x32_bf16 v[52:55], v[176:179], v[144:147], v[52:55]
	v_mfma_f32_16x16x32_bf16 v[48:51], v[184:187], v[144:147], v[48:51]
	v_mfma_f32_16x16x32_bf16 v[36:39], v[176:179], v[152:155], v[36:39]
	v_mfma_f32_16x16x32_bf16 v[32:35], v[184:187], v[152:155], v[32:35]
	v_mfma_f32_16x16x32_bf16 v[20:23], v[176:179], v[160:163], v[20:23]
	v_mfma_f32_16x16x32_bf16 v[16:19], v[184:187], v[160:163], v[16:19]
	v_mfma_f32_16x16x32_bf16 v[4:7], v[176:179], v[168:171], v[4:7]
	v_mfma_f32_16x16x32_bf16 v[0:3], v[184:187], v[168:171], v[0:3]
	v_mfma_f32_16x16x32_bf16 v[52:55], v[180:183], v[148:151], v[52:55]
	v_mfma_f32_16x16x32_bf16 v[48:51], v[188:191], v[148:151], v[48:51]
	v_mfma_f32_16x16x32_bf16 v[36:39], v[180:183], v[156:159], v[36:39]
	v_mfma_f32_16x16x32_bf16 v[32:35], v[188:191], v[156:159], v[32:35]
	v_mfma_f32_16x16x32_bf16 v[20:23], v[180:183], v[164:167], v[20:23]
	v_mfma_f32_16x16x32_bf16 v[16:19], v[188:191], v[164:167], v[16:19]
	v_mfma_f32_16x16x32_bf16 v[4:7], v[180:183], v[172:175], v[4:7]
	v_mfma_f32_16x16x32_bf16 v[0:3], v[188:191], v[172:175], v[0:3]
	s_setprio 0
	s_add_i32 s92, s92, 2
	s_add_u32 s10, s10, 0x100
	s_addc_u32 s11, s11, 0
	s_add_u32 s55, s55, 0x100
	s_addc_u32 s57, s57, 0
	s_cmp_gt_u32 s92, 13
	s_barrier
	s_cbranch_scc0 .LBB0_740
	s_branch .Lz6_skip
.Lz6_0_first:
	v_mfma_f32_16x16x32_bf16 v[140:143], v[64:67], v[144:147], 0
	v_mfma_f32_16x16x32_bf16 v[136:139], v[84:87], v[144:147], 0
	v_mfma_f32_16x16x32_bf16 v[124:127], v[64:67], v[152:155], 0
	v_mfma_f32_16x16x32_bf16 v[120:123], v[84:87], v[152:155], 0
	v_mfma_f32_16x16x32_bf16 v[108:111], v[64:67], v[160:163], 0
	v_mfma_f32_16x16x32_bf16 v[104:107], v[84:87], v[160:163], 0
	v_mfma_f32_16x16x32_bf16 v[88:91], v[64:67], v[168:171], 0
	v_mfma_f32_16x16x32_bf16 v[80:83], v[84:87], v[168:171], 0
	v_mfma_f32_16x16x32_bf16 v[140:143], v[68:71], v[148:151], v[140:143]
	v_mfma_f32_16x16x32_bf16 v[136:139], v[92:95], v[148:151], v[136:139]
	v_mfma_f32_16x16x32_bf16 v[124:127], v[68:71], v[156:159], v[124:127]
	v_mfma_f32_16x16x32_bf16 v[120:123], v[92:95], v[156:159], v[120:123]
	v_mfma_f32_16x16x32_bf16 v[108:111], v[68:71], v[164:167], v[108:111]
	v_mfma_f32_16x16x32_bf16 v[104:107], v[92:95], v[164:167], v[104:107]
	v_mfma_f32_16x16x32_bf16 v[88:91], v[68:71], v[172:175], v[88:91]
	v_mfma_f32_16x16x32_bf16 v[80:83], v[92:95], v[172:175], v[80:83]
	s_branch .Lz6_0_join
.Lz6_1_first:
	v_mfma_f32_16x16x32_bf16 v[132:135], v[176:179], v[144:147], 0
	v_mfma_f32_16x16x32_bf16 v[128:131], v[184:187], v[144:147], 0
	v_mfma_f32_16x16x32_bf16 v[116:119], v[176:179], v[152:155], 0
	v_mfma_f32_16x16x32_bf16 v[112:115], v[184:187], v[152:155], 0
	v_mfma_f32_16x16x32_bf16 v[100:103], v[176:179], v[160:163], 0
	v_mfma_f32_16x16x32_bf16 v[96:99], v[184:187], v[160:163], 0
	v_mfma_f32_16x16x32_bf16 v[76:79], v[176:179], v[168:171], 0
	v_mfma_f32_16x16x32_bf16 v[72:75], v[184:187], v[168:171], 0
	v_mfma_f32_16x16x32_bf16 v[132:135], v[180:183], v[148:151], v[132:135]
	v_mfma_f32_16x16x32_bf16 v[128:131], v[188:191], v[148:151], v[128:131]
	v_mfma_f32_16x16x32_bf16 v[116:119], v[180:183], v[156:159], v[116:119]
	v_mfma_f32_16x16x32_bf16 v[112:115], v[188:191], v[156:159], v[112:115]
	v_mfma_f32_16x16x32_bf16 v[100:103], v[180:183], v[164:167], v[100:103]
	v_mfma_f32_16x16x32_bf16 v[96:99], v[188:191], v[164:167], v[96:99]
	v_mfma_f32_16x16x32_bf16 v[76:79], v[180:183], v[172:175], v[76:79]
	v_mfma_f32_16x16x32_bf16 v[72:75], v[188:191], v[172:175], v[72:75]
	s_branch .Lz6_1_join
.Lz6_2_first:
	v_mfma_f32_16x16x32_bf16 v[60:63], v[64:67], v[144:147], 0
	v_mfma_f32_16x16x32_bf16 v[56:59], v[84:87], v[144:147], 0
	v_mfma_f32_16x16x32_bf16 v[44:47], v[64:67], v[152:155], 0
	v_mfma_f32_16x16x32_bf16 v[40:43], v[84:87], v[152:155], 0
	v_mfma_f32_16x16x32_bf16 v[28:31], v[64:67], v[160:163], 0
	v_mfma_f32_16x16x32_bf16 v[24:27], v[84:87], v[160:163], 0
	v_mfma_f32_16x16x32_bf16 v[12:15], v[64:67], v[168:171], 0
	v_mfma_f32_16x16x32_bf16 v[8:11], v[84:87], v[168:171], 0
	v_mfma_f32_16x16x32_bf16 v[60:63], v[68:71], v[148:151], v[60:63]
	v_mfma_f32_16x16x32_bf16 v[56:59], v[92:95], v[148:151], v[56:59]
	v_mfma_f32_16x16x32_bf16 v[44:47], v[68:71], v[156:159], v[44:47]
	v_mfma_f32_16x16x32_bf16 v[40:43], v[92:95], v[156:159], v[40:43]
	v_mfma_f32_16x16x32_bf16 v[28:31], v[68:71], v[164:167], v[28:31]
	v_mfma_f32_16x16x32_bf16 v[24:27], v[92:95], v[164:167], v[24:27]
	v_mfma_f32_16x16x32_bf16 v[12:15], v[68:71], v[172:175], v[12:15]
	v_mfma_f32_16x16x32_bf16 v[8:11], v[92:95], v[172:175], v[8:11]
	s_branch .Lz6_2_join
.Lz6_3_first:
	v_mfma_f32_16x16x32_bf16 v[52:55], v[176:179], v[144:147], 0
	v_mfma_f32_16x16x32_bf16 v[48:51], v[184:187], v[144:147], 0
	v_mfma_f32_16x16x32_bf16 v[36:39], v[176:179], v[152:155], 0
	v_mfma_f32_16x16x32_bf16 v[32:35], v[184:187], v[152:155], 0
	v_mfma_f32_16x16x32_bf16 v[20:23], v[176:179], v[160:163], 0
	v_mfma_f32_16x16x32_bf16 v[16:19], v[184:187], v[160:163], 0
	v_mfma_f32_16x16x32_bf16 v[4:7], v[176:179], v[168:171], 0
	v_mfma_f32_16x16x32_bf16 v[0:3], v[184:187], v[168:171], 0
	v_mfma_f32_16x16x32_bf16 v[52:55], v[180:183], v[148:151], v[52:55]
	v_mfma_f32_16x16x32_bf16 v[48:51], v[188:191], v[148:151], v[48:51]
	v_mfma_f32_16x16x32_bf16 v[36:39], v[180:183], v[156:159], v[36:39]
	v_mfma_f32_16x16x32_bf16 v[32:35], v[188:191], v[156:159], v[32:35]
	v_mfma_f32_16x16x32_bf16 v[20:23], v[180:183], v[164:167], v[20:23]
	v_mfma_f32_16x16x32_bf16 v[16:19], v[188:191], v[164:167], v[16:19]
	v_mfma_f32_16x16x32_bf16 v[4:7], v[180:183], v[172:175], v[4:7]
	v_mfma_f32_16x16x32_bf16 v[0:3], v[188:191], v[172:175], v[0:3]
	s_branch .Lz6_3_join
.Lz6_skip:
	v_lshl_add_u32 v212, s8, 8, v195
	v_lshl_or_b32 v214, s12, 8, v219
	v_ashrrev_i32_e32 v213, 31, v212
	v_ashrrev_i32_e32 v215, 31, v214
	s_mov_b64 s[8:9], -1
	s_and_b64 vcc, exec, s[48:49]
	s_cbranch_vccz .LBB0_743
	v_lshlrev_b64 v[64:65], 12, v[212:213]
	v_lshl_add_u64 v[64:65], s[36:37], 0, v[64:65]
	v_lshl_add_u64 v[64:65], v[214:215], 2, v[64:65]
	global_load_dwordx4 v[160:163], v[64:65], off offset:16
	global_load_dwordx4 v[164:167], v[64:65], off
	global_load_dwordx4 v[168:171], v[64:65], off offset:144
	global_load_dwordx4 v[172:175], v[64:65], off offset:128
	s_mov_b64 s[8:9], 0

.LBB0_903:
	s_ashr_i32 s45, s44, 31
	v_cmp_lt_i64_e32 vcc, s[0:1], v[142:143]
	s_lshl_b64 s[0:1], s[44:45], 19
	s_add_u32 s46, s42, s0
	s_addc_u32 s47, s43, s1
	s_and_b64 s[0:1], vcc, exec
	s_cselect_b32 s7, s47, s53
	s_cselect_b32 s45, s46, s52
	s_ashr_i32 s37, s36, 31
	s_lshl_b64 s[0:1], s[36:37], 19
	s_add_u32 s48, s74, s0
	s_addc_u32 s49, s75, s1
	s_and_b64 s[0:1], vcc, exec
	s_cselect_b32 s37, s49, s51
	s_cselect_b32 s67, s48, s50
	s_add_u32 s0, s52, 0x40080
	s_addc_u32 s1, s53, 0
	s_add_u32 s76, s50, 0x100
	s_addc_u32 s77, s51, 0
	s_mov_b32 s78, -2
.LBB0_904:
	ds_read_b128 v[146:149], v169
	ds_read_b128 v[150:153], v169 offset:1024
	ds_read_b128 v[154:157], v169 offset:2048
	ds_read_b128 v[174:177], v169 offset:3072
	s_add_u32 s28, s0, 0xfffc0080
	s_addc_u32 s29, s1, -1
	s_cmp_eq_u32 s78, 12
	s_cselect_b32 s53, s7, s29
	s_cselect_b32 s52, s45, s28
	s_cselect_b32 s51, s37, s77
	s_cselect_b32 s50, s67, s76
	v_lshl_add_u64 v[158:159], s[0:1], 0, v[138:139]
	s_add_i32 m0, s54, 0xc000
	ds_read_b128 v[178:181], v171
	ds_read_b128 v[182:185], v171 offset:1024
	ds_read_b128 v[186:189], v171 offset:2048
	ds_read_b128 v[196:199], v171 offset:3072
	ds_read_b128 v[200:203], v171 offset:4096
	ds_read_b128 v[204:207], v171 offset:5120
	ds_read_b128 v[208:211], v171 offset:6144
	ds_read_b128 v[212:215], v171 offset:7168
	global_load_lds_dwordx4 v[158:159], off
	v_lshl_add_u64 v[158:159], s[0:1], 0, v[140:141]
	s_add_i32 m0, s54, 0xe000
	s_nop 0
	global_load_lds_dwordx4 v[158:159], off
	s_waitcnt lgkmcnt(8)
	s_barrier
	s_waitcnt lgkmcnt(0)
	s_setprio 1
	s_waitcnt lgkmcnt(0)
	s_cmp_eq_u32 s78, -2
	s_cbranch_scc1 .Lz7_0_first
	v_mfma_f32_16x16x32_bf16 v[124:127], v[146:149], v[178:181], v[124:127]
	v_mfma_f32_16x16x32_bf16 v[120:123], v[154:157], v[178:181], v[120:123]
	v_mfma_f32_16x16x32_bf16 v[108:111], v[146:149], v[186:189], v[108:111]
	v_mfma_f32_16x16x32_bf16 v[104:107], v[154:157], v[186:189], v[104:107]
	v_mfma_f32_16x16x32_bf16 v[92:95], v[146:149], v[200:203], v[92:95]
	v_mfma_f32_16x16x32_bf16 v[88:91], v[154:157], v[200:203], v[88:91]
	v_mfma_f32_16x16x32_bf16 v[76:79], v[146:149], v[208:211], v[76:79]
	v_mfma_f32_16x16x32_bf16 v[72:75], v[154:157], v[208:211], v[72:75]
	v_mfma_f32_16x16x32_bf16 v[124:127], v[150:153], v[182:185], v[124:127]
	v_mfma_f32_16x16x32_bf16 v[120:123], v[174:177], v[182:185], v[120:123]
	v_mfma_f32_16x16x32_bf16 v[108:111], v[150:153], v[196:199], v[108:111]
	v_mfma_f32_16x16x32_bf16 v[104:107], v[174:177], v[196:199], v[104:107]
	v_mfma_f32_16x16x32_bf16 v[92:95], v[150:153], v[204:207], v[92:95]
	v_mfma_f32_16x16x32_bf16 v[88:91], v[174:177], v[204:207], v[88:91]
	v_mfma_f32_16x16x32_bf16 v[76:79], v[150:153], v[212:215], v[76:79]
	v_mfma_f32_16x16x32_bf16 v[72:75], v[174:177], v[212:215], v[72:75]
.Lz7_0_join:
	s_setprio 0
	s_barrier
	s_add_i32 s28, s63, s13
	v_lshl_add_u64 v[158:159], s[50:51], 0, v[132:133]
	s_mov_b32 m0, s28
	ds_read_b128 v[216:219], v172
	ds_read_b128 v[220:223], v172 offset:1024
	ds_read_b128 v[224:227], v172 offset:2048
	ds_read_b128 v[228:231], v172 offset:3072
	global_load_lds_dwordx4 v[158:159], off
	v_lshl_add_u64 v[164:165], s[50:51], 0, v[128:129]
	s_add_i32 m0, s28, 0x2000
	s_nop 0
	global_load_lds_dwordx4 v[164:165], off
	s_barrier
	s_waitcnt lgkmcnt(0)
	s_setprio 1
	s_waitcnt lgkmcnt(0)
	s_cmp_eq_u32 s78, -2
	s_cbranch_scc1 .Lz7_1_first
	v_mfma_f32_16x16x32_bf16 v[116:119], v[216:219], v[178:181], v[116:119]
	v_mfma_f32_16x16x32_bf16 v[112:115], v[224:227], v[178:181], v[112:115]
	v_mfma_f32_16x16x32_bf16 v[100:103], v[216:219], v[186:189], v[100:103]
	v_mfma_f32_16x16x32_bf16 v[96:99], v[224:227], v[186:189], v[96:99]
	v_mfma_f32_16x16x32_bf16 v[84:87], v[216:219], v[200:203], v[84:87]
	v_mfma_f32_16x16x32_bf16 v[80:83], v[224:227], v[200:203], v[80:83]
	v_mfma_f32_16x16x32_bf16 v[68:71], v[216:219], v[208:211], v[68:71]
	v_mfma_f32_16x16x32_bf16 v[64:67], v[224:227], v[208:211], v[64:67]
	v_mfma_f32_16x16x32_bf16 v[116:119], v[220:223], v[182:185], v[116:119]
	v_mfma_f32_16x16x32_bf16 v[112:115], v[228:231], v[182:185], v[112:115]
	v_mfma_f32_16x16x32_bf16 v[100:103], v[220:223], v[196:199], v[100:103]
	v_mfma_f32_16x16x32_bf16 v[96:99], v[228:231], v[196:199], v[96:99]
	v_mfma_f32_16x16x32_bf16 v[84:87], v[220:223], v[204:207], v[84:87]
	v_mfma_f32_16x16x32_bf16 v[80:83], v[228:231], v[204:207], v[80:83]
	v_mfma_f32_16x16x32_bf16 v[68:71], v[220:223], v[212:215], v[68:71]
	v_mfma_f32_16x16x32_bf16 v[64:67], v[228:231], v[212:215], v[64:67]
.Lz7_1_join:
	s_setprio 0
	s_mov_b32 m0, s54
	v_lshl_add_u64 v[190:191], s[52:53], 0, v[134:135]
	s_barrier
	ds_read_b128 v[178:181], v171 offset:16384
	ds_read_b128 v[182:185], v171 offset:17408
	ds_read_b128 v[186:189], v171 offset:18432
	ds_read_b128 v[196:199], v171 offset:19456
	ds_read_b128 v[200:203], v171 offset:20480
	ds_read_b128 v[204:207], v171 offset:21504
	ds_read_b128 v[208:211], v171 offset:22528
	ds_read_b128 v[212:215], v171 offset:23552
	global_load_lds_dwordx4 v[190:191], off
	v_lshl_add_u64 v[232:233], s[52:53], 0, v[130:131]
	s_mov_b32 m0, s55
	s_nop 0
	global_load_lds_dwordx4 v[232:233], off
	s_barrier
	s_waitcnt lgkmcnt(0)
	s_setprio 1
	s_waitcnt lgkmcnt(0)
	s_cmp_eq_u32 s78, -2
	s_cbranch_scc1 .Lz7_2_first
	v_mfma_f32_16x16x32_bf16 v[60:63], v[146:149], v[178:181], v[60:63]
	v_mfma_f32_16x16x32_bf16 v[56:59], v[154:157], v[178:181], v[56:59]
	v_mfma_f32_16x16x32_bf16 v[44:47], v[146:149], v[186:189], v[44:47]
	v_mfma_f32_16x16x32_bf16 v[40:43], v[154:157], v[186:189], v[40:43]
	v_mfma_f32_16x16x32_bf16 v[28:31], v[146:149], v[200:203], v[28:31]
	v_mfma_f32_16x16x32_bf16 v[24:27], v[154:157], v[200:203], v[24:27]
	v_mfma_f32_16x16x32_bf16 v[12:15], v[146:149], v[208:211], v[12:15]
	v_mfma_f32_16x16x32_bf16 v[8:11], v[154:157], v[208:211], v[8:11]
	v_mfma_f32_16x16x32_bf16 v[60:63], v[150:153], v[182:185], v[60:63]
	v_mfma_f32_16x16x32_bf16 v[56:59], v[174:177], v[182:185], v[56:59]
	v_mfma_f32_16x16x32_bf16 v[44:47], v[150:153], v[196:199], v[44:47]
	v_mfma_f32_16x16x32_bf16 v[40:43], v[174:177], v[196:199], v[40:43]
	v_mfma_f32_16x16x32_bf16 v[28:31], v[150:153], v[204:207], v[28:31]
	v_mfma_f32_16x16x32_bf16 v[24:27], v[174:177], v[204:207], v[24:27]
	v_mfma_f32_16x16x32_bf16 v[12:15], v[150:153], v[212:215], v[12:15]
	v_mfma_f32_16x16x32_bf16 v[8:11], v[174:177], v[212:215], v[8:11]
.Lz7_2_join:
	s_setprio 0
	s_barrier
	s_add_u32 s80, s50, 0x10000
	s_addc_u32 s81, s51, 0
	s_add_i32 s28, s64, s13
	v_lshl_add_u64 v[146:147], s[80:81], 0, v[132:133]
	s_mov_b32 m0, s28
	s_nop 0
	global_load_lds_dwordx4 v[146:147], off
	v_lshl_add_u64 v[146:147], s[80:81], 0, v[128:129]
	s_add_i32 m0, s28, 0x2000
	s_nop 0
	global_load_lds_dwordx4 v[146:147], off
	s_waitcnt vmcnt(6)
	s_barrier
	s_setprio 1
	s_cmp_eq_u32 s78, -2
	s_cbranch_scc1 .Lz7_3_first
	v_mfma_f32_16x16x32_bf16 v[52:55], v[216:219], v[178:181], v[52:55]
	v_mfma_f32_16x16x32_bf16 v[48:51], v[224:227], v[178:181], v[48:51]
	v_mfma_f32_16x16x32_bf16 v[36:39], v[216:219], v[186:189], v[36:39]
	v_mfma_f32_16x16x32_bf16 v[32:35], v[224:227], v[186:189], v[32:35]
	v_mfma_f32_16x16x32_bf16 v[20:23], v[216:219], v[200:203], v[20:23]
	v_mfma_f32_16x16x32_bf16 v[16:19], v[224:227], v[200:203], v[16:19]
	v_mfma_f32_16x16x32_bf16 v[4:7], v[216:219], v[208:211], v[4:7]
	v_mfma_f32_16x16x32_bf16 v[0:3], v[224:227], v[208:211], v[0:3]
	v_mfma_f32_16x16x32_bf16 v[52:55], v[220:223], v[182:185], v[52:55]
	v_mfma_f32_16x16x32_bf16 v[48:51], v[228:231], v[182:185], v[48:51]
	v_mfma_f32_16x16x32_bf16 v[36:39], v[220:223], v[196:199], v[36:39]
	v_mfma_f32_16x16x32_bf16 v[32:35], v[228:231], v[196:199], v[32:35]
	v_mfma_f32_16x16x32_bf16 v[20:23], v[220:223], v[204:207], v[20:23]
	v_mfma_f32_16x16x32_bf16 v[16:19], v[228:231], v[204:207], v[16:19]
	v_mfma_f32_16x16x32_bf16 v[4:7], v[220:223], v[212:215], v[4:7]
	v_mfma_f32_16x16x32_bf16 v[0:3], v[228:231], v[212:215], v[0:3]
.Lz7_3_join:
	s_setprio 0
	s_add_i32 s28, 0, 0x18000
	v_add_u32_e32 v160, s28, v163
	s_barrier
	ds_read_b128 v[146:149], v160
	ds_read_b128 v[150:153], v160 offset:1024
	ds_read_b128 v[154:157], v160 offset:2048
	ds_read_b128 v[174:177], v160 offset:3072
	s_add_u32 s52, s52, 0x40000
	s_addc_u32 s53, s53, 0
	s_mov_b32 m0, s56
	v_lshl_add_u64 v[216:217], s[52:53], 0, v[134:135]
	ds_read_b128 v[178:181], v171 offset:32768
	ds_read_b128 v[182:185], v171 offset:33792
	ds_read_b128 v[186:189], v171 offset:34816
	ds_read_b128 v[196:199], v171 offset:35840
	ds_read_b128 v[200:203], v171 offset:36864
	ds_read_b128 v[204:207], v171 offset:37888
	ds_read_b128 v[208:211], v171 offset:38912
	ds_read_b128 v[212:215], v171 offset:39936
	global_load_lds_dwordx4 v[216:217], off
	v_lshl_add_u64 v[216:217], s[52:53], 0, v[130:131]
	s_mov_b32 m0, s57
	s_nop 0
	global_load_lds_dwordx4 v[216:217], off
	s_waitcnt lgkmcnt(8)
	s_barrier
	s_waitcnt lgkmcnt(0)
	s_setprio 1
	s_waitcnt lgkmcnt(0)
	v_mfma_f32_16x16x32_bf16 v[124:127], v[146:149], v[178:181], v[124:127]
	v_mfma_f32_16x16x32_bf16 v[120:123], v[154:157], v[178:181], v[120:123]
	v_mfma_f32_16x16x32_bf16 v[108:111], v[146:149], v[186:189], v[108:111]
	v_mfma_f32_16x16x32_bf16 v[104:107], v[154:157], v[186:189], v[104:107]
	v_mfma_f32_16x16x32_bf16 v[92:95], v[146:149], v[200:203], v[92:95]
	v_mfma_f32_16x16x32_bf16 v[88:91], v[154:157], v[200:203], v[88:91]
	v_mfma_f32_16x16x32_bf16 v[76:79], v[146:149], v[208:211], v[76:79]
	v_mfma_f32_16x16x32_bf16 v[72:75], v[154:157], v[208:211], v[72:75]
	v_mfma_f32_16x16x32_bf16 v[124:127], v[150:153], v[182:185], v[124:127]
	v_mfma_f32_16x16x32_bf16 v[120:123], v[174:177], v[182:185], v[120:123]
	v_mfma_f32_16x16x32_bf16 v[108:111], v[150:153], v[196:199], v[108:111]
	v_mfma_f32_16x16x32_bf16 v[104:107], v[174:177], v[196:199], v[104:107]
	v_mfma_f32_16x16x32_bf16 v[92:95], v[150:153], v[204:207], v[92:95]
	v_mfma_f32_16x16x32_bf16 v[88:91], v[174:177], v[204:207], v[88:91]
	v_mfma_f32_16x16x32_bf16 v[76:79], v[150:153], v[212:215], v[76:79]
	v_mfma_f32_16x16x32_bf16 v[72:75], v[174:177], v[212:215], v[72:75]
	s_setprio 0
	s_barrier
	s_add_i32 s29, 0, 0x1c000
	s_add_i32 s28, s28, s13
	v_add_u32_e32 v160, s29, v163
	v_lshl_add_u64 v[158:159], v[158:159], 0, s[8:9]
	s_mov_b32 m0, s28
	ds_read_b128 v[216:219], v160
	ds_read_b128 v[220:223], v160 offset:1024
	ds_read_b128 v[224:227], v160 offset:2048
	ds_read_b128 v[228:231], v160 offset:3072
	global_load_lds_dwordx4 v[158:159], off
	v_lshl_add_u64 v[158:159], v[164:165], 0, s[8:9]
	s_add_i32 m0, s28, 0x2000
	s_nop 0
	global_load_lds_dwordx4 v[158:159], off
	s_barrier
	s_waitcnt lgkmcnt(0)
	s_setprio 1
	s_waitcnt lgkmcnt(0)
	v_mfma_f32_16x16x32_bf16 v[116:119], v[216:219], v[178:181], v[116:119]
	v_mfma_f32_16x16x32_bf16 v[112:115], v[224:227], v[178:181], v[112:115]
	v_mfma_f32_16x16x32_bf16 v[100:103], v[216:219], v[186:189], v[100:103]
	v_mfma_f32_16x16x32_bf16 v[96:99], v[224:227], v[186:189], v[96:99]
	v_mfma_f32_16x16x32_bf16 v[84:87], v[216:219], v[200:203], v[84:87]
	v_mfma_f32_16x16x32_bf16 v[80:83], v[224:227], v[200:203], v[80:83]
	v_mfma_f32_16x16x32_bf16 v[68:71], v[216:219], v[208:211], v[68:71]
	v_mfma_f32_16x16x32_bf16 v[64:67], v[224:227], v[208:211], v[64:67]
	v_mfma_f32_16x16x32_bf16 v[116:119], v[220:223], v[182:185], v[116:119]
	v_mfma_f32_16x16x32_bf16 v[112:115], v[228:231], v[182:185], v[112:115]
	v_mfma_f32_16x16x32_bf16 v[100:103], v[220:223], v[196:199], v[100:103]
	v_mfma_f32_16x16x32_bf16 v[96:99], v[228:231], v[196:199], v[96:99]
	v_mfma_f32_16x16x32_bf16 v[84:87], v[220:223], v[204:207], v[84:87]
	v_mfma_f32_16x16x32_bf16 v[80:83], v[228:231], v[204:207], v[80:83]
	v_mfma_f32_16x16x32_bf16 v[68:71], v[220:223], v[212:215], v[68:71]
	v_mfma_f32_16x16x32_bf16 v[64:67], v[228:231], v[212:215], v[64:67]
	s_setprio 0
	s_mov_b32 m0, s60
	v_lshl_add_u64 v[158:159], v[190:191], 0, s[8:9]
	s_barrier
	ds_read_b128 v[178:181], v171 offset:49152
	ds_read_b128 v[182:185], v171 offset:50176
	ds_read_b128 v[186:189], v171 offset:51200
	ds_read_b128 v[196:199], v171 offset:52224
	ds_read_b128 v[200:203], v171 offset:53248
	ds_read_b128 v[204:207], v171 offset:54272
	ds_read_b128 v[208:211], v171 offset:55296
	ds_read_b128 v[212:215], v171 offset:56320
	global_load_lds_dwordx4 v[158:159], off
	v_lshl_add_u64 v[158:159], v[232:233], 0, s[8:9]
	s_mov_b32 m0, s61
	s_nop 0
	global_load_lds_dwordx4 v[158:159], off
	s_barrier
	s_waitcnt lgkmcnt(0)
	s_setprio 1
	s_waitcnt lgkmcnt(0)
	v_mfma_f32_16x16x32_bf16 v[60:63], v[146:149], v[178:181], v[60:63]
	v_mfma_f32_16x16x32_bf16 v[56:59], v[154:157], v[178:181], v[56:59]
	v_mfma_f32_16x16x32_bf16 v[44:47], v[146:149], v[186:189], v[44:47]
	v_mfma_f32_16x16x32_bf16 v[40:43], v[154:157], v[186:189], v[40:43]
	v_mfma_f32_16x16x32_bf16 v[28:31], v[146:149], v[200:203], v[28:31]
	v_mfma_f32_16x16x32_bf16 v[24:27], v[154:157], v[200:203], v[24:27]
	v_mfma_f32_16x16x32_bf16 v[12:15], v[146:149], v[208:211], v[12:15]
	v_mfma_f32_16x16x32_bf16 v[8:11], v[154:157], v[208:211], v[8:11]
	v_mfma_f32_16x16x32_bf16 v[60:63], v[150:153], v[182:185], v[60:63]
	v_mfma_f32_16x16x32_bf16 v[56:59], v[174:177], v[182:185], v[56:59]
	v_mfma_f32_16x16x32_bf16 v[44:47], v[150:153], v[196:199], v[44:47]
	v_mfma_f32_16x16x32_bf16 v[40:43], v[174:177], v[196:199], v[40:43]
	v_mfma_f32_16x16x32_bf16 v[28:31], v[150:153], v[204:207], v[28:31]
	v_mfma_f32_16x16x32_bf16 v[24:27], v[174:177], v[204:207], v[24:27]
	v_mfma_f32_16x16x32_bf16 v[12:15], v[150:153], v[212:215], v[12:15]
	v_mfma_f32_16x16x32_bf16 v[8:11], v[174:177], v[212:215], v[8:11]
	s_setprio 0
	s_barrier
	s_add_u32 s50, s50, 0x10080
	s_addc_u32 s51, s51, 0
	s_add_i32 s28, s29, s13
	v_lshl_add_u64 v[146:147], s[50:51], 0, v[132:133]
	s_mov_b32 m0, s28
	s_nop 0
	global_load_lds_dwordx4 v[146:147], off
	v_lshl_add_u64 v[146:147], s[50:51], 0, v[128:129]
	s_add_i32 m0, s28, 0x2000
	s_nop 0
	global_load_lds_dwordx4 v[146:147], off
	s_waitcnt vmcnt(6)
	s_barrier
	s_setprio 1
	v_mfma_f32_16x16x32_bf16 v[52:55], v[216:219], v[178:181], v[52:55]
	v_mfma_f32_16x16x32_bf16 v[48:51], v[224:227], v[178:181], v[48:51]
	v_mfma_f32_16x16x32_bf16 v[36:39], v[216:219], v[186:189], v[36:39]
	v_mfma_f32_16x16x32_bf16 v[32:35], v[224:227], v[186:189], v[32:35]
	v_mfma_f32_16x16x32_bf16 v[20:23], v[216:219], v[200:203], v[20:23]
	v_mfma_f32_16x16x32_bf16 v[16:19], v[224:227], v[200:203], v[16:19]
	v_mfma_f32_16x16x32_bf16 v[4:7], v[216:219], v[208:211], v[4:7]
	v_mfma_f32_16x16x32_bf16 v[0:3], v[224:227], v[208:211], v[0:3]
	v_mfma_f32_16x16x32_bf16 v[52:55], v[220:223], v[182:185], v[52:55]
	v_mfma_f32_16x16x32_bf16 v[48:51], v[228:231], v[182:185], v[48:51]
	v_mfma_f32_16x16x32_bf16 v[36:39], v[220:223], v[196:199], v[36:39]
	v_mfma_f32_16x16x32_bf16 v[32:35], v[228:231], v[196:199], v[32:35]
	v_mfma_f32_16x16x32_bf16 v[20:23], v[220:223], v[204:207], v[20:23]
	v_mfma_f32_16x16x32_bf16 v[16:19], v[228:231], v[204:207], v[16:19]
	v_mfma_f32_16x16x32_bf16 v[4:7], v[220:223], v[212:215], v[4:7]
	v_mfma_f32_16x16x32_bf16 v[0:3], v[228:231], v[212:215], v[0:3]
	s_setprio 0
	s_add_i32 s78, s78, 2
	s_add_u32 s0, s0, 0x100
	s_addc_u32 s1, s1, 0
	s_add_u32 s76, s76, 0x100
	s_addc_u32 s77, s77, 0
	s_cmp_gt_u32 s78, 13
	s_barrier
	s_cbranch_scc0 .LBB0_904
	s_branch .Lz7_skip
.Lz7_0_first:
	v_mfma_f32_16x16x32_bf16 v[124:127], v[146:149], v[178:181], 0
	v_mfma_f32_16x16x32_bf16 v[120:123], v[154:157], v[178:181], 0
	v_mfma_f32_16x16x32_bf16 v[108:111], v[146:149], v[186:189], 0
	v_mfma_f32_16x16x32_bf16 v[104:107], v[154:157], v[186:189], 0
	v_mfma_f32_16x16x32_bf16 v[92:95], v[146:149], v[200:203], 0
	v_mfma_f32_16x16x32_bf16 v[88:91], v[154:157], v[200:203], 0
	v_mfma_f32_16x16x32_bf16 v[76:79], v[146:149], v[208:211], 0
	v_mfma_f32_16x16x32_bf16 v[72:75], v[154:157], v[208:211], 0
	v_mfma_f32_16x16x32_bf16 v[124:127], v[150:153], v[182:185], v[124:127]
	v_mfma_f32_16x16x32_bf16 v[120:123], v[174:177], v[182:185], v[120:123]
	v_mfma_f32_16x16x32_bf16 v[108:111], v[150:153], v[196:199], v[108:111]
	v_mfma_f32_16x16x32_bf16 v[104:107], v[174:177], v[196:199], v[104:107]
	v_mfma_f32_16x16x32_bf16 v[92:95], v[150:153], v[204:207], v[92:95]
	v_mfma_f32_16x16x32_bf16 v[88:91], v[174:177], v[204:207], v[88:91]
	v_mfma_f32_16x16x32_bf16 v[76:79], v[150:153], v[212:215], v[76:79]
	v_mfma_f32_16x16x32_bf16 v[72:75], v[174:177], v[212:215], v[72:75]
	s_branch .Lz7_0_join
.Lz7_1_first:
	v_mfma_f32_16x16x32_bf16 v[116:119], v[216:219], v[178:181], 0
	v_mfma_f32_16x16x32_bf16 v[112:115], v[224:227], v[178:181], 0
	v_mfma_f32_16x16x32_bf16 v[100:103], v[216:219], v[186:189], 0
	v_mfma_f32_16x16x32_bf16 v[96:99], v[224:227], v[186:189], 0
	v_mfma_f32_16x16x32_bf16 v[84:87], v[216:219], v[200:203], 0
	v_mfma_f32_16x16x32_bf16 v[80:83], v[224:227], v[200:203], 0
	v_mfma_f32_16x16x32_bf16 v[68:71], v[216:219], v[208:211], 0
	v_mfma_f32_16x16x32_bf16 v[64:67], v[224:227], v[208:211], 0
	v_mfma_f32_16x16x32_bf16 v[116:119], v[220:223], v[182:185], v[116:119]
	v_mfma_f32_16x16x32_bf16 v[112:115], v[228:231], v[182:185], v[112:115]
	v_mfma_f32_16x16x32_bf16 v[100:103], v[220:223], v[196:199], v[100:103]
	v_mfma_f32_16x16x32_bf16 v[96:99], v[228:231], v[196:199], v[96:99]
	v_mfma_f32_16x16x32_bf16 v[84:87], v[220:223], v[204:207], v[84:87]
	v_mfma_f32_16x16x32_bf16 v[80:83], v[228:231], v[204:207], v[80:83]
	v_mfma_f32_16x16x32_bf16 v[68:71], v[220:223], v[212:215], v[68:71]
	v_mfma_f32_16x16x32_bf16 v[64:67], v[228:231], v[212:215], v[64:67]
	s_branch .Lz7_1_join
.Lz7_2_first:
	v_mfma_f32_16x16x32_bf16 v[60:63], v[146:149], v[178:181], 0
	v_mfma_f32_16x16x32_bf16 v[56:59], v[154:157], v[178:181], 0
	v_mfma_f32_16x16x32_bf16 v[44:47], v[146:149], v[186:189], 0
	v_mfma_f32_16x16x32_bf16 v[40:43], v[154:157], v[186:189], 0
	v_mfma_f32_16x16x32_bf16 v[28:31], v[146:149], v[200:203], 0
	v_mfma_f32_16x16x32_bf16 v[24:27], v[154:157], v[200:203], 0
	v_mfma_f32_16x16x32_bf16 v[12:15], v[146:149], v[208:211], 0
	v_mfma_f32_16x16x32_bf16 v[8:11], v[154:157], v[208:211], 0
	v_mfma_f32_16x16x32_bf16 v[60:63], v[150:153], v[182:185], v[60:63]
	v_mfma_f32_16x16x32_bf16 v[56:59], v[174:177], v[182:185], v[56:59]
	v_mfma_f32_16x16x32_bf16 v[44:47], v[150:153], v[196:199], v[44:47]
	v_mfma_f32_16x16x32_bf16 v[40:43], v[174:177], v[196:199], v[40:43]
	v_mfma_f32_16x16x32_bf16 v[28:31], v[150:153], v[204:207], v[28:31]
	v_mfma_f32_16x16x32_bf16 v[24:27], v[174:177], v[204:207], v[24:27]
	v_mfma_f32_16x16x32_bf16 v[12:15], v[150:153], v[212:215], v[12:15]
	v_mfma_f32_16x16x32_bf16 v[8:11], v[174:177], v[212:215], v[8:11]
	s_branch .Lz7_2_join
.Lz7_3_first:
	v_mfma_f32_16x16x32_bf16 v[52:55], v[216:219], v[178:181], 0
	v_mfma_f32_16x16x32_bf16 v[48:51], v[224:227], v[178:181], 0
	v_mfma_f32_16x16x32_bf16 v[36:39], v[216:219], v[186:189], 0
	v_mfma_f32_16x16x32_bf16 v[32:35], v[224:227], v[186:189], 0
	v_mfma_f32_16x16x32_bf16 v[20:23], v[216:219], v[200:203], 0
	v_mfma_f32_16x16x32_bf16 v[16:19], v[224:227], v[200:203], 0
	v_mfma_f32_16x16x32_bf16 v[4:7], v[216:219], v[208:211], 0
	v_mfma_f32_16x16x32_bf16 v[0:3], v[224:227], v[208:211], 0
	v_mfma_f32_16x16x32_bf16 v[52:55], v[220:223], v[182:185], v[52:55]
	v_mfma_f32_16x16x32_bf16 v[48:51], v[228:231], v[182:185], v[48:51]
	v_mfma_f32_16x16x32_bf16 v[36:39], v[220:223], v[196:199], v[36:39]
	v_mfma_f32_16x16x32_bf16 v[32:35], v[228:231], v[196:199], v[32:35]
	v_mfma_f32_16x16x32_bf16 v[20:23], v[220:223], v[204:207], v[20:23]
	v_mfma_f32_16x16x32_bf16 v[16:19], v[228:231], v[204:207], v[16:19]
	v_mfma_f32_16x16x32_bf16 v[4:7], v[220:223], v[212:215], v[4:7]
	v_mfma_f32_16x16x32_bf16 v[0:3], v[228:231], v[212:215], v[0:3]
	s_branch .Lz7_3_join
.Lz7_skip:
	v_lshl_add_u32 v146, s6, 8, v161
	v_or_b32_e32 v164, 16, v146
	v_ashrrev_i32_e32 v165, 31, v164
	v_lshlrev_b64 v[148:149], 6, v[164:165]
	v_or_b32_e32 v158, 32, v146
	v_lshl_add_u64 v[148:149], v[136:137], 0, v[148:149]
	v_ashrrev_i32_e32 v159, 31, v158
	v_or_b32_e32 v156, 48, v146
	global_load_dwordx4 v[174:177], v[148:149], off
	v_lshlrev_b64 v[148:149], 6, v[158:159]
	v_ashrrev_i32_e32 v157, 31, v156
	v_add_u32_e32 v154, 0x80, v146
	v_lshl_add_u64 v[148:149], v[136:137], 0, v[148:149]
	v_lshlrev_b64 v[150:151], 6, v[156:157]
	v_ashrrev_i32_e32 v155, 31, v154
	v_lshl_add_u64 v[150:151], v[136:137], 0, v[150:151]
	global_load_dwordx4 v[178:181], v[148:149], off
	global_load_dwordx4 v[182:185], v[150:151], off
	v_lshlrev_b64 v[148:149], 6, v[154:155]
	v_lshl_add_u64 v[148:149], v[136:137], 0, v[148:149]
	global_load_dwordx4 v[186:189], v[148:149], off
	v_ashrrev_i32_e32 v147, 31, v146
	v_lshlrev_b64 v[148:149], 6, v[146:147]
	v_add_u32_e32 v152, 0x90, v146
	v_lshl_add_u64 v[148:149], v[136:137], 0, v[148:149]
	v_ashrrev_i32_e32 v153, 31, v152
	global_load_dwordx4 v[196:199], v[148:149], off
	v_lshlrev_b64 v[148:149], 6, v[152:153]
	v_lshl_add_u64 v[148:149], v[136:137], 0, v[148:149]
	global_load_dwordx4 v[200:203], v[148:149], off
	v_add_u32_e32 v148, 0xa0, v146
	v_ashrrev_i32_e32 v149, 31, v148
	v_lshlrev_b64 v[150:151], 6, v[148:149]
	v_lshl_add_u64 v[150:151], v[136:137], 0, v[150:151]
	global_load_dwordx4 v[204:207], v[150:151], off
	v_add_u32_e32 v150, 0xb0, v146
	v_ashrrev_i32_e32 v151, 31, v150
	v_lshlrev_b64 v[208:209], 6, v[150:151]
	v_lshl_add_u64 v[208:209], v[136:137], 0, v[208:209]
	global_load_dwordx4 v[208:211], v[208:209], off
	v_and_b32_e32 v149, 64, v173
	v_xor_b32_e32 v147, 16, v173
	v_add_u32_e32 v149, 64, v149
	v_cmp_lt_i32_e32 vcc, v147, v149
	v_xor_b32_e32 v153, 32, v173
	v_mov_b64_e32 v[190:191], s[12:13]
	v_cndmask_b32_e32 v147, v173, v147, vcc
	v_lshlrev_b32_e32 v147, 2, v147
	v_cmp_lt_i32_e32 vcc, v153, v149
	s_waitcnt vmcnt(0)
	v_mov_b32_e32 v212, v175
	v_mov_b32_e32 v213, v176
	v_mov_b32_e32 v175, v177
	v_pk_add_f32 v[174:175], v[212:213], v[174:175]
	v_cndmask_b32_e32 v149, v173, v153, vcc
	v_lshlrev_b32_e32 v149, 2, v149
	v_mov_b32_e32 v176, v179
	v_mov_b32_e32 v177, v180
	v_mov_b32_e32 v179, v181
	v_mov_b32_e32 v180, v183
	v_mov_b32_e32 v181, v184
	v_mov_b32_e32 v183, v185
	v_mov_b32_e32 v184, v187
	v_mov_b32_e32 v185, v188
	v_mov_b32_e32 v187, v189
	v_pk_add_f32 v[176:177], v[176:177], v[178:179]
	v_pk_add_f32 v[178:179], v[180:181], v[182:183]
	v_pk_add_f32 v[180:181], v[184:185], v[186:187]
	v_mov_b32_e32 v182, v176
	v_mov_b32_e32 v183, v174
	v_mov_b32_e32 v174, v177
	v_mov_b32_e32 v176, v180
	v_mov_b32_e32 v177, v178
	v_mov_b32_e32 v178, v181
	v_pk_add_f32 v[174:175], v[182:183], v[174:175]
	v_pk_add_f32 v[176:177], v[176:177], v[178:179]
	ds_bpermute_b32 v179, v147, v175
	ds_bpermute_b32 v178, v147, v174
	ds_bpermute_b32 v181, v147, v177
	ds_bpermute_b32 v180, v147, v176
	v_mov_b32_e32 v184, v201
	v_mov_b32_e32 v185, v202
	s_waitcnt lgkmcnt(0)
	v_pk_add_f32 v[174:175], v[174:175], v[178:179]
	ds_bpermute_b32 v179, v149, v175
	v_pk_add_f32 v[176:177], v[176:177], v[180:181]
	ds_bpermute_b32 v178, v149, v174
	ds_bpermute_b32 v181, v149, v177
	ds_bpermute_b32 v180, v149, v176
	v_mov_b32_e32 v201, v203
	v_mov_b32_e32 v182, v197
	s_waitcnt lgkmcnt(2)
	v_pk_add_f32 v[174:175], v[174:175], v[178:179]
	v_pk_add_f32 v[178:179], v[184:185], v[200:201]
	s_waitcnt lgkmcnt(0)
	v_pk_add_f32 v[176:177], v[176:177], v[180:181]
	v_pk_fma_f32 v[174:175], v[174:175], s[10:11], v[190:191] op_sel_hi:[1,0,0]
	v_mov_b32_e32 v180, v205
	v_mov_b32_e32 v181, v206
	v_mov_b32_e32 v205, v207
	v_mul_f32_e32 v151, 0x4b800000, v175
	v_cmp_gt_f32_e32 vcc, s65, v175
	v_pk_add_f32 v[180:181], v[180:181], v[204:205]
	v_mov_b32_e32 v185, v178
	v_cndmask_b32_e32 v151, v175, v151, vcc
	v_mov_b32_e32 v184, v180
	v_mov_b32_e32 v178, v181
	v_rsq_f32_e32 v151, v151
	v_pk_add_f32 v[178:179], v[184:185], v[178:179]
	ds_bpermute_b32 v181, v147, v179
	ds_bpermute_b32 v180, v147, v178
	v_pk_fma_f32 v[176:177], v[176:177], s[10:11], v[190:191] op_sel_hi:[1,0,0]
	v_mul_f32_e32 v153, 0x4b800000, v174
	v_cmp_gt_f32_e64 s[0:1], s65, v174
	v_mul_f32_e32 v157, 0x45800000, v151
	v_mul_f32_e32 v155, 0x4b800000, v177
	v_cndmask_b32_e64 v153, v174, v153, s[0:1]
	v_cmp_gt_f32_e64 s[6:7], s65, v177
	v_cndmask_b32_e32 v174, v151, v157, vcc
	v_mul_f32_e32 v151, 0x4b800000, v176
	v_cmp_gt_f32_e32 vcc, s65, v176
	v_cndmask_b32_e64 v155, v177, v155, s[6:7]
	v_rsq_f32_e32 v153, v153
	v_cndmask_b32_e32 v151, v176, v151, vcc
	s_waitcnt lgkmcnt(0)
	v_pk_add_f32 v[176:177], v[178:179], v[180:181]
	ds_bpermute_b32 v179, v149, v177
	ds_bpermute_b32 v178, v149, v176
	v_rsq_f32_e32 v155, v155
	v_mul_f32_e32 v159, 0x45800000, v153
	v_cndmask_b32_e64 v180, v153, v159, s[0:1]
	v_rsq_f32_e32 v151, v151
	s_waitcnt lgkmcnt(0)
	v_pk_add_f32 v[176:177], v[176:177], v[178:179]
	v_mul_f32_e32 v153, 0x45800000, v155
	v_pk_fma_f32 v[176:177], v[176:177], s[10:11], v[190:191] op_sel_hi:[1,0,0]
	v_cndmask_b32_e64 v170, v155, v153, s[6:7]
	v_mul_f32_e32 v155, 0x4b800000, v177
	v_cmp_gt_f32_e64 s[0:1], s65, v177
	v_mul_f32_e32 v157, 0x4b800000, v176
	v_cmp_gt_f32_e64 s[6:7], s65, v176
	v_cndmask_b32_e64 v155, v177, v155, s[0:1]
	v_rsq_f32_e32 v155, v155
	v_cndmask_b32_e64 v157, v176, v157, s[6:7]
	v_rsq_f32_e32 v157, v157
	v_mul_f32_e32 v153, 0x45800000, v151
	v_cndmask_b32_e32 v168, v151, v153, vcc
	v_mul_f32_e32 v151, 0x45800000, v155
	v_mov_b32_e32 v183, v198
	v_mov_b32_e32 v197, v199
	v_cndmask_b32_e64 v166, v155, v151, s[0:1]
	v_mul_f32_e32 v151, 0x45800000, v157
	v_mov_b32_e32 v176, v209
	v_mov_b32_e32 v177, v210
	v_mov_b32_e32 v209, v211
	v_pk_add_f32 v[182:183], v[182:183], v[196:197]
	v_cndmask_b32_e64 v162, v157, v151, s[6:7]
	v_pk_add_f32 v[176:177], v[176:177], v[208:209]
	v_mov_b32_e32 v178, v182
	v_mov_b32_e32 v179, v176
	v_mov_b32_e32 v176, v183
	v_pk_add_f32 v[176:177], v[178:179], v[176:177]
	ds_bpermute_b32 v178, v147, v176
	ds_bpermute_b32 v179, v147, v177
	v_lshl_or_b32 v182, s66, 8, v167
	v_pk_mul_f32 v[100:101], v[100:101], v[174:175] op_sel_hi:[1,0]
	v_pk_mul_f32 v[108:109], v[108:109], v[174:175] op_sel_hi:[1,0]
	v_ashrrev_i32_e32 v183, 31, v182
	s_waitcnt lgkmcnt(0)
	v_pk_add_f32 v[176:177], v[176:177], v[178:179]
	ds_bpermute_b32 v178, v149, v176
	ds_bpermute_b32 v179, v149, v177
	v_pk_mul_f32 v[96:97], v[96:97], v[174:175] op_sel_hi:[1,0]
	v_pk_mul_f32 v[102:103], v[102:103], v[174:175] op_sel_hi:[1,0]
	v_pk_mul_f32 v[110:111], v[110:111], v[174:175] op_sel_hi:[1,0]
	v_cvt_pk_bf16_f32 v108, v108, v109
	s_waitcnt lgkmcnt(0)
	v_pk_add_f32 v[176:177], v[176:177], v[178:179]
	v_pk_mul_f32 v[106:107], v[106:107], v[174:175] op_sel_hi:[1,0]
	v_pk_fma_f32 v[176:177], v[176:177], s[10:11], v[190:191] op_sel_hi:[1,0,0]
	v_pk_mul_f32 v[104:105], v[104:105], v[174:175] op_sel_hi:[1,0]
	v_mul_f32_e32 v147, 0x4b800000, v177
	v_cmp_gt_f32_e32 vcc, s65, v177
	v_mul_f32_e32 v149, 0x4b800000, v176
	v_cmp_gt_f32_e64 s[0:1], s65, v176
	v_cndmask_b32_e32 v147, v177, v147, vcc
	v_rsq_f32_e32 v147, v147
	v_cndmask_b32_e64 v149, v176, v149, s[0:1]
	v_rsq_f32_e32 v149, v149
	v_cvt_pk_bf16_f32 v100, v100, v101
	v_mul_f32_e32 v151, 0x45800000, v147
	v_cndmask_b32_e32 v160, v147, v151, vcc
	v_mul_f32_e32 v147, 0x45800000, v149
	v_cndmask_b32_e64 v176, v149, v147, s[0:1]
	v_pk_mul_f32 v[112:113], v[112:113], v[176:177] op_sel_hi:[1,0]
	v_pk_mul_f32 v[116:117], v[116:117], v[176:177] op_sel_hi:[1,0]
	v_pk_mul_f32 v[124:125], v[124:125], v[176:177] op_sel_hi:[1,0]
	v_pk_mul_f32 v[122:123], v[122:123], v[176:177] op_sel_hi:[1,0]
	v_pk_mul_f32 v[120:121], v[120:121], v[176:177] op_sel_hi:[1,0]
	v_pk_mul_f32 v[114:115], v[114:115], v[176:177] op_sel_hi:[1,0]
	v_pk_mul_f32 v[118:119], v[118:119], v[176:177] op_sel_hi:[1,0]
	v_pk_mul_f32 v[126:127], v[126:127], v[176:177] op_sel_hi:[1,0]
	v_cvt_pk_bf16_f32 v124, v124, v125
	v_cvt_pk_bf16_f32 v120, v120, v121
	v_cvt_pk_bf16_f32 v121, v122, v123
	v_cvt_pk_bf16_f32 v122, v116, v117
	v_cvt_pk_bf16_f32 v112, v112, v113
	v_cvt_pk_bf16_f32 v125, v126, v127
	v_cvt_pk_bf16_f32 v118, v118, v119
	v_cvt_pk_bf16_f32 v113, v114, v115
	v_cndmask_b32_e64 v114, v124, v122, s[2:3]
	v_mov_b32_e32 v123, 0
	v_cndmask_b32_e64 v115, v120, v112, s[2:3]
	v_mov_b32_e32 v126, 0
	v_mov_b32_dpp v123, v114 row_ror:8 row_mask:0xf bank_mask:0xf
	v_cndmask_b32_e64 v114, v125, v118, s[2:3]
	v_mov_b32_e32 v119, 0
	v_mov_b32_dpp v126, v115 row_ror:8 row_mask:0xf bank_mask:0xf
	v_mov_b32_e32 v127, 0
	v_mov_b32_dpp v119, v114 row_ror:8 row_mask:0xf bank_mask:0xf
	v_cndmask_b32_e64 v114, v121, v113, s[2:3]
	v_cndmask_b32_e64 v116, v126, v120, s[2:3]
	v_cndmask_b32_e64 v120, v112, v126, s[2:3]
	v_add_u32_e32 v112, -8, v146
	v_mov_b32_dpp v127, v114 row_ror:8 row_mask:0xf bank_mask:0xf
	v_cndmask_b32_e64 v112, v112, v146, s[2:3]
	v_cndmask_b32_e64 v117, v127, v121, s[2:3]
	v_cndmask_b32_e64 v121, v113, v127, s[2:3]
	v_ashrrev_i32_e32 v113, 31, v112
	v_lshlrev_b64 v[112:113], 10, v[112:113]
	v_cndmask_b32_e64 v115, v119, v125, s[2:3]
	v_cndmask_b32_e64 v114, v123, v124, s[2:3]
	v_cndmask_b32_e64 v119, v118, v119, s[2:3]
	v_cndmask_b32_e64 v118, v122, v123, s[2:3]
	v_lshl_add_u64 v[122:123], s[38:39], 0, v[112:113]
	v_lshlrev_b64 v[112:113], 1, v[182:183]
	v_pk_mul_f32 v[98:99], v[98:99], v[174:175] op_sel_hi:[1,0]
	v_cvt_pk_bf16_f32 v109, v110, v111
	v_cvt_pk_bf16_f32 v104, v104, v105
	v_cvt_pk_bf16_f32 v105, v106, v107
	v_cvt_pk_bf16_f32 v101, v102, v103
	v_cvt_pk_bf16_f32 v102, v96, v97
	v_cndmask_b32_e64 v96, v108, v100, s[2:3]
	v_mov_b32_e32 v106, 0
	v_lshl_add_u64 v[122:123], v[122:123], 0, v[112:113]
	v_cvt_pk_bf16_f32 v103, v98, v99
	v_mov_b32_dpp v106, v96 row_ror:8 row_mask:0xf bank_mask:0xf
	v_cndmask_b32_e64 v96, v109, v101, s[2:3]
	v_mov_b32_e32 v107, 0
	v_cndmask_b32_e64 v97, v104, v102, s[2:3]
	v_mov_b32_e32 v110, 0
	global_store_dwordx4 v[122:123], v[114:117], off
	v_mov_b32_dpp v107, v96 row_ror:8 row_mask:0xf bank_mask:0xf
	v_cndmask_b32_e64 v96, v105, v103, s[2:3]
	v_add_u32_e32 v116, 8, v146
	v_mov_b32_dpp v110, v97 row_ror:8 row_mask:0xf bank_mask:0xf
	v_mov_b32_e32 v111, 0
	v_cndmask_b32_e64 v114, v146, v116, s[2:3]
	v_cndmask_b32_e64 v98, v110, v104, s[2:3]
	v_mov_b32_dpp v111, v96 row_ror:8 row_mask:0xf bank_mask:0xf
	v_cndmask_b32_e64 v104, v116, v164, s[2:3]
	v_ashrrev_i32_e32 v115, 31, v114
	v_cndmask_b32_e64 v99, v111, v105, s[2:3]
	v_ashrrev_i32_e32 v105, 31, v104
	v_pk_mul_f32 v[84:85], v[84:85], v[180:181] op_sel_hi:[1,0]
	v_pk_mul_f32 v[92:93], v[92:93], v[180:181] op_sel_hi:[1,0]
	v_lshlrev_b64 v[114:115], 10, v[114:115]
	v_lshlrev_b64 v[104:105], 10, v[104:105]
	v_pk_mul_f32 v[80:81], v[80:81], v[180:181] op_sel_hi:[1,0]
	v_pk_mul_f32 v[86:87], v[86:87], v[180:181] op_sel_hi:[1,0]
	v_pk_mul_f32 v[94:95], v[94:95], v[180:181] op_sel_hi:[1,0]
	v_cvt_pk_bf16_f32 v92, v92, v93
	v_pk_mul_f32 v[90:91], v[90:91], v[180:181] op_sel_hi:[1,0]
	v_pk_mul_f32 v[88:89], v[88:89], v[180:181] op_sel_hi:[1,0]
	v_cvt_pk_bf16_f32 v84, v84, v85
	v_lshl_add_u64 v[114:115], s[38:39], 0, v[114:115]
	v_lshl_add_u64 v[104:105], s[38:39], 0, v[104:105]
	v_pk_mul_f32 v[82:83], v[82:83], v[180:181] op_sel_hi:[1,0]
	v_cvt_pk_bf16_f32 v93, v94, v95
	v_cvt_pk_bf16_f32 v88, v88, v89
	v_cvt_pk_bf16_f32 v89, v90, v91
	v_cvt_pk_bf16_f32 v85, v86, v87
	v_cvt_pk_bf16_f32 v86, v80, v81
	v_cndmask_b32_e64 v80, v92, v84, s[2:3]
	v_mov_b32_e32 v90, 0
	v_lshl_add_u64 v[114:115], v[114:115], 0, v[112:113]
	v_cndmask_b32_e64 v97, v107, v109, s[2:3]
	v_cndmask_b32_e64 v96, v106, v108, s[2:3]
	v_lshl_add_u64 v[104:105], v[104:105], 0, v[112:113]
	v_cvt_pk_bf16_f32 v87, v82, v83
	v_mov_b32_dpp v90, v80 row_ror:8 row_mask:0xf bank_mask:0xf
	v_cndmask_b32_e64 v80, v93, v85, s[2:3]
	v_mov_b32_e32 v91, 0
	v_cndmask_b32_e64 v81, v88, v86, s[2:3]
	v_mov_b32_e32 v94, 0
	global_store_dwordx4 v[114:115], v[118:121], off
	global_store_dwordx4 v[104:105], v[96:99], off
	v_mov_b32_dpp v91, v80 row_ror:8 row_mask:0xf bank_mask:0xf
	v_cndmask_b32_e64 v80, v89, v87, s[2:3]
	v_add_u32_e32 v98, 24, v146
	v_mov_b32_dpp v94, v81 row_ror:8 row_mask:0xf bank_mask:0xf
	v_mov_b32_e32 v95, 0
	v_cndmask_b32_e64 v96, v164, v98, s[2:3]
	v_cndmask_b32_e64 v82, v94, v88, s[2:3]
	v_mov_b32_dpp v95, v80 row_ror:8 row_mask:0xf bank_mask:0xf
	v_cndmask_b32_e64 v88, v98, v158, s[2:3]
	v_ashrrev_i32_e32 v97, 31, v96
	v_cndmask_b32_e64 v83, v95, v89, s[2:3]
	v_ashrrev_i32_e32 v89, 31, v88
	v_pk_mul_f32 v[68:69], v[68:69], v[170:171] op_sel_hi:[1,0]
	v_pk_mul_f32 v[76:77], v[76:77], v[170:171] op_sel_hi:[1,0]
	v_lshlrev_b64 v[96:97], 10, v[96:97]
	v_lshlrev_b64 v[88:89], 10, v[88:89]
	v_pk_mul_f32 v[64:65], v[64:65], v[170:171] op_sel_hi:[1,0]
	v_pk_mul_f32 v[70:71], v[70:71], v[170:171] op_sel_hi:[1,0]
	v_pk_mul_f32 v[78:79], v[78:79], v[170:171] op_sel_hi:[1,0]
	v_cvt_pk_bf16_f32 v76, v76, v77
	v_pk_mul_f32 v[74:75], v[74:75], v[170:171] op_sel_hi:[1,0]
	v_pk_mul_f32 v[72:73], v[72:73], v[170:171] op_sel_hi:[1,0]
	v_cvt_pk_bf16_f32 v68, v68, v69
	v_lshl_add_u64 v[96:97], s[38:39], 0, v[96:97]
	v_lshl_add_u64 v[88:89], s[38:39], 0, v[88:89]
	v_pk_mul_f32 v[66:67], v[66:67], v[170:171] op_sel_hi:[1,0]
	v_cvt_pk_bf16_f32 v77, v78, v79
	v_cvt_pk_bf16_f32 v72, v72, v73
	v_cvt_pk_bf16_f32 v73, v74, v75
	v_cvt_pk_bf16_f32 v69, v70, v71
	v_cvt_pk_bf16_f32 v70, v64, v65
	v_cndmask_b32_e64 v64, v76, v68, s[2:3]
	v_mov_b32_e32 v74, 0
	v_cndmask_b32_e64 v103, v103, v111, s[2:3]
	v_cndmask_b32_e64 v102, v102, v110, s[2:3]
	v_cndmask_b32_e64 v101, v101, v107, s[2:3]
	v_cndmask_b32_e64 v100, v100, v106, s[2:3]
	v_lshl_add_u64 v[96:97], v[96:97], 0, v[112:113]
	v_cndmask_b32_e64 v81, v91, v93, s[2:3]
	v_cndmask_b32_e64 v80, v90, v92, s[2:3]
	v_lshl_add_u64 v[88:89], v[88:89], 0, v[112:113]
	v_cvt_pk_bf16_f32 v71, v66, v67
	v_mov_b32_dpp v74, v64 row_ror:8 row_mask:0xf bank_mask:0xf
	v_cndmask_b32_e64 v64, v77, v69, s[2:3]
	v_mov_b32_e32 v75, 0
	v_cndmask_b32_e64 v65, v72, v70, s[2:3]
	v_mov_b32_e32 v78, 0
	global_store_dwordx4 v[96:97], v[100:103], off
	global_store_dwordx4 v[88:89], v[80:83], off
	v_mov_b32_dpp v75, v64 row_ror:8 row_mask:0xf bank_mask:0xf
	v_cndmask_b32_e64 v64, v73, v71, s[2:3]
	v_add_u32_e32 v82, 40, v146
	v_mov_b32_dpp v78, v65 row_ror:8 row_mask:0xf bank_mask:0xf
	v_mov_b32_e32 v79, 0
	v_cndmask_b32_e64 v80, v158, v82, s[2:3]
	v_cndmask_b32_e64 v66, v78, v72, s[2:3]
	v_mov_b32_dpp v79, v64 row_ror:8 row_mask:0xf bank_mask:0xf
	v_cndmask_b32_e64 v72, v82, v156, s[2:3]
	v_ashrrev_i32_e32 v81, 31, v80
	v_cndmask_b32_e64 v67, v79, v73, s[2:3]
	v_ashrrev_i32_e32 v73, 31, v72
	v_pk_mul_f32 v[48:49], v[48:49], v[168:169] op_sel_hi:[1,0]
	v_pk_mul_f32 v[54:55], v[54:55], v[168:169] op_sel_hi:[1,0]
	v_pk_mul_f32 v[52:53], v[52:53], v[168:169] op_sel_hi:[1,0]
	v_pk_mul_f32 v[60:61], v[60:61], v[168:169] op_sel_hi:[1,0]
	v_pk_mul_f32 v[56:57], v[56:57], v[168:169] op_sel_hi:[1,0]
	v_lshlrev_b64 v[80:81], 10, v[80:81]
	v_lshlrev_b64 v[72:73], 10, v[72:73]
	v_pk_mul_f32 v[62:63], v[62:63], v[168:169] op_sel_hi:[1,0]
	v_cvt_pk_bf16_f32 v60, v60, v61
	v_pk_mul_f32 v[58:59], v[58:59], v[168:169] op_sel_hi:[1,0]
	v_cvt_pk_bf16_f32 v56, v56, v57
	v_cvt_pk_bf16_f32 v52, v52, v53
	v_cvt_pk_bf16_f32 v53, v54, v55
	v_cvt_pk_bf16_f32 v54, v48, v49
	v_lshl_add_u64 v[80:81], s[38:39], 0, v[80:81]
	v_lshl_add_u64 v[72:73], s[38:39], 0, v[72:73]
	v_pk_mul_f32 v[50:51], v[50:51], v[168:169] op_sel_hi:[1,0]
	v_cvt_pk_bf16_f32 v61, v62, v63
	v_cvt_pk_bf16_f32 v57, v58, v59
	v_cndmask_b32_e64 v48, v60, v52, s[2:3]
	v_mov_b32_e32 v58, 0
	v_cndmask_b32_e64 v49, v56, v54, s[2:3]
	v_mov_b32_e32 v62, 0
	v_cndmask_b32_e64 v87, v87, v95, s[2:3]
	v_cndmask_b32_e64 v86, v86, v94, s[2:3]
	v_cndmask_b32_e64 v85, v85, v91, s[2:3]
	v_cndmask_b32_e64 v84, v84, v90, s[2:3]
	v_lshl_add_u64 v[80:81], v[80:81], 0, v[112:113]
	v_cndmask_b32_e64 v65, v75, v77, s[2:3]
	v_cndmask_b32_e64 v64, v74, v76, s[2:3]
	v_lshl_add_u64 v[72:73], v[72:73], 0, v[112:113]
	v_cvt_pk_bf16_f32 v55, v50, v51
	v_mov_b32_dpp v58, v48 row_ror:8 row_mask:0xf bank_mask:0xf
	v_cndmask_b32_e64 v48, v61, v53, s[2:3]
	v_mov_b32_e32 v59, 0
	v_mov_b32_dpp v62, v49 row_ror:8 row_mask:0xf bank_mask:0xf
	global_store_dwordx4 v[80:81], v[84:87], off
	global_store_dwordx4 v[72:73], v[64:67], off
	v_mov_b32_dpp v59, v48 row_ror:8 row_mask:0xf bank_mask:0xf
	v_cndmask_b32_e64 v48, v57, v55, s[2:3]
	v_add_u32_e32 v64, 56, v146
	v_mov_b32_e32 v63, 0
	v_cndmask_b32_e64 v50, v62, v56, s[2:3]
	v_add_u32_e32 v56, 0x78, v146
	v_cndmask_b32_e64 v64, v156, v64, s[2:3]
	v_mov_b32_dpp v63, v48 row_ror:8 row_mask:0xf bank_mask:0xf
	v_cndmask_b32_e64 v56, v56, v154, s[2:3]
	v_ashrrev_i32_e32 v65, 31, v64
	v_cndmask_b32_e64 v51, v63, v57, s[2:3]
	v_ashrrev_i32_e32 v57, 31, v56
	v_pk_mul_f32 v[36:37], v[36:37], v[166:167] op_sel_hi:[1,0]
	v_pk_mul_f32 v[44:45], v[44:45], v[166:167] op_sel_hi:[1,0]
	v_lshlrev_b64 v[64:65], 10, v[64:65]
	v_lshlrev_b64 v[56:57], 10, v[56:57]
	v_pk_mul_f32 v[32:33], v[32:33], v[166:167] op_sel_hi:[1,0]
	v_pk_mul_f32 v[38:39], v[38:39], v[166:167] op_sel_hi:[1,0]
	v_pk_mul_f32 v[46:47], v[46:47], v[166:167] op_sel_hi:[1,0]
	v_cvt_pk_bf16_f32 v44, v44, v45
	v_pk_mul_f32 v[42:43], v[42:43], v[166:167] op_sel_hi:[1,0]
	v_pk_mul_f32 v[40:41], v[40:41], v[166:167] op_sel_hi:[1,0]
	v_cvt_pk_bf16_f32 v36, v36, v37
	v_lshl_add_u64 v[64:65], s[38:39], 0, v[64:65]
	v_lshl_add_u64 v[56:57], s[38:39], 0, v[56:57]
	v_pk_mul_f32 v[34:35], v[34:35], v[166:167] op_sel_hi:[1,0]
	v_cvt_pk_bf16_f32 v45, v46, v47
	v_cvt_pk_bf16_f32 v40, v40, v41
	v_cvt_pk_bf16_f32 v41, v42, v43
	v_cvt_pk_bf16_f32 v37, v38, v39
	v_cvt_pk_bf16_f32 v38, v32, v33
	v_cndmask_b32_e64 v32, v44, v36, s[2:3]
	v_mov_b32_e32 v42, 0
	v_cndmask_b32_e64 v71, v71, v79, s[2:3]
	v_cndmask_b32_e64 v70, v70, v78, s[2:3]
	v_cndmask_b32_e64 v69, v69, v75, s[2:3]
	v_cndmask_b32_e64 v68, v68, v74, s[2:3]
	v_lshl_add_u64 v[64:65], v[64:65], 0, v[112:113]
	v_cndmask_b32_e64 v49, v59, v61, s[2:3]
	v_cndmask_b32_e64 v48, v58, v60, s[2:3]
	v_lshl_add_u64 v[56:57], v[56:57], 0, v[112:113]
	v_cvt_pk_bf16_f32 v39, v34, v35
	v_mov_b32_dpp v42, v32 row_ror:8 row_mask:0xf bank_mask:0xf
	v_cndmask_b32_e64 v32, v45, v37, s[2:3]
	v_mov_b32_e32 v43, 0
	v_cndmask_b32_e64 v33, v40, v38, s[2:3]
	v_mov_b32_e32 v46, 0
	global_store_dwordx4 v[64:65], v[68:71], off
	global_store_dwordx4 v[56:57], v[48:51], off
	v_mov_b32_dpp v43, v32 row_ror:8 row_mask:0xf bank_mask:0xf
	v_cndmask_b32_e64 v32, v41, v39, s[2:3]
	v_add_u32_e32 v50, 0x88, v146
	v_mov_b32_dpp v46, v33 row_ror:8 row_mask:0xf bank_mask:0xf
	v_mov_b32_e32 v47, 0
	v_cndmask_b32_e64 v34, v46, v40, s[2:3]
	v_cndmask_b32_e64 v40, v50, v152, s[2:3]
	v_mov_b32_dpp v47, v32 row_ror:8 row_mask:0xf bank_mask:0xf
	v_cndmask_b32_e64 v35, v47, v41, s[2:3]
	v_ashrrev_i32_e32 v41, 31, v40
	v_pk_mul_f32 v[20:21], v[20:21], v[162:163] op_sel_hi:[1,0]
	v_pk_mul_f32 v[28:29], v[28:29], v[162:163] op_sel_hi:[1,0]
	v_lshlrev_b64 v[40:41], 10, v[40:41]
	v_pk_mul_f32 v[16:17], v[16:17], v[162:163] op_sel_hi:[1,0]
	v_pk_mul_f32 v[22:23], v[22:23], v[162:163] op_sel_hi:[1,0]
	v_pk_mul_f32 v[30:31], v[30:31], v[162:163] op_sel_hi:[1,0]
	v_cvt_pk_bf16_f32 v28, v28, v29
	v_pk_mul_f32 v[26:27], v[26:27], v[162:163] op_sel_hi:[1,0]
	v_pk_mul_f32 v[24:25], v[24:25], v[162:163] op_sel_hi:[1,0]
	v_cvt_pk_bf16_f32 v20, v20, v21
	v_lshl_add_u64 v[40:41], s[38:39], 0, v[40:41]
	v_pk_mul_f32 v[18:19], v[18:19], v[162:163] op_sel_hi:[1,0]
	v_cvt_pk_bf16_f32 v29, v30, v31
	v_cvt_pk_bf16_f32 v24, v24, v25
	v_cvt_pk_bf16_f32 v25, v26, v27
	v_cvt_pk_bf16_f32 v21, v22, v23
	v_cvt_pk_bf16_f32 v22, v16, v17
	v_cndmask_b32_e64 v16, v28, v20, s[2:3]
	v_mov_b32_e32 v26, 0
	v_cndmask_b32_e64 v33, v43, v45, s[2:3]
	v_cndmask_b32_e64 v32, v42, v44, s[2:3]
	v_lshl_add_u64 v[40:41], v[40:41], 0, v[112:113]
	v_cvt_pk_bf16_f32 v23, v18, v19
	v_mov_b32_dpp v26, v16 row_ror:8 row_mask:0xf bank_mask:0xf
	v_cndmask_b32_e64 v16, v29, v21, s[2:3]
	v_mov_b32_e32 v27, 0
	v_cndmask_b32_e64 v17, v24, v22, s[2:3]
	v_mov_b32_e32 v30, 0
	global_store_dwordx4 v[40:41], v[32:35], off
	v_mov_b32_dpp v27, v16 row_ror:8 row_mask:0xf bank_mask:0xf
	v_cndmask_b32_e64 v16, v25, v23, s[2:3]
	v_add_u32_e32 v34, 0x98, v146
	v_mov_b32_dpp v30, v17 row_ror:8 row_mask:0xf bank_mask:0xf
	v_mov_b32_e32 v31, 0
	v_cndmask_b32_e64 v18, v30, v24, s[2:3]
	v_cndmask_b32_e64 v24, v34, v148, s[2:3]
	v_mov_b32_dpp v31, v16 row_ror:8 row_mask:0xf bank_mask:0xf
	v_cndmask_b32_e64 v19, v31, v25, s[2:3]
	v_ashrrev_i32_e32 v25, 31, v24
	v_lshlrev_b64 v[24:25], 10, v[24:25]
	v_lshl_add_u64 v[24:25], s[38:39], 0, v[24:25]
	v_cndmask_b32_e64 v17, v27, v29, s[2:3]
	v_cndmask_b32_e64 v16, v26, v28, s[2:3]
	v_lshl_add_u64 v[24:25], v[24:25], 0, v[112:113]
	global_store_dwordx4 v[24:25], v[16:19], off
	v_pk_mul_f32 v[4:5], v[4:5], v[160:161] op_sel_hi:[1,0]
	v_pk_mul_f32 v[12:13], v[12:13], v[160:161] op_sel_hi:[1,0]
	v_add_u32_e32 v18, 0xa8, v146
	v_cndmask_b32_e64 v16, v148, v18, s[2:3]
	v_ashrrev_i32_e32 v17, 31, v16
	v_pk_mul_f32 v[10:11], v[10:11], v[160:161] op_sel_hi:[1,0]
	v_pk_mul_f32 v[8:9], v[8:9], v[160:161] op_sel_hi:[1,0]
	v_lshlrev_b64 v[16:17], 10, v[16:17]
	v_pk_mul_f32 v[0:1], v[0:1], v[160:161] op_sel_hi:[1,0]
	v_pk_mul_f32 v[6:7], v[6:7], v[160:161] op_sel_hi:[1,0]
	v_pk_mul_f32 v[14:15], v[14:15], v[160:161] op_sel_hi:[1,0]
	v_cvt_pk_bf16_f32 v12, v12, v13
	v_cvt_pk_bf16_f32 v8, v8, v9
	v_cvt_pk_bf16_f32 v9, v10, v11
	v_cvt_pk_bf16_f32 v10, v4, v5
	v_lshl_add_u64 v[16:17], s[38:39], 0, v[16:17]
	v_pk_mul_f32 v[2:3], v[2:3], v[160:161] op_sel_hi:[1,0]
	v_cvt_pk_bf16_f32 v13, v14, v15
	v_cvt_pk_bf16_f32 v6, v6, v7
	v_cvt_pk_bf16_f32 v7, v0, v1
	v_cndmask_b32_e64 v0, v12, v10, s[2:3]
	v_mov_b32_e32 v14, 0
	v_cndmask_b32_e64 v4, v18, v150, s[2:3]
	v_cndmask_b32_e64 v23, v23, v31, s[2:3]
	v_cndmask_b32_e64 v22, v22, v30, s[2:3]
	v_cndmask_b32_e64 v21, v21, v27, s[2:3]
	v_cndmask_b32_e64 v20, v20, v26, s[2:3]
	v_lshl_add_u64 v[16:17], v[16:17], 0, v[112:113]
	v_cvt_pk_bf16_f32 v11, v2, v3
	v_mov_b32_dpp v14, v0 row_ror:8 row_mask:0xf bank_mask:0xf
	v_cndmask_b32_e64 v0, v13, v6, s[2:3]
	v_mov_b32_e32 v15, 0
	v_ashrrev_i32_e32 v5, 31, v4
	global_store_dwordx4 v[16:17], v[20:23], off
	v_mov_b32_dpp v15, v0 row_ror:8 row_mask:0xf bank_mask:0xf
	v_cndmask_b32_e64 v0, v9, v11, s[2:3]
	v_cndmask_b32_e64 v1, v8, v7, s[2:3]
	v_mov_b32_e32 v16, 0
	v_mov_b32_e32 v17, 0
	v_lshlrev_b64 v[4:5], 10, v[4:5]
	v_mov_b32_dpp v16, v1 row_ror:8 row_mask:0xf bank_mask:0xf
	v_mov_b32_dpp v17, v0 row_ror:8 row_mask:0xf bank_mask:0xf
	v_lshl_add_u64 v[4:5], s[38:39], 0, v[4:5]
	v_cndmask_b32_e64 v3, v17, v9, s[2:3]
	v_cndmask_b32_e64 v2, v16, v8, s[2:3]
	v_cndmask_b32_e64 v1, v15, v13, s[2:3]
	v_cndmask_b32_e64 v0, v14, v12, s[2:3]
	v_lshl_add_u64 v[4:5], v[4:5], 0, v[112:113]
	global_store_dwordx4 v[4:5], v[0:3], off
	v_cndmask_b32_e64 v48, v154, v50, s[2:3]
	v_cndmask_b32_e64 v32, v152, v34, s[2:3]
	v_add_u32_e32 v0, 0xb8, v146
	v_cndmask_b32_e64 v0, v150, v0, s[2:3]
	v_ashrrev_i32_e32 v49, 31, v48
	v_ashrrev_i32_e32 v33, 31, v32
	v_ashrrev_i32_e32 v1, 31, v0
	v_lshlrev_b64 v[48:49], 10, v[48:49]
	v_lshlrev_b64 v[32:33], 10, v[32:33]
	v_lshlrev_b64 v[0:1], 10, v[0:1]
	v_lshl_add_u64 v[48:49], s[38:39], 0, v[48:49]
	v_lshl_add_u64 v[32:33], s[38:39], 0, v[32:33]
	v_lshl_add_u64 v[0:1], s[38:39], 0, v[0:1]
	v_cndmask_b32_e64 v55, v55, v63, s[2:3]
	v_cndmask_b32_e64 v54, v54, v62, s[2:3]
	v_cndmask_b32_e64 v53, v53, v59, s[2:3]
	v_cndmask_b32_e64 v52, v52, v58, s[2:3]
	v_lshl_add_u64 v[48:49], v[48:49], 0, v[112:113]
	v_cndmask_b32_e64 v39, v39, v47, s[2:3]
	v_cndmask_b32_e64 v38, v38, v46, s[2:3]
	v_cndmask_b32_e64 v37, v37, v43, s[2:3]
	v_cndmask_b32_e64 v36, v36, v42, s[2:3]
	v_lshl_add_u64 v[32:33], v[32:33], 0, v[112:113]
	v_lshl_add_u64 v[4:5], v[0:1], 0, v[112:113]
	v_cndmask_b32_e64 v3, v11, v17, s[2:3]
	v_cndmask_b32_e64 v2, v7, v16, s[2:3]
	v_cndmask_b32_e64 v1, v6, v15, s[2:3]
	v_cndmask_b32_e64 v0, v10, v14, s[2:3]
	s_and_b64 vcc, exec, s[4:5]
	s_mov_b32 s66, s36
	s_mov_b32 s6, s44
	s_mov_b64 s[50:51], s[48:49]
	s_mov_b64 s[52:53], s[46:47]
	global_store_dwordx4 v[48:49], v[52:55], off
	global_store_dwordx4 v[32:33], v[36:39], off
	global_store_dwordx4 v[4:5], v[0:3], off
	s_cbranch_vccz .LBB0_897
	s_waitcnt vmcnt(0)
	s_cmpk_gt_u32 s11, 0xff
	s_cbranch_scc1 .LBB0_908
	s_barrier

.LBB0_996:
	s_ashr_i32 s41, s40, 31
	v_cmp_lt_i64_e32 vcc, s[44:45], v[148:149]
	s_lshl_b64 s[44:45], s[40:41], 18
	s_add_u32 s44, s74, s44
	s_addc_u32 s45, s75, s45
	s_and_b64 s[46:47], vcc, exec
	s_cselect_b32 s9, s45, s49
	s_cselect_b32 s41, s44, s48
	s_ashr_i32 s39, s38, 31
	s_lshl_b64 s[46:47], s[38:39], 18
	s_add_u32 s46, s72, s46
	s_addc_u32 s47, s73, s47
	s_and_b64 s[52:53], vcc, exec
	s_cselect_b32 s39, s47, s51
	s_cselect_b32 s76, s46, s50
	s_add_u32 s48, s48, 0x20080
	s_addc_u32 s49, s49, 0
	s_add_u32 s77, s50, 0x100
	s_addc_u32 s78, s51, 0
	s_mov_b32 s79, -2
	s_waitcnt lgkmcnt(0)
.LBB0_997:
	ds_read_b128 v[128:131], v164
	ds_read_b128 v[132:135], v164 offset:1024
	ds_read_b128 v[152:155], v164 offset:2048
	ds_read_b128 v[156:159], v164 offset:3072
	s_add_u32 s28, s48, 0xfffe0080
	s_addc_u32 s29, s49, -1
	s_cmp_eq_u32 s79, 4
	s_cselect_b32 s53, s9, s29
	s_cselect_b32 s52, s41, s28
	s_cselect_b32 s51, s39, s78
	s_cselect_b32 s50, s76, s77
	v_lshl_add_u64 v[204:205], s[48:49], 0, v[144:145]
	s_add_i32 m0, s55, 0xc000
	ds_read_b128 v[168:171], v165
	ds_read_b128 v[172:175], v165 offset:1024
	ds_read_b128 v[176:179], v165 offset:2048
	ds_read_b128 v[180:183], v165 offset:3072
	ds_read_b128 v[184:187], v165 offset:4096
	ds_read_b128 v[188:191], v165 offset:5120
	ds_read_b128 v[196:199], v165 offset:6144
	ds_read_b128 v[200:203], v165 offset:7168
	global_load_lds_dwordx4 v[204:205], off
	v_lshl_add_u64 v[204:205], s[48:49], 0, v[146:147]
	s_add_i32 m0, s55, 0xe000
	s_nop 0
	global_load_lds_dwordx4 v[204:205], off
	s_waitcnt lgkmcnt(8)
	s_barrier
	s_waitcnt lgkmcnt(0)
	s_setprio 1
	s_waitcnt lgkmcnt(0)
	s_cmp_eq_u32 s79, -2
	s_cbranch_scc1 .Lz9_0_first
	v_mfma_f32_16x16x32_bf16 v[124:127], v[128:131], v[168:171], v[124:127]
	v_mfma_f32_16x16x32_bf16 v[120:123], v[152:155], v[168:171], v[120:123]
	v_mfma_f32_16x16x32_bf16 v[108:111], v[128:131], v[176:179], v[108:111]
	v_mfma_f32_16x16x32_bf16 v[104:107], v[152:155], v[176:179], v[104:107]
	v_mfma_f32_16x16x32_bf16 v[92:95], v[128:131], v[184:187], v[92:95]
	v_mfma_f32_16x16x32_bf16 v[88:91], v[152:155], v[184:187], v[88:91]
	v_mfma_f32_16x16x32_bf16 v[76:79], v[128:131], v[196:199], v[76:79]
	v_mfma_f32_16x16x32_bf16 v[72:75], v[152:155], v[196:199], v[72:75]
	v_mfma_f32_16x16x32_bf16 v[124:127], v[132:135], v[172:175], v[124:127]
	v_mfma_f32_16x16x32_bf16 v[120:123], v[156:159], v[172:175], v[120:123]
	v_mfma_f32_16x16x32_bf16 v[108:111], v[132:135], v[180:183], v[108:111]
	v_mfma_f32_16x16x32_bf16 v[104:107], v[156:159], v[180:183], v[104:107]
	v_mfma_f32_16x16x32_bf16 v[92:95], v[132:135], v[188:191], v[92:95]
	v_mfma_f32_16x16x32_bf16 v[88:91], v[156:159], v[188:191], v[88:91]
	v_mfma_f32_16x16x32_bf16 v[76:79], v[132:135], v[200:203], v[76:79]
	v_mfma_f32_16x16x32_bf16 v[72:75], v[156:159], v[200:203], v[72:75]
.Lz9_0_join:
	s_setprio 0
	s_barrier
	s_add_i32 s28, s65, s54
	v_lshl_add_u64 v[220:221], s[50:51], 0, v[138:139]
	s_mov_b32 m0, s28
	ds_read_b128 v[204:207], v166
	ds_read_b128 v[208:211], v166 offset:1024
	ds_read_b128 v[212:215], v166 offset:2048
	ds_read_b128 v[216:219], v166 offset:3072
	global_load_lds_dwordx4 v[220:221], off
	v_lshl_add_u64 v[222:223], s[50:51], 0, v[142:143]
	s_add_i32 m0, s28, 0x2000
	s_nop 0
	global_load_lds_dwordx4 v[222:223], off
	s_barrier
	s_waitcnt lgkmcnt(0)
	s_setprio 1
	s_waitcnt lgkmcnt(0)
	s_cmp_eq_u32 s79, -2
	s_cbranch_scc1 .Lz9_1_first
	v_mfma_f32_16x16x32_bf16 v[116:119], v[204:207], v[168:171], v[116:119]
	v_mfma_f32_16x16x32_bf16 v[112:115], v[212:215], v[168:171], v[112:115]
	v_mfma_f32_16x16x32_bf16 v[100:103], v[204:207], v[176:179], v[100:103]
	v_mfma_f32_16x16x32_bf16 v[96:99], v[212:215], v[176:179], v[96:99]
	v_mfma_f32_16x16x32_bf16 v[84:87], v[204:207], v[184:187], v[84:87]
	v_mfma_f32_16x16x32_bf16 v[80:83], v[212:215], v[184:187], v[80:83]
	v_mfma_f32_16x16x32_bf16 v[68:71], v[204:207], v[196:199], v[68:71]
	v_mfma_f32_16x16x32_bf16 v[64:67], v[212:215], v[196:199], v[64:67]
	v_mfma_f32_16x16x32_bf16 v[116:119], v[208:211], v[172:175], v[116:119]
	v_mfma_f32_16x16x32_bf16 v[112:115], v[216:219], v[172:175], v[112:115]
	v_mfma_f32_16x16x32_bf16 v[100:103], v[208:211], v[180:183], v[100:103]
	v_mfma_f32_16x16x32_bf16 v[96:99], v[216:219], v[180:183], v[96:99]
	v_mfma_f32_16x16x32_bf16 v[84:87], v[208:211], v[188:191], v[84:87]
	v_mfma_f32_16x16x32_bf16 v[80:83], v[216:219], v[188:191], v[80:83]
	v_mfma_f32_16x16x32_bf16 v[68:71], v[208:211], v[200:203], v[68:71]
	v_mfma_f32_16x16x32_bf16 v[64:67], v[216:219], v[200:203], v[64:67]
.Lz9_1_join:
	s_setprio 0
	s_mov_b32 m0, s55
	v_lshl_add_u64 v[224:225], s[52:53], 0, v[136:137]
	s_barrier
	ds_read_b128 v[168:171], v165 offset:16384
	ds_read_b128 v[172:175], v165 offset:17408
	ds_read_b128 v[176:179], v165 offset:18432
	ds_read_b128 v[180:183], v165 offset:19456
	ds_read_b128 v[184:187], v165 offset:20480
	ds_read_b128 v[188:191], v165 offset:21504
	ds_read_b128 v[196:199], v165 offset:22528
	ds_read_b128 v[200:203], v165 offset:23552
	global_load_lds_dwordx4 v[224:225], off
	v_lshl_add_u64 v[226:227], s[52:53], 0, v[140:141]
	s_mov_b32 m0, s56
	s_nop 0
	global_load_lds_dwordx4 v[226:227], off
	s_barrier
	s_waitcnt lgkmcnt(0)
	s_setprio 1
	s_waitcnt lgkmcnt(0)
	s_cmp_eq_u32 s79, -2
	s_cbranch_scc1 .Lz9_2_first
	v_mfma_f32_16x16x32_bf16 v[60:63], v[128:131], v[168:171], v[60:63]
	v_mfma_f32_16x16x32_bf16 v[56:59], v[152:155], v[168:171], v[56:59]
	v_mfma_f32_16x16x32_bf16 v[44:47], v[128:131], v[176:179], v[44:47]
	v_mfma_f32_16x16x32_bf16 v[40:43], v[152:155], v[176:179], v[40:43]
	v_mfma_f32_16x16x32_bf16 v[28:31], v[128:131], v[184:187], v[28:31]
	v_mfma_f32_16x16x32_bf16 v[24:27], v[152:155], v[184:187], v[24:27]
	v_mfma_f32_16x16x32_bf16 v[12:15], v[128:131], v[196:199], v[12:15]
	v_mfma_f32_16x16x32_bf16 v[8:11], v[152:155], v[196:199], v[8:11]
	v_mfma_f32_16x16x32_bf16 v[60:63], v[132:135], v[172:175], v[60:63]
	v_mfma_f32_16x16x32_bf16 v[56:59], v[156:159], v[172:175], v[56:59]
	v_mfma_f32_16x16x32_bf16 v[44:47], v[132:135], v[180:183], v[44:47]
	v_mfma_f32_16x16x32_bf16 v[40:43], v[156:159], v[180:183], v[40:43]
	v_mfma_f32_16x16x32_bf16 v[28:31], v[132:135], v[188:191], v[28:31]
	v_mfma_f32_16x16x32_bf16 v[24:27], v[156:159], v[188:191], v[24:27]
	v_mfma_f32_16x16x32_bf16 v[12:15], v[132:135], v[200:203], v[12:15]
	v_mfma_f32_16x16x32_bf16 v[8:11], v[156:159], v[200:203], v[8:11]
.Lz9_2_join:
	s_setprio 0
	s_barrier
	s_add_u32 s80, s50, 0x8000
	s_addc_u32 s81, s51, 0
	s_add_i32 s28, s66, s54
	v_lshl_add_u64 v[128:129], s[80:81], 0, v[138:139]
	s_mov_b32 m0, s28
	s_nop 0
	global_load_lds_dwordx4 v[128:129], off
	v_lshl_add_u64 v[128:129], s[80:81], 0, v[142:143]
	s_add_i32 m0, s28, 0x2000
	s_nop 0
	global_load_lds_dwordx4 v[128:129], off
	s_waitcnt vmcnt(6)
	s_barrier
	s_setprio 1
	s_cmp_eq_u32 s79, -2
	s_cbranch_scc1 .Lz9_3_first
	v_mfma_f32_16x16x32_bf16 v[52:55], v[204:207], v[168:171], v[52:55]
	v_mfma_f32_16x16x32_bf16 v[48:51], v[212:215], v[168:171], v[48:51]
	v_mfma_f32_16x16x32_bf16 v[36:39], v[204:207], v[176:179], v[36:39]
	v_mfma_f32_16x16x32_bf16 v[32:35], v[212:215], v[176:179], v[32:35]
	v_mfma_f32_16x16x32_bf16 v[20:23], v[204:207], v[184:187], v[20:23]
	v_mfma_f32_16x16x32_bf16 v[16:19], v[212:215], v[184:187], v[16:19]
	v_mfma_f32_16x16x32_bf16 v[4:7], v[204:207], v[196:199], v[4:7]
	v_mfma_f32_16x16x32_bf16 v[0:3], v[212:215], v[196:199], v[0:3]
	v_mfma_f32_16x16x32_bf16 v[52:55], v[208:211], v[172:175], v[52:55]
	v_mfma_f32_16x16x32_bf16 v[48:51], v[216:219], v[172:175], v[48:51]
	v_mfma_f32_16x16x32_bf16 v[36:39], v[208:211], v[180:183], v[36:39]
	v_mfma_f32_16x16x32_bf16 v[32:35], v[216:219], v[180:183], v[32:35]
	v_mfma_f32_16x16x32_bf16 v[20:23], v[208:211], v[188:191], v[20:23]
	v_mfma_f32_16x16x32_bf16 v[16:19], v[216:219], v[188:191], v[16:19]
	v_mfma_f32_16x16x32_bf16 v[4:7], v[208:211], v[200:203], v[4:7]
	v_mfma_f32_16x16x32_bf16 v[0:3], v[216:219], v[200:203], v[0:3]
.Lz9_3_join:
	s_setprio 0
	s_add_i32 s28, 0, 0x18000
	v_add_u32_e32 v156, s28, v161
	s_barrier
	ds_read_b128 v[128:131], v156
	ds_read_b128 v[132:135], v156 offset:1024
	ds_read_b128 v[152:155], v156 offset:2048
	ds_read_b128 v[156:159], v156 offset:3072
	s_add_u32 s52, s52, 0x20000
	s_addc_u32 s53, s53, 0
	s_mov_b32 m0, s57
	v_lshl_add_u64 v[204:205], s[52:53], 0, v[136:137]
	ds_read_b128 v[168:171], v165 offset:32768
	ds_read_b128 v[172:175], v165 offset:33792
	ds_read_b128 v[176:179], v165 offset:34816
	ds_read_b128 v[180:183], v165 offset:35840
	ds_read_b128 v[184:187], v165 offset:36864
	ds_read_b128 v[188:191], v165 offset:37888
	ds_read_b128 v[196:199], v165 offset:38912
	ds_read_b128 v[200:203], v165 offset:39936
	global_load_lds_dwordx4 v[204:205], off
	v_lshl_add_u64 v[204:205], s[52:53], 0, v[140:141]
	s_mov_b32 m0, s58
	s_nop 0
	global_load_lds_dwordx4 v[204:205], off
	s_waitcnt lgkmcnt(8)
	s_barrier
	s_waitcnt lgkmcnt(0)
	s_setprio 1
	s_waitcnt lgkmcnt(0)
	v_mfma_f32_16x16x32_bf16 v[124:127], v[128:131], v[168:171], v[124:127]
	v_mfma_f32_16x16x32_bf16 v[120:123], v[152:155], v[168:171], v[120:123]
	v_mfma_f32_16x16x32_bf16 v[108:111], v[128:131], v[176:179], v[108:111]
	v_mfma_f32_16x16x32_bf16 v[104:107], v[152:155], v[176:179], v[104:107]
	v_mfma_f32_16x16x32_bf16 v[92:95], v[128:131], v[184:187], v[92:95]
	v_mfma_f32_16x16x32_bf16 v[88:91], v[152:155], v[184:187], v[88:91]
	v_mfma_f32_16x16x32_bf16 v[76:79], v[128:131], v[196:199], v[76:79]
	v_mfma_f32_16x16x32_bf16 v[72:75], v[152:155], v[196:199], v[72:75]
	v_mfma_f32_16x16x32_bf16 v[124:127], v[132:135], v[172:175], v[124:127]
	v_mfma_f32_16x16x32_bf16 v[120:123], v[156:159], v[172:175], v[120:123]
	v_mfma_f32_16x16x32_bf16 v[108:111], v[132:135], v[180:183], v[108:111]
	v_mfma_f32_16x16x32_bf16 v[104:107], v[156:159], v[180:183], v[104:107]
	v_mfma_f32_16x16x32_bf16 v[92:95], v[132:135], v[188:191], v[92:95]
	v_mfma_f32_16x16x32_bf16 v[88:91], v[156:159], v[188:191], v[88:91]
	v_mfma_f32_16x16x32_bf16 v[76:79], v[132:135], v[200:203], v[76:79]
	v_mfma_f32_16x16x32_bf16 v[72:75], v[156:159], v[200:203], v[72:75]
	s_setprio 0
	s_barrier
	s_add_i32 s29, 0, 0x1c000
	s_add_i32 s28, s28, s54
	v_add_u32_e32 v195, s29, v161
	v_lshl_add_u64 v[220:221], v[220:221], 0, s[36:37]
	s_mov_b32 m0, s28
	ds_read_b128 v[204:207], v195
	ds_read_b128 v[208:211], v195 offset:1024
	ds_read_b128 v[212:215], v195 offset:2048
	ds_read_b128 v[216:219], v195 offset:3072
	global_load_lds_dwordx4 v[220:221], off
	v_lshl_add_u64 v[220:221], v[222:223], 0, s[36:37]
	s_add_i32 m0, s28, 0x2000
	s_nop 0
	global_load_lds_dwordx4 v[220:221], off
	s_barrier
	s_waitcnt lgkmcnt(0)
	s_setprio 1
	s_waitcnt lgkmcnt(0)
	v_mfma_f32_16x16x32_bf16 v[116:119], v[204:207], v[168:171], v[116:119]
	v_mfma_f32_16x16x32_bf16 v[112:115], v[212:215], v[168:171], v[112:115]
	v_mfma_f32_16x16x32_bf16 v[100:103], v[204:207], v[176:179], v[100:103]
	v_mfma_f32_16x16x32_bf16 v[96:99], v[212:215], v[176:179], v[96:99]
	v_mfma_f32_16x16x32_bf16 v[84:87], v[204:207], v[184:187], v[84:87]
	v_mfma_f32_16x16x32_bf16 v[80:83], v[212:215], v[184:187], v[80:83]
	v_mfma_f32_16x16x32_bf16 v[68:71], v[204:207], v[196:199], v[68:71]
	v_mfma_f32_16x16x32_bf16 v[64:67], v[212:215], v[196:199], v[64:67]
	v_mfma_f32_16x16x32_bf16 v[116:119], v[208:211], v[172:175], v[116:119]
	v_mfma_f32_16x16x32_bf16 v[112:115], v[216:219], v[172:175], v[112:115]
	v_mfma_f32_16x16x32_bf16 v[100:103], v[208:211], v[180:183], v[100:103]
	v_mfma_f32_16x16x32_bf16 v[96:99], v[216:219], v[180:183], v[96:99]
	v_mfma_f32_16x16x32_bf16 v[84:87], v[208:211], v[188:191], v[84:87]
	v_mfma_f32_16x16x32_bf16 v[80:83], v[216:219], v[188:191], v[80:83]
	v_mfma_f32_16x16x32_bf16 v[68:71], v[208:211], v[200:203], v[68:71]
	v_mfma_f32_16x16x32_bf16 v[64:67], v[216:219], v[200:203], v[64:67]
	s_setprio 0
	s_mov_b32 m0, s62
	v_lshl_add_u64 v[220:221], v[224:225], 0, s[36:37]
	s_barrier
	ds_read_b128 v[168:171], v165 offset:49152
	ds_read_b128 v[172:175], v165 offset:50176
	ds_read_b128 v[176:179], v165 offset:51200
	ds_read_b128 v[180:183], v165 offset:52224
	ds_read_b128 v[184:187], v165 offset:53248
	ds_read_b128 v[188:191], v165 offset:54272
	ds_read_b128 v[196:199], v165 offset:55296
	ds_read_b128 v[200:203], v165 offset:56320
	global_load_lds_dwordx4 v[220:221], off
	v_lshl_add_u64 v[220:221], v[226:227], 0, s[36:37]
	s_mov_b32 m0, s63
	s_nop 0
	global_load_lds_dwordx4 v[220:221], off
	s_barrier
	s_waitcnt lgkmcnt(0)
	s_setprio 1
	s_waitcnt lgkmcnt(0)
	v_mfma_f32_16x16x32_bf16 v[60:63], v[128:131], v[168:171], v[60:63]
	v_mfma_f32_16x16x32_bf16 v[56:59], v[152:155], v[168:171], v[56:59]
	v_mfma_f32_16x16x32_bf16 v[44:47], v[128:131], v[176:179], v[44:47]
	v_mfma_f32_16x16x32_bf16 v[40:43], v[152:155], v[176:179], v[40:43]
	v_mfma_f32_16x16x32_bf16 v[28:31], v[128:131], v[184:187], v[28:31]
	v_mfma_f32_16x16x32_bf16 v[24:27], v[152:155], v[184:187], v[24:27]
	v_mfma_f32_16x16x32_bf16 v[12:15], v[128:131], v[196:199], v[12:15]
	v_mfma_f32_16x16x32_bf16 v[8:11], v[152:155], v[196:199], v[8:11]
	v_mfma_f32_16x16x32_bf16 v[60:63], v[132:135], v[172:175], v[60:63]
	v_mfma_f32_16x16x32_bf16 v[56:59], v[156:159], v[172:175], v[56:59]
	v_mfma_f32_16x16x32_bf16 v[44:47], v[132:135], v[180:183], v[44:47]
	v_mfma_f32_16x16x32_bf16 v[40:43], v[156:159], v[180:183], v[40:43]
	v_mfma_f32_16x16x32_bf16 v[28:31], v[132:135], v[188:191], v[28:31]
	v_mfma_f32_16x16x32_bf16 v[24:27], v[156:159], v[188:191], v[24:27]
	v_mfma_f32_16x16x32_bf16 v[12:15], v[132:135], v[200:203], v[12:15]
	v_mfma_f32_16x16x32_bf16 v[8:11], v[156:159], v[200:203], v[8:11]
	s_setprio 0
	s_barrier
	s_add_u32 s50, s50, 0x8080
	s_addc_u32 s51, s51, 0
	s_add_i32 s28, s29, s54
	v_lshl_add_u64 v[128:129], s[50:51], 0, v[138:139]
	s_mov_b32 m0, s28
	s_nop 0
	global_load_lds_dwordx4 v[128:129], off
	v_lshl_add_u64 v[128:129], s[50:51], 0, v[142:143]
	s_add_i32 m0, s28, 0x2000
	s_nop 0
	global_load_lds_dwordx4 v[128:129], off
	s_waitcnt vmcnt(6)
	s_barrier
	s_setprio 1
	v_mfma_f32_16x16x32_bf16 v[52:55], v[204:207], v[168:171], v[52:55]
	v_mfma_f32_16x16x32_bf16 v[48:51], v[212:215], v[168:171], v[48:51]
	v_mfma_f32_16x16x32_bf16 v[36:39], v[204:207], v[176:179], v[36:39]
	v_mfma_f32_16x16x32_bf16 v[32:35], v[212:215], v[176:179], v[32:35]
	v_mfma_f32_16x16x32_bf16 v[20:23], v[204:207], v[184:187], v[20:23]
	v_mfma_f32_16x16x32_bf16 v[16:19], v[212:215], v[184:187], v[16:19]
	v_mfma_f32_16x16x32_bf16 v[4:7], v[204:207], v[196:199], v[4:7]
	v_mfma_f32_16x16x32_bf16 v[0:3], v[212:215], v[196:199], v[0:3]
	v_mfma_f32_16x16x32_bf16 v[52:55], v[208:211], v[172:175], v[52:55]
	v_mfma_f32_16x16x32_bf16 v[48:51], v[216:219], v[172:175], v[48:51]
	v_mfma_f32_16x16x32_bf16 v[36:39], v[208:211], v[180:183], v[36:39]
	v_mfma_f32_16x16x32_bf16 v[32:35], v[216:219], v[180:183], v[32:35]
	v_mfma_f32_16x16x32_bf16 v[20:23], v[208:211], v[188:191], v[20:23]
	v_mfma_f32_16x16x32_bf16 v[16:19], v[216:219], v[188:191], v[16:19]
	v_mfma_f32_16x16x32_bf16 v[4:7], v[208:211], v[200:203], v[4:7]
	v_mfma_f32_16x16x32_bf16 v[0:3], v[216:219], v[200:203], v[0:3]
	s_setprio 0
	s_add_i32 s79, s79, 2
	s_add_u32 s48, s48, 0x100
	s_addc_u32 s49, s49, 0
	s_add_u32 s77, s77, 0x100
	s_addc_u32 s78, s78, 0
	s_cmp_gt_u32 s79, 5
	s_barrier
	s_cbranch_scc0 .LBB0_997
	s_branch .Lz9_skip
.Lz9_0_first:
	v_mfma_f32_16x16x32_bf16 v[124:127], v[128:131], v[168:171], 0
	v_mfma_f32_16x16x32_bf16 v[120:123], v[152:155], v[168:171], 0
	v_mfma_f32_16x16x32_bf16 v[108:111], v[128:131], v[176:179], 0
	v_mfma_f32_16x16x32_bf16 v[104:107], v[152:155], v[176:179], 0
	v_mfma_f32_16x16x32_bf16 v[92:95], v[128:131], v[184:187], 0
	v_mfma_f32_16x16x32_bf16 v[88:91], v[152:155], v[184:187], 0
	v_mfma_f32_16x16x32_bf16 v[76:79], v[128:131], v[196:199], 0
	v_mfma_f32_16x16x32_bf16 v[72:75], v[152:155], v[196:199], 0
	v_mfma_f32_16x16x32_bf16 v[124:127], v[132:135], v[172:175], v[124:127]
	v_mfma_f32_16x16x32_bf16 v[120:123], v[156:159], v[172:175], v[120:123]
	v_mfma_f32_16x16x32_bf16 v[108:111], v[132:135], v[180:183], v[108:111]
	v_mfma_f32_16x16x32_bf16 v[104:107], v[156:159], v[180:183], v[104:107]
	v_mfma_f32_16x16x32_bf16 v[92:95], v[132:135], v[188:191], v[92:95]
	v_mfma_f32_16x16x32_bf16 v[88:91], v[156:159], v[188:191], v[88:91]
	v_mfma_f32_16x16x32_bf16 v[76:79], v[132:135], v[200:203], v[76:79]
	v_mfma_f32_16x16x32_bf16 v[72:75], v[156:159], v[200:203], v[72:75]
	s_branch .Lz9_0_join
.Lz9_1_first:
	v_mfma_f32_16x16x32_bf16 v[116:119], v[204:207], v[168:171], 0
	v_mfma_f32_16x16x32_bf16 v[112:115], v[212:215], v[168:171], 0
	v_mfma_f32_16x16x32_bf16 v[100:103], v[204:207], v[176:179], 0
	v_mfma_f32_16x16x32_bf16 v[96:99], v[212:215], v[176:179], 0
	v_mfma_f32_16x16x32_bf16 v[84:87], v[204:207], v[184:187], 0
	v_mfma_f32_16x16x32_bf16 v[80:83], v[212:215], v[184:187], 0
	v_mfma_f32_16x16x32_bf16 v[68:71], v[204:207], v[196:199], 0
	v_mfma_f32_16x16x32_bf16 v[64:67], v[212:215], v[196:199], 0
	v_mfma_f32_16x16x32_bf16 v[116:119], v[208:211], v[172:175], v[116:119]
	v_mfma_f32_16x16x32_bf16 v[112:115], v[216:219], v[172:175], v[112:115]
	v_mfma_f32_16x16x32_bf16 v[100:103], v[208:211], v[180:183], v[100:103]
	v_mfma_f32_16x16x32_bf16 v[96:99], v[216:219], v[180:183], v[96:99]
	v_mfma_f32_16x16x32_bf16 v[84:87], v[208:211], v[188:191], v[84:87]
	v_mfma_f32_16x16x32_bf16 v[80:83], v[216:219], v[188:191], v[80:83]
	v_mfma_f32_16x16x32_bf16 v[68:71], v[208:211], v[200:203], v[68:71]
	v_mfma_f32_16x16x32_bf16 v[64:67], v[216:219], v[200:203], v[64:67]
	s_branch .Lz9_1_join
.Lz9_2_first:
	v_mfma_f32_16x16x32_bf16 v[60:63], v[128:131], v[168:171], 0
	v_mfma_f32_16x16x32_bf16 v[56:59], v[152:155], v[168:171], 0
	v_mfma_f32_16x16x32_bf16 v[44:47], v[128:131], v[176:179], 0
	v_mfma_f32_16x16x32_bf16 v[40:43], v[152:155], v[176:179], 0
	v_mfma_f32_16x16x32_bf16 v[28:31], v[128:131], v[184:187], 0
	v_mfma_f32_16x16x32_bf16 v[24:27], v[152:155], v[184:187], 0
	v_mfma_f32_16x16x32_bf16 v[12:15], v[128:131], v[196:199], 0
	v_mfma_f32_16x16x32_bf16 v[8:11], v[152:155], v[196:199], 0
	v_mfma_f32_16x16x32_bf16 v[60:63], v[132:135], v[172:175], v[60:63]
	v_mfma_f32_16x16x32_bf16 v[56:59], v[156:159], v[172:175], v[56:59]
	v_mfma_f32_16x16x32_bf16 v[44:47], v[132:135], v[180:183], v[44:47]
	v_mfma_f32_16x16x32_bf16 v[40:43], v[156:159], v[180:183], v[40:43]
	v_mfma_f32_16x16x32_bf16 v[28:31], v[132:135], v[188:191], v[28:31]
	v_mfma_f32_16x16x32_bf16 v[24:27], v[156:159], v[188:191], v[24:27]
	v_mfma_f32_16x16x32_bf16 v[12:15], v[132:135], v[200:203], v[12:15]
	v_mfma_f32_16x16x32_bf16 v[8:11], v[156:159], v[200:203], v[8:11]
	s_branch .Lz9_2_join
.Lz9_3_first:
	v_mfma_f32_16x16x32_bf16 v[52:55], v[204:207], v[168:171], 0
	v_mfma_f32_16x16x32_bf16 v[48:51], v[212:215], v[168:171], 0
	v_mfma_f32_16x16x32_bf16 v[36:39], v[204:207], v[176:179], 0
	v_mfma_f32_16x16x32_bf16 v[32:35], v[212:215], v[176:179], 0
	v_mfma_f32_16x16x32_bf16 v[20:23], v[204:207], v[184:187], 0
	v_mfma_f32_16x16x32_bf16 v[16:19], v[212:215], v[184:187], 0
	v_mfma_f32_16x16x32_bf16 v[4:7], v[204:207], v[196:199], 0
	v_mfma_f32_16x16x32_bf16 v[0:3], v[212:215], v[196:199], 0
	v_mfma_f32_16x16x32_bf16 v[52:55], v[208:211], v[172:175], v[52:55]
	v_mfma_f32_16x16x32_bf16 v[48:51], v[216:219], v[172:175], v[48:51]
	v_mfma_f32_16x16x32_bf16 v[36:39], v[208:211], v[180:183], v[36:39]
	v_mfma_f32_16x16x32_bf16 v[32:35], v[216:219], v[180:183], v[32:35]
	v_mfma_f32_16x16x32_bf16 v[20:23], v[208:211], v[188:191], v[20:23]
	v_mfma_f32_16x16x32_bf16 v[16:19], v[216:219], v[188:191], v[16:19]
	v_mfma_f32_16x16x32_bf16 v[4:7], v[208:211], v[200:203], v[4:7]
	v_mfma_f32_16x16x32_bf16 v[0:3], v[216:219], v[200:203], v[0:3]
	s_branch .Lz9_3_join
.Lz9_skip:
	v_lshl_add_u32 v152, s8, 8, v160
	v_lshl_or_b32 v156, s10, 8, v162
	v_ashrrev_i32_e32 v153, 31, v152
	v_lshlrev_b64 v[128:129], 11, v[152:153]
	v_ashrrev_i32_e32 v157, 31, v156
	v_lshl_add_u64 v[128:129], s[42:43], 0, v[128:129]
	v_lshlrev_b64 v[130:131], 1, v[156:157]
	v_or_b32_e32 v158, 16, v152
	v_lshl_add_u64 v[128:129], v[128:129], 0, v[130:131]
	v_ashrrev_i32_e32 v159, 31, v158
	global_load_dwordx4 v[168:171], v[128:129], off
	global_load_dwordx4 v[172:175], v[128:129], off offset:64
	v_lshlrev_b64 v[128:129], 11, v[158:159]
	v_lshl_add_u64 v[128:129], s[42:43], 0, v[128:129]
	v_lshl_add_u64 v[128:129], v[128:129], 0, v[130:131]
	global_load_dwordx4 v[132:135], v[128:129], off
	s_nop 0
	global_load_dwordx4 v[128:131], v[128:129], off offset:64
	v_cndmask_b32_e64 v155, 0, 1, s[12:13]
	v_or_b32_e32 v154, v156, v163
	v_cmp_ne_u32_e64 s[8:9], 1, v155
	v_ashrrev_i32_e32 v155, 31, v154
	s_andn2_b64 vcc, exec, s[12:13]
	v_lshlrev_b64 v[154:155], 1, v[154:155]
	s_waitcnt vmcnt(0)
	v_lshlrev_b32_e32 v176, 16, v168
	v_and_b32_e32 v177, 0xffff0000, v168
	v_lshlrev_b32_e32 v168, 16, v169
	v_and_b32_e32 v169, 0xffff0000, v169
	v_lshlrev_b32_e32 v178, 16, v170
	v_and_b32_e32 v179, 0xffff0000, v170
	v_lshlrev_b32_e32 v170, 16, v171
	v_and_b32_e32 v171, 0xffff0000, v171
	v_lshlrev_b32_e32 v180, 16, v172
	v_and_b32_e32 v181, 0xffff0000, v172
	v_lshlrev_b32_e32 v172, 16, v173
	v_and_b32_e32 v173, 0xffff0000, v173
	v_lshlrev_b32_e32 v182, 16, v174
	v_and_b32_e32 v183, 0xffff0000, v174
	v_lshlrev_b32_e32 v174, 16, v175
	v_and_b32_e32 v175, 0xffff0000, v175
	v_pk_add_f32 v[126:127], v[126:127], v[168:169]
	v_pk_add_f32 v[124:125], v[124:125], v[176:177]
	v_pk_add_f32 v[122:123], v[122:123], v[170:171]
	v_pk_add_f32 v[120:121], v[120:121], v[178:179]
	v_pk_add_f32 v[118:119], v[118:119], v[172:173]
	v_pk_add_f32 v[116:117], v[116:117], v[180:181]
	v_pk_add_f32 v[114:115], v[114:115], v[174:175]
	v_pk_add_f32 v[112:113], v[112:113], v[182:183]
	v_add_u32_e32 v169, 8, v152
	s_cbranch_vccnz .LBB0_1000
	v_cvt_pk_bf16_f32 v168, v124, v125
	v_cvt_pk_bf16_f32 v174, v116, v117
	v_cvt_pk_bf16_f32 v170, v126, v127
	v_cvt_pk_bf16_f32 v171, v120, v121
	v_cvt_pk_bf16_f32 v175, v118, v119
	v_cvt_pk_bf16_f32 v176, v112, v113
	v_cndmask_b32_e64 v173, v168, v174, s[4:5]
	v_mov_b32_e32 v178, 0
	v_cvt_pk_bf16_f32 v172, v122, v123
	v_cvt_pk_bf16_f32 v177, v114, v115
	v_mov_b32_dpp v178, v173 row_ror:8 row_mask:0xf bank_mask:0xf
	v_cndmask_b32_e64 v173, v170, v175, s[4:5]
	v_mov_b32_e32 v179, 0
	v_cndmask_b32_e64 v180, v171, v176, s[4:5]
	v_mov_b32_e32 v181, 0
	v_mov_b32_dpp v179, v173 row_ror:8 row_mask:0xf bank_mask:0xf
	v_cndmask_b32_e64 v173, v172, v177, s[4:5]
	v_mov_b32_dpp v181, v180 row_ror:8 row_mask:0xf bank_mask:0xf
	v_mov_b32_e32 v180, 0
	v_cndmask_b32_e64 v174, v174, v178, s[4:5]
	v_cndmask_b32_e64 v175, v175, v179, s[4:5]
	v_mov_b32_dpp v180, v173 row_ror:8 row_mask:0xf bank_mask:0xf
	v_cndmask_b32_e64 v173, v180, v172, s[4:5]
	v_cndmask_b32_e64 v172, v181, v171, s[4:5]
	v_cndmask_b32_e64 v171, v179, v170, s[4:5]
	v_cndmask_b32_e64 v170, v178, v168, s[4:5]
	v_add_u32_e32 v168, -8, v152
	v_cndmask_b32_e64 v178, v168, v152, s[4:5]
	v_ashrrev_i32_e32 v179, 31, v178
	v_lshlrev_b64 v[178:179], 11, v[178:179]
	v_lshl_add_u64 v[178:179], s[68:69], 0, v[178:179]
	v_lshl_add_u64 v[178:179], v[178:179], 0, v[154:155]
	global_store_dwordx4 v[178:179], v[170:173], off
	v_cndmask_b32_e64 v177, v177, v180, s[4:5]
	v_cndmask_b32_e64 v176, v176, v181, s[4:5]
	v_cndmask_b32_e64 v170, v152, v169, s[4:5]
	v_ashrrev_i32_e32 v171, 31, v170
	v_lshlrev_b64 v[170:171], 11, v[170:171]
	v_lshl_add_u64 v[170:171], s[68:69], 0, v[170:171]
	v_lshl_add_u64 v[170:171], v[170:171], 0, v[154:155]
	global_store_dwordx4 v[170:171], v[174:177], off

.LBB0_1168:
	s_add_u32 s63, s42, 0x100
	s_addc_u32 s64, s43, 0
	s_mov_b32 s65, -2
	s_waitcnt lgkmcnt(0)
.LBB0_1169:
	ds_read_b128 v[128:131], v167
	ds_read_b128 v[132:135], v167 offset:1024
	ds_read_b128 v[136:139], v167 offset:2048
	ds_read_b128 v[156:159], v167 offset:3072
	s_add_u32 s6, s40, 0x100
	s_addc_u32 s7, s41, 0
	s_cmp_eq_u32 s65, 40
	s_cselect_b32 s45, s1, s7
	s_cselect_b32 s44, s0, s6
	s_cselect_b32 s43, s39, s64
	s_cselect_b32 s42, s38, s63
	v_lshl_add_u64 v[202:203], s[40:41], 0, v[148:149]
	s_add_i32 m0, s47, 0xc000
	ds_read_b128 v[160:163], v168
	ds_read_b128 v[172:175], v168 offset:1024
	ds_read_b128 v[176:179], v168 offset:2048
	ds_read_b128 v[180:183], v168 offset:3072
	ds_read_b128 v[184:187], v168 offset:4096
	ds_read_b128 v[188:191], v168 offset:5120
	ds_read_b128 v[194:197], v168 offset:6144
	ds_read_b128 v[198:201], v168 offset:7168
	global_load_lds_dwordx4 v[202:203], off
	v_lshl_add_u64 v[202:203], s[40:41], 0, v[150:151]
	s_add_i32 m0, s47, 0xe000
	s_nop 0
	global_load_lds_dwordx4 v[202:203], off
	s_waitcnt lgkmcnt(8)
	s_barrier
	s_waitcnt lgkmcnt(0)
	s_setprio 1
	s_waitcnt lgkmcnt(0)
	s_cmp_eq_u32 s65, -2
	s_cbranch_scc1 .Lz11_0_first
	v_mfma_f32_16x16x32_bf16 v[124:127], v[128:131], v[160:163], v[124:127]
	v_mfma_f32_16x16x32_bf16 v[120:123], v[136:139], v[160:163], v[120:123]
	v_mfma_f32_16x16x32_bf16 v[108:111], v[128:131], v[176:179], v[108:111]
	v_mfma_f32_16x16x32_bf16 v[104:107], v[136:139], v[176:179], v[104:107]
	v_mfma_f32_16x16x32_bf16 v[92:95], v[128:131], v[184:187], v[92:95]
	v_mfma_f32_16x16x32_bf16 v[88:91], v[136:139], v[184:187], v[88:91]
	v_mfma_f32_16x16x32_bf16 v[76:79], v[128:131], v[194:197], v[76:79]
	v_mfma_f32_16x16x32_bf16 v[72:75], v[136:139], v[194:197], v[72:75]
	v_mfma_f32_16x16x32_bf16 v[124:127], v[132:135], v[172:175], v[124:127]
	v_mfma_f32_16x16x32_bf16 v[120:123], v[156:159], v[172:175], v[120:123]
	v_mfma_f32_16x16x32_bf16 v[108:111], v[132:135], v[180:183], v[108:111]
	v_mfma_f32_16x16x32_bf16 v[104:107], v[156:159], v[180:183], v[104:107]
	v_mfma_f32_16x16x32_bf16 v[92:95], v[132:135], v[188:191], v[92:95]
	v_mfma_f32_16x16x32_bf16 v[88:91], v[156:159], v[188:191], v[88:91]
	v_mfma_f32_16x16x32_bf16 v[76:79], v[132:135], v[198:201], v[76:79]
	v_mfma_f32_16x16x32_bf16 v[72:75], v[156:159], v[198:201], v[72:75]
.Lz11_0_join:
	s_setprio 0
	s_barrier
	s_add_i32 s28, s57, s46
	v_lshl_add_u64 v[218:219], s[42:43], 0, v[142:143]
	s_mov_b32 m0, s28
	ds_read_b128 v[202:205], v169
	ds_read_b128 v[206:209], v169 offset:1024
	ds_read_b128 v[210:213], v169 offset:2048
	ds_read_b128 v[214:217], v169 offset:3072
	global_load_lds_dwordx4 v[218:219], off
	v_lshl_add_u64 v[220:221], s[42:43], 0, v[146:147]
	s_add_i32 m0, s28, 0x2000
	s_nop 0
	global_load_lds_dwordx4 v[220:221], off
	s_barrier
	s_waitcnt lgkmcnt(0)
	s_setprio 1
	s_waitcnt lgkmcnt(0)
	s_cmp_eq_u32 s65, -2
	s_cbranch_scc1 .Lz11_1_first
	v_mfma_f32_16x16x32_bf16 v[116:119], v[202:205], v[160:163], v[116:119]
	v_mfma_f32_16x16x32_bf16 v[112:115], v[210:213], v[160:163], v[112:115]
	v_mfma_f32_16x16x32_bf16 v[100:103], v[202:205], v[176:179], v[100:103]
	v_mfma_f32_16x16x32_bf16 v[96:99], v[210:213], v[176:179], v[96:99]
	v_mfma_f32_16x16x32_bf16 v[84:87], v[202:205], v[184:187], v[84:87]
	v_mfma_f32_16x16x32_bf16 v[80:83], v[210:213], v[184:187], v[80:83]
	v_mfma_f32_16x16x32_bf16 v[68:71], v[202:205], v[194:197], v[68:71]
	v_mfma_f32_16x16x32_bf16 v[64:67], v[210:213], v[194:197], v[64:67]
	v_mfma_f32_16x16x32_bf16 v[116:119], v[206:209], v[172:175], v[116:119]
	v_mfma_f32_16x16x32_bf16 v[112:115], v[214:217], v[172:175], v[112:115]
	v_mfma_f32_16x16x32_bf16 v[100:103], v[206:209], v[180:183], v[100:103]
	v_mfma_f32_16x16x32_bf16 v[96:99], v[214:217], v[180:183], v[96:99]
	v_mfma_f32_16x16x32_bf16 v[84:87], v[206:209], v[188:191], v[84:87]
	v_mfma_f32_16x16x32_bf16 v[80:83], v[214:217], v[188:191], v[80:83]
	v_mfma_f32_16x16x32_bf16 v[68:71], v[206:209], v[198:201], v[68:71]
	v_mfma_f32_16x16x32_bf16 v[64:67], v[214:217], v[198:201], v[64:67]
.Lz11_1_join:
	s_setprio 0
	s_mov_b32 m0, s47
	v_lshl_add_u64 v[222:223], s[44:45], 0, v[140:141]
	s_barrier
	ds_read_b128 v[160:163], v168 offset:16384
	ds_read_b128 v[172:175], v168 offset:17408
	ds_read_b128 v[176:179], v168 offset:18432
	ds_read_b128 v[180:183], v168 offset:19456
	ds_read_b128 v[184:187], v168 offset:20480
	ds_read_b128 v[188:191], v168 offset:21504
	ds_read_b128 v[194:197], v168 offset:22528
	ds_read_b128 v[198:201], v168 offset:23552
	global_load_lds_dwordx4 v[222:223], off
	v_lshl_add_u64 v[224:225], s[44:45], 0, v[144:145]
	s_mov_b32 m0, s48
	s_nop 0
	global_load_lds_dwordx4 v[224:225], off
	s_barrier
	s_waitcnt lgkmcnt(0)
	s_setprio 1
	s_waitcnt lgkmcnt(0)
	s_cmp_eq_u32 s65, -2
	s_cbranch_scc1 .Lz11_2_first
	v_mfma_f32_16x16x32_bf16 v[60:63], v[128:131], v[160:163], v[60:63]
	v_mfma_f32_16x16x32_bf16 v[56:59], v[136:139], v[160:163], v[56:59]
	v_mfma_f32_16x16x32_bf16 v[44:47], v[128:131], v[176:179], v[44:47]
	v_mfma_f32_16x16x32_bf16 v[40:43], v[136:139], v[176:179], v[40:43]
	v_mfma_f32_16x16x32_bf16 v[28:31], v[128:131], v[184:187], v[28:31]
	v_mfma_f32_16x16x32_bf16 v[24:27], v[136:139], v[184:187], v[24:27]
	v_mfma_f32_16x16x32_bf16 v[12:15], v[128:131], v[194:197], v[12:15]
	v_mfma_f32_16x16x32_bf16 v[8:11], v[136:139], v[194:197], v[8:11]
	v_mfma_f32_16x16x32_bf16 v[60:63], v[132:135], v[172:175], v[60:63]
	v_mfma_f32_16x16x32_bf16 v[56:59], v[156:159], v[172:175], v[56:59]
	v_mfma_f32_16x16x32_bf16 v[44:47], v[132:135], v[180:183], v[44:47]
	v_mfma_f32_16x16x32_bf16 v[40:43], v[156:159], v[180:183], v[40:43]
	v_mfma_f32_16x16x32_bf16 v[28:31], v[132:135], v[188:191], v[28:31]
	v_mfma_f32_16x16x32_bf16 v[24:27], v[156:159], v[188:191], v[24:27]
	v_mfma_f32_16x16x32_bf16 v[12:15], v[132:135], v[198:201], v[12:15]
	v_mfma_f32_16x16x32_bf16 v[8:11], v[156:159], v[198:201], v[8:11]
.Lz11_2_join:
	s_setprio 0
	s_barrier
	s_add_u32 s40, s42, 0x2c000
	s_addc_u32 s41, s43, 0
	s_add_i32 s28, s58, s46
	v_lshl_add_u64 v[128:129], s[40:41], 0, v[142:143]
	s_mov_b32 m0, s28
	s_nop 0
	global_load_lds_dwordx4 v[128:129], off
	v_lshl_add_u64 v[128:129], s[40:41], 0, v[146:147]
	s_add_i32 m0, s28, 0x2000
	s_nop 0
	global_load_lds_dwordx4 v[128:129], off
	s_waitcnt vmcnt(6)
	s_barrier
	s_setprio 1
	s_cmp_eq_u32 s65, -2
	s_cbranch_scc1 .Lz11_3_first
	v_mfma_f32_16x16x32_bf16 v[52:55], v[202:205], v[160:163], v[52:55]
	v_mfma_f32_16x16x32_bf16 v[48:51], v[210:213], v[160:163], v[48:51]
	v_mfma_f32_16x16x32_bf16 v[36:39], v[202:205], v[176:179], v[36:39]
	v_mfma_f32_16x16x32_bf16 v[32:35], v[210:213], v[176:179], v[32:35]
	v_mfma_f32_16x16x32_bf16 v[20:23], v[202:205], v[184:187], v[20:23]
	v_mfma_f32_16x16x32_bf16 v[16:19], v[210:213], v[184:187], v[16:19]
	v_mfma_f32_16x16x32_bf16 v[4:7], v[202:205], v[194:197], v[4:7]
	v_mfma_f32_16x16x32_bf16 v[0:3], v[210:213], v[194:197], v[0:3]
	v_mfma_f32_16x16x32_bf16 v[52:55], v[206:209], v[172:175], v[52:55]
	v_mfma_f32_16x16x32_bf16 v[48:51], v[214:217], v[172:175], v[48:51]
	v_mfma_f32_16x16x32_bf16 v[36:39], v[206:209], v[180:183], v[36:39]
	v_mfma_f32_16x16x32_bf16 v[32:35], v[214:217], v[180:183], v[32:35]
	v_mfma_f32_16x16x32_bf16 v[20:23], v[206:209], v[188:191], v[20:23]
	v_mfma_f32_16x16x32_bf16 v[16:19], v[214:217], v[188:191], v[16:19]
	v_mfma_f32_16x16x32_bf16 v[4:7], v[206:209], v[198:201], v[4:7]
	v_mfma_f32_16x16x32_bf16 v[0:3], v[214:217], v[198:201], v[0:3]
.Lz11_3_join:
	s_setprio 0
	s_add_i32 s28, 0, 0x18000
	v_add_u32_e32 v156, s28, v165
	s_barrier
	ds_read_b128 v[128:131], v156
	ds_read_b128 v[132:135], v156 offset:1024
	ds_read_b128 v[136:139], v156 offset:2048
	ds_read_b128 v[156:159], v156 offset:3072
	s_add_u32 s40, s44, 0xb0000
	s_addc_u32 s41, s45, 0
	s_mov_b32 m0, s49
	v_lshl_add_u64 v[202:203], s[40:41], 0, v[140:141]
	ds_read_b128 v[160:163], v168 offset:32768
	ds_read_b128 v[172:175], v168 offset:33792
	ds_read_b128 v[176:179], v168 offset:34816
	ds_read_b128 v[180:183], v168 offset:35840
	ds_read_b128 v[184:187], v168 offset:36864
	ds_read_b128 v[188:191], v168 offset:37888
	ds_read_b128 v[194:197], v168 offset:38912
	ds_read_b128 v[198:201], v168 offset:39936
	global_load_lds_dwordx4 v[202:203], off
	v_lshl_add_u64 v[202:203], s[40:41], 0, v[144:145]
	s_mov_b32 m0, s50
	s_nop 0
	global_load_lds_dwordx4 v[202:203], off
	s_waitcnt lgkmcnt(8)
	s_barrier
	s_waitcnt lgkmcnt(0)
	s_setprio 1
	s_waitcnt lgkmcnt(0)
	v_mfma_f32_16x16x32_bf16 v[124:127], v[128:131], v[160:163], v[124:127]
	v_mfma_f32_16x16x32_bf16 v[120:123], v[136:139], v[160:163], v[120:123]
	v_mfma_f32_16x16x32_bf16 v[108:111], v[128:131], v[176:179], v[108:111]
	v_mfma_f32_16x16x32_bf16 v[104:107], v[136:139], v[176:179], v[104:107]
	v_mfma_f32_16x16x32_bf16 v[92:95], v[128:131], v[184:187], v[92:95]
	v_mfma_f32_16x16x32_bf16 v[88:91], v[136:139], v[184:187], v[88:91]
	v_mfma_f32_16x16x32_bf16 v[76:79], v[128:131], v[194:197], v[76:79]
	v_mfma_f32_16x16x32_bf16 v[72:75], v[136:139], v[194:197], v[72:75]
	v_mfma_f32_16x16x32_bf16 v[124:127], v[132:135], v[172:175], v[124:127]
	v_mfma_f32_16x16x32_bf16 v[120:123], v[156:159], v[172:175], v[120:123]
	v_mfma_f32_16x16x32_bf16 v[108:111], v[132:135], v[180:183], v[108:111]
	v_mfma_f32_16x16x32_bf16 v[104:107], v[156:159], v[180:183], v[104:107]
	v_mfma_f32_16x16x32_bf16 v[92:95], v[132:135], v[188:191], v[92:95]
	v_mfma_f32_16x16x32_bf16 v[88:91], v[156:159], v[188:191], v[88:91]
	v_mfma_f32_16x16x32_bf16 v[76:79], v[132:135], v[198:201], v[76:79]
	v_mfma_f32_16x16x32_bf16 v[72:75], v[156:159], v[198:201], v[72:75]
	s_setprio 0
	s_barrier
	s_add_i32 s29, 0, 0x1c000
	s_add_i32 s28, s28, s46
	v_add_u32_e32 v171, s29, v165
	v_lshl_add_u64 v[218:219], v[218:219], 0, s[36:37]
	s_mov_b32 m0, s28
	ds_read_b128 v[202:205], v171
	ds_read_b128 v[206:209], v171 offset:1024
	ds_read_b128 v[210:213], v171 offset:2048
	ds_read_b128 v[214:217], v171 offset:3072
	global_load_lds_dwordx4 v[218:219], off
	v_lshl_add_u64 v[218:219], v[220:221], 0, s[36:37]
	s_add_i32 m0, s28, 0x2000
	s_nop 0
	global_load_lds_dwordx4 v[218:219], off
	s_barrier
	s_waitcnt lgkmcnt(0)
	s_setprio 1
	s_waitcnt lgkmcnt(0)
	v_mfma_f32_16x16x32_bf16 v[116:119], v[202:205], v[160:163], v[116:119]
	v_mfma_f32_16x16x32_bf16 v[112:115], v[210:213], v[160:163], v[112:115]
	v_mfma_f32_16x16x32_bf16 v[100:103], v[202:205], v[176:179], v[100:103]
	v_mfma_f32_16x16x32_bf16 v[96:99], v[210:213], v[176:179], v[96:99]
	v_mfma_f32_16x16x32_bf16 v[84:87], v[202:205], v[184:187], v[84:87]
	v_mfma_f32_16x16x32_bf16 v[80:83], v[210:213], v[184:187], v[80:83]
	v_mfma_f32_16x16x32_bf16 v[68:71], v[202:205], v[194:197], v[68:71]
	v_mfma_f32_16x16x32_bf16 v[64:67], v[210:213], v[194:197], v[64:67]
	v_mfma_f32_16x16x32_bf16 v[116:119], v[206:209], v[172:175], v[116:119]
	v_mfma_f32_16x16x32_bf16 v[112:115], v[214:217], v[172:175], v[112:115]
	v_mfma_f32_16x16x32_bf16 v[100:103], v[206:209], v[180:183], v[100:103]
	v_mfma_f32_16x16x32_bf16 v[96:99], v[214:217], v[180:183], v[96:99]
	v_mfma_f32_16x16x32_bf16 v[84:87], v[206:209], v[188:191], v[84:87]
	v_mfma_f32_16x16x32_bf16 v[80:83], v[214:217], v[188:191], v[80:83]
	v_mfma_f32_16x16x32_bf16 v[68:71], v[206:209], v[198:201], v[68:71]
	v_mfma_f32_16x16x32_bf16 v[64:67], v[214:217], v[198:201], v[64:67]
	s_setprio 0
	s_mov_b32 m0, s54
	v_lshl_add_u64 v[218:219], v[222:223], 0, s[36:37]
	s_barrier
	ds_read_b128 v[160:163], v168 offset:49152
	ds_read_b128 v[172:175], v168 offset:50176
	ds_read_b128 v[176:179], v168 offset:51200
	ds_read_b128 v[180:183], v168 offset:52224
	ds_read_b128 v[184:187], v168 offset:53248
	ds_read_b128 v[188:191], v168 offset:54272
	ds_read_b128 v[194:197], v168 offset:55296
	ds_read_b128 v[198:201], v168 offset:56320
	global_load_lds_dwordx4 v[218:219], off
	v_lshl_add_u64 v[218:219], v[224:225], 0, s[36:37]
	s_mov_b32 m0, s55
	s_nop 0
	global_load_lds_dwordx4 v[218:219], off
	s_barrier
	s_waitcnt lgkmcnt(0)
	s_setprio 1
	s_waitcnt lgkmcnt(0)
	v_mfma_f32_16x16x32_bf16 v[60:63], v[128:131], v[160:163], v[60:63]
	v_mfma_f32_16x16x32_bf16 v[56:59], v[136:139], v[160:163], v[56:59]
	v_mfma_f32_16x16x32_bf16 v[44:47], v[128:131], v[176:179], v[44:47]
	v_mfma_f32_16x16x32_bf16 v[40:43], v[136:139], v[176:179], v[40:43]
	v_mfma_f32_16x16x32_bf16 v[28:31], v[128:131], v[184:187], v[28:31]
	v_mfma_f32_16x16x32_bf16 v[24:27], v[136:139], v[184:187], v[24:27]
	v_mfma_f32_16x16x32_bf16 v[12:15], v[128:131], v[194:197], v[12:15]
	v_mfma_f32_16x16x32_bf16 v[8:11], v[136:139], v[194:197], v[8:11]
	v_mfma_f32_16x16x32_bf16 v[60:63], v[132:135], v[172:175], v[60:63]
	v_mfma_f32_16x16x32_bf16 v[56:59], v[156:159], v[172:175], v[56:59]
	v_mfma_f32_16x16x32_bf16 v[44:47], v[132:135], v[180:183], v[44:47]
	v_mfma_f32_16x16x32_bf16 v[40:43], v[156:159], v[180:183], v[40:43]
	v_mfma_f32_16x16x32_bf16 v[28:31], v[132:135], v[188:191], v[28:31]
	v_mfma_f32_16x16x32_bf16 v[24:27], v[156:159], v[188:191], v[24:27]
	v_mfma_f32_16x16x32_bf16 v[12:15], v[132:135], v[198:201], v[12:15]
	v_mfma_f32_16x16x32_bf16 v[8:11], v[156:159], v[198:201], v[8:11]
	s_setprio 0
	s_barrier
	s_add_u32 s40, s42, 0x2c080
	s_addc_u32 s41, s43, 0
	s_add_i32 s28, s29, s46
	v_lshl_add_u64 v[128:129], s[40:41], 0, v[142:143]
	s_mov_b32 m0, s28
	s_nop 0
	global_load_lds_dwordx4 v[128:129], off
	v_lshl_add_u64 v[128:129], s[40:41], 0, v[146:147]
	s_add_i32 m0, s28, 0x2000
	s_nop 0
	global_load_lds_dwordx4 v[128:129], off
	s_waitcnt vmcnt(6)
	s_barrier
	s_setprio 1
	v_mfma_f32_16x16x32_bf16 v[52:55], v[202:205], v[160:163], v[52:55]
	v_mfma_f32_16x16x32_bf16 v[48:51], v[210:213], v[160:163], v[48:51]
	v_mfma_f32_16x16x32_bf16 v[36:39], v[202:205], v[176:179], v[36:39]
	v_mfma_f32_16x16x32_bf16 v[32:35], v[210:213], v[176:179], v[32:35]
	v_mfma_f32_16x16x32_bf16 v[20:23], v[202:205], v[184:187], v[20:23]
	v_mfma_f32_16x16x32_bf16 v[16:19], v[210:213], v[184:187], v[16:19]
	v_mfma_f32_16x16x32_bf16 v[4:7], v[202:205], v[194:197], v[4:7]
	v_mfma_f32_16x16x32_bf16 v[0:3], v[210:213], v[194:197], v[0:3]
	v_mfma_f32_16x16x32_bf16 v[52:55], v[206:209], v[172:175], v[52:55]
	v_mfma_f32_16x16x32_bf16 v[48:51], v[214:217], v[172:175], v[48:51]
	v_mfma_f32_16x16x32_bf16 v[36:39], v[206:209], v[180:183], v[36:39]
	v_mfma_f32_16x16x32_bf16 v[32:35], v[214:217], v[180:183], v[32:35]
	v_mfma_f32_16x16x32_bf16 v[20:23], v[206:209], v[188:191], v[20:23]
	v_mfma_f32_16x16x32_bf16 v[16:19], v[214:217], v[188:191], v[16:19]
	v_mfma_f32_16x16x32_bf16 v[4:7], v[206:209], v[198:201], v[4:7]
	v_mfma_f32_16x16x32_bf16 v[0:3], v[214:217], v[198:201], v[0:3]
	s_setprio 0
	s_add_i32 s65, s65, 2
	s_add_u32 s63, s63, 0x100
	s_addc_u32 s64, s64, 0
	s_cmp_gt_u32 s65, 41
	s_mov_b64 s[40:41], s[6:7]
	s_barrier
	s_cbranch_scc0 .LBB0_1169
	s_branch .Lz11_skip
.Lz11_0_first:
	v_mfma_f32_16x16x32_bf16 v[124:127], v[128:131], v[160:163], 0
	v_mfma_f32_16x16x32_bf16 v[120:123], v[136:139], v[160:163], 0
	v_mfma_f32_16x16x32_bf16 v[108:111], v[128:131], v[176:179], 0
	v_mfma_f32_16x16x32_bf16 v[104:107], v[136:139], v[176:179], 0
	v_mfma_f32_16x16x32_bf16 v[92:95], v[128:131], v[184:187], 0
	v_mfma_f32_16x16x32_bf16 v[88:91], v[136:139], v[184:187], 0
	v_mfma_f32_16x16x32_bf16 v[76:79], v[128:131], v[194:197], 0
	v_mfma_f32_16x16x32_bf16 v[72:75], v[136:139], v[194:197], 0
	v_mfma_f32_16x16x32_bf16 v[124:127], v[132:135], v[172:175], v[124:127]
	v_mfma_f32_16x16x32_bf16 v[120:123], v[156:159], v[172:175], v[120:123]
	v_mfma_f32_16x16x32_bf16 v[108:111], v[132:135], v[180:183], v[108:111]
	v_mfma_f32_16x16x32_bf16 v[104:107], v[156:159], v[180:183], v[104:107]
	v_mfma_f32_16x16x32_bf16 v[92:95], v[132:135], v[188:191], v[92:95]
	v_mfma_f32_16x16x32_bf16 v[88:91], v[156:159], v[188:191], v[88:91]
	v_mfma_f32_16x16x32_bf16 v[76:79], v[132:135], v[198:201], v[76:79]
	v_mfma_f32_16x16x32_bf16 v[72:75], v[156:159], v[198:201], v[72:75]
	s_branch .Lz11_0_join
.Lz11_1_first:
	v_mfma_f32_16x16x32_bf16 v[116:119], v[202:205], v[160:163], 0
	v_mfma_f32_16x16x32_bf16 v[112:115], v[210:213], v[160:163], 0
	v_mfma_f32_16x16x32_bf16 v[100:103], v[202:205], v[176:179], 0
	v_mfma_f32_16x16x32_bf16 v[96:99], v[210:213], v[176:179], 0
	v_mfma_f32_16x16x32_bf16 v[84:87], v[202:205], v[184:187], 0
	v_mfma_f32_16x16x32_bf16 v[80:83], v[210:213], v[184:187], 0
	v_mfma_f32_16x16x32_bf16 v[68:71], v[202:205], v[194:197], 0
	v_mfma_f32_16x16x32_bf16 v[64:67], v[210:213], v[194:197], 0
	v_mfma_f32_16x16x32_bf16 v[116:119], v[206:209], v[172:175], v[116:119]
	v_mfma_f32_16x16x32_bf16 v[112:115], v[214:217], v[172:175], v[112:115]
	v_mfma_f32_16x16x32_bf16 v[100:103], v[206:209], v[180:183], v[100:103]
	v_mfma_f32_16x16x32_bf16 v[96:99], v[214:217], v[180:183], v[96:99]
	v_mfma_f32_16x16x32_bf16 v[84:87], v[206:209], v[188:191], v[84:87]
	v_mfma_f32_16x16x32_bf16 v[80:83], v[214:217], v[188:191], v[80:83]
	v_mfma_f32_16x16x32_bf16 v[68:71], v[206:209], v[198:201], v[68:71]
	v_mfma_f32_16x16x32_bf16 v[64:67], v[214:217], v[198:201], v[64:67]
	s_branch .Lz11_1_join
.Lz11_2_first:
	v_mfma_f32_16x16x32_bf16 v[60:63], v[128:131], v[160:163], 0
	v_mfma_f32_16x16x32_bf16 v[56:59], v[136:139], v[160:163], 0
	v_mfma_f32_16x16x32_bf16 v[44:47], v[128:131], v[176:179], 0
	v_mfma_f32_16x16x32_bf16 v[40:43], v[136:139], v[176:179], 0
	v_mfma_f32_16x16x32_bf16 v[28:31], v[128:131], v[184:187], 0
	v_mfma_f32_16x16x32_bf16 v[24:27], v[136:139], v[184:187], 0
	v_mfma_f32_16x16x32_bf16 v[12:15], v[128:131], v[194:197], 0
	v_mfma_f32_16x16x32_bf16 v[8:11], v[136:139], v[194:197], 0
	v_mfma_f32_16x16x32_bf16 v[60:63], v[132:135], v[172:175], v[60:63]
	v_mfma_f32_16x16x32_bf16 v[56:59], v[156:159], v[172:175], v[56:59]
	v_mfma_f32_16x16x32_bf16 v[44:47], v[132:135], v[180:183], v[44:47]
	v_mfma_f32_16x16x32_bf16 v[40:43], v[156:159], v[180:183], v[40:43]
	v_mfma_f32_16x16x32_bf16 v[28:31], v[132:135], v[188:191], v[28:31]
	v_mfma_f32_16x16x32_bf16 v[24:27], v[156:159], v[188:191], v[24:27]
	v_mfma_f32_16x16x32_bf16 v[12:15], v[132:135], v[198:201], v[12:15]
	v_mfma_f32_16x16x32_bf16 v[8:11], v[156:159], v[198:201], v[8:11]
	s_branch .Lz11_2_join
.Lz11_3_first:
	v_mfma_f32_16x16x32_bf16 v[52:55], v[202:205], v[160:163], 0
	v_mfma_f32_16x16x32_bf16 v[48:51], v[210:213], v[160:163], 0
	v_mfma_f32_16x16x32_bf16 v[36:39], v[202:205], v[176:179], 0
	v_mfma_f32_16x16x32_bf16 v[32:35], v[210:213], v[176:179], 0
	v_mfma_f32_16x16x32_bf16 v[20:23], v[202:205], v[184:187], 0
	v_mfma_f32_16x16x32_bf16 v[16:19], v[210:213], v[184:187], 0
	v_mfma_f32_16x16x32_bf16 v[4:7], v[202:205], v[194:197], 0
	v_mfma_f32_16x16x32_bf16 v[0:3], v[210:213], v[194:197], 0
	v_mfma_f32_16x16x32_bf16 v[52:55], v[206:209], v[172:175], v[52:55]
	v_mfma_f32_16x16x32_bf16 v[48:51], v[214:217], v[172:175], v[48:51]
	v_mfma_f32_16x16x32_bf16 v[36:39], v[206:209], v[180:183], v[36:39]
	v_mfma_f32_16x16x32_bf16 v[32:35], v[214:217], v[180:183], v[32:35]
	v_mfma_f32_16x16x32_bf16 v[20:23], v[206:209], v[188:191], v[20:23]
	v_mfma_f32_16x16x32_bf16 v[16:19], v[214:217], v[188:191], v[16:19]
	v_mfma_f32_16x16x32_bf16 v[4:7], v[206:209], v[198:201], v[4:7]
	v_mfma_f32_16x16x32_bf16 v[0:3], v[214:217], v[198:201], v[0:3]
	s_branch .Lz11_3_join
.Lz11_skip:
	v_lshl_add_u32 v171, s62, 8, v164
	v_lshl_or_b32 v188, s10, 8, v166
	s_mov_b32 s63, 0xffff0000
	v_lshlrev_b32_e32 v128, 11, v171
	v_lshl_add_u32 v128, v188, 1, v128
	v_lshlrev_b32_e32 v129, 12, v171
	v_lshl_add_u32 v129, v188, 2, v129
	v_lshlrev_b32_e32 v132, 2, v188
	s_mov_b64 s[70:71], s[68:69]
	global_load_dwordx4 v[194:197], v128, s[70:71]
	global_load_dwordx4 v[198:201], v128, s[70:71] offset:64
	s_add_u32 s70, s70, 0x8000
	s_addc_u32 s71, s71, 0
	global_load_dwordx4 v[202:205], v128, s[70:71]
	global_load_dwordx4 v[206:209], v128, s[70:71] offset:64
	s_add_u32 s70, s70, 0x8000
	s_addc_u32 s71, s71, 0
	global_load_dwordx4 v[210:213], v128, s[70:71]
	global_load_dwordx4 v[214:217], v128, s[70:71] offset:64
	s_add_u32 s70, s70, 0x8000
	s_addc_u32 s71, s71, 0
	global_load_dwordx4 v[218:221], v128, s[70:71]
	global_load_dwordx4 v[222:225], v128, s[70:71] offset:64
	s_add_u32 s70, s70, 0x28000
	s_addc_u32 s71, s71, 0
	global_load_dwordx4 v[226:229], v128, s[70:71]
	global_load_dwordx4 v[230:233], v128, s[70:71] offset:64
	s_add_u32 s70, s70, 0x8000
	s_addc_u32 s71, s71, 0
	global_load_dwordx4 v[234:237], v128, s[70:71]
	global_load_dwordx4 v[238:241], v128, s[70:71] offset:64
	s_add_u32 s70, s70, 0x8000
	s_addc_u32 s71, s71, 0
	global_load_dwordx4 v[172:175], v128, s[70:71]
	global_load_dwordx4 v[176:179], v128, s[70:71] offset:64
	s_add_u32 s70, s70, 0x8000
	s_addc_u32 s71, s71, 0
	global_load_dwordx4 v[180:183], v128, s[70:71]
	global_load_dwordx4 v[184:187], v128, s[70:71] offset:64
	s_bfe_u32 s42, s17, 0x20006
	s_lshl_b32 s43, s10, 4
	s_lshl_b32 s42, s42, 2
	s_add_i32 s43, s43, s42
	v_lshl_add_u32 v130, v171, 6, s43
	v_and_b32_e32 v131, 48, v170
	v_lshl_add_u32 v131, v171, 6, v131
	v_xor_b32_e32 v134, 16, v170
	v_xor_b32_e32 v135, 32, v170
	v_lshlrev_b32_e32 v134, 2, v134
	v_lshlrev_b32_e32 v135, 2, v135
	v_cmp_gt_u32_e64 s[64:65], 16, v170
	s_add_u32 s74, s8, 0x2000
	s_addc_u32 s75, s9, 0
	s_lshl_b32 s42, s62, 7
	s_add_u32 s78, s26, 0x3c08000
	s_addc_u32 s79, s27, 0
	s_add_u32 s78, s78, s42
	s_addc_u32 s79, s79, 0
	s_waitcnt vmcnt(14)
	v_lshlrev_b32_e32 v136, 16, v194
	v_and_b32_e32 v137, s63, v194
	v_pk_add_f32 v[124:125], v[124:125], v[136:137]
	v_lshlrev_b32_e32 v138, 16, v195
	v_and_b32_e32 v139, s63, v195
	v_pk_add_f32 v[126:127], v[126:127], v[138:139]
	v_lshlrev_b32_e32 v190, 16, v196
	v_and_b32_e32 v191, s63, v196
	v_pk_add_f32 v[120:121], v[120:121], v[190:191]
	v_lshlrev_b32_e32 v136, 16, v197
	v_and_b32_e32 v137, s63, v197
	v_pk_add_f32 v[122:123], v[122:123], v[136:137]
	v_lshlrev_b32_e32 v138, 16, v198
	v_and_b32_e32 v139, s63, v198
	v_pk_add_f32 v[116:117], v[116:117], v[138:139]
	v_lshlrev_b32_e32 v190, 16, v199
	v_and_b32_e32 v191, s63, v199
	v_pk_add_f32 v[118:119], v[118:119], v[190:191]
	v_lshlrev_b32_e32 v136, 16, v200
	v_and_b32_e32 v137, s63, v200
	v_pk_add_f32 v[112:113], v[112:113], v[136:137]
	v_lshlrev_b32_e32 v138, 16, v201
	v_and_b32_e32 v139, s63, v201
	v_pk_add_f32 v[114:115], v[114:115], v[138:139]
	v_mul_f32_e32 v156, v120, v120
	v_mul_f32_e32 v189, v112, v112
	v_fmac_f32_e32 v156, v121, v121
	v_fmac_f32_e32 v189, v113, v113
	v_fmac_f32_e32 v156, v122, v122
	v_fmac_f32_e32 v189, v114, v114
	v_fmac_f32_e32 v156, v123, v123
	v_fmac_f32_e32 v189, v115, v115
	v_fmac_f32_e32 v156, v124, v124
	v_fmac_f32_e32 v189, v116, v116
	v_fmac_f32_e32 v156, v125, v125
	v_fmac_f32_e32 v189, v117, v117
	v_fmac_f32_e32 v156, v126, v126
	v_fmac_f32_e32 v189, v118, v118
	v_fmac_f32_e32 v156, v127, v127
	v_fmac_f32_e32 v189, v119, v119
	v_add_f32_e32 v156, v156, v189
	s_waitcnt vmcnt(12)
	v_lshlrev_b32_e32 v190, 16, v202
	v_and_b32_e32 v191, s63, v202
	v_pk_add_f32 v[108:109], v[108:109], v[190:191]
	v_lshlrev_b32_e32 v136, 16, v203
	v_and_b32_e32 v137, s63, v203
	v_pk_add_f32 v[110:111], v[110:111], v[136:137]
	v_lshlrev_b32_e32 v138, 16, v204
	v_and_b32_e32 v139, s63, v204
	v_pk_add_f32 v[104:105], v[104:105], v[138:139]
	v_lshlrev_b32_e32 v190, 16, v205
	v_and_b32_e32 v191, s63, v205
	v_pk_add_f32 v[106:107], v[106:107], v[190:191]
	v_lshlrev_b32_e32 v136, 16, v206
	v_and_b32_e32 v137, s63, v206
	v_pk_add_f32 v[100:101], v[100:101], v[136:137]
	v_lshlrev_b32_e32 v138, 16, v207
	v_and_b32_e32 v139, s63, v207
	v_pk_add_f32 v[102:103], v[102:103], v[138:139]
	v_lshlrev_b32_e32 v190, 16, v208
	v_and_b32_e32 v191, s63, v208
	v_pk_add_f32 v[96:97], v[96:97], v[190:191]
	v_lshlrev_b32_e32 v136, 16, v209
	v_and_b32_e32 v137, s63, v209
	v_pk_add_f32 v[98:99], v[98:99], v[136:137]
	v_mul_f32_e32 v157, v104, v104
	v_mul_f32_e32 v189, v96, v96
	v_fmac_f32_e32 v157, v105, v105
	v_fmac_f32_e32 v189, v97, v97
	v_fmac_f32_e32 v157, v106, v106
	v_fmac_f32_e32 v189, v98, v98
	v_fmac_f32_e32 v157, v107, v107
	v_fmac_f32_e32 v189, v99, v99
	v_fmac_f32_e32 v157, v108, v108
	v_fmac_f32_e32 v189, v100, v100
	v_fmac_f32_e32 v157, v109, v109
	v_fmac_f32_e32 v189, v101, v101
	v_fmac_f32_e32 v157, v110, v110
	v_fmac_f32_e32 v189, v102, v102
	v_fmac_f32_e32 v157, v111, v111
	v_fmac_f32_e32 v189, v103, v103
	v_add_f32_e32 v157, v157, v189
	s_waitcnt vmcnt(10)
	v_lshlrev_b32_e32 v138, 16, v210
	v_and_b32_e32 v139, s63, v210
	v_pk_add_f32 v[92:93], v[92:93], v[138:139]
	v_lshlrev_b32_e32 v190, 16, v211
	v_and_b32_e32 v191, s63, v211
	v_pk_add_f32 v[94:95], v[94:95], v[190:191]
	v_lshlrev_b32_e32 v136, 16, v212
	v_and_b32_e32 v137, s63, v212
	v_pk_add_f32 v[88:89], v[88:89], v[136:137]
	v_lshlrev_b32_e32 v138, 16, v213
	v_and_b32_e32 v139, s63, v213
	v_pk_add_f32 v[90:91], v[90:91], v[138:139]
	v_lshlrev_b32_e32 v190, 16, v214
	v_and_b32_e32 v191, s63, v214
	v_pk_add_f32 v[84:85], v[84:85], v[190:191]
	v_lshlrev_b32_e32 v136, 16, v215
	v_and_b32_e32 v137, s63, v215
	v_pk_add_f32 v[86:87], v[86:87], v[136:137]
	v_lshlrev_b32_e32 v138, 16, v216
	v_and_b32_e32 v139, s63, v216
	v_pk_add_f32 v[80:81], v[80:81], v[138:139]
	v_lshlrev_b32_e32 v190, 16, v217
	v_and_b32_e32 v191, s63, v217
	v_pk_add_f32 v[82:83], v[82:83], v[190:191]
	v_mul_f32_e32 v158, v88, v88
	v_mul_f32_e32 v189, v80, v80
	v_fmac_f32_e32 v158, v89, v89
	v_fmac_f32_e32 v189, v81, v81
	v_fmac_f32_e32 v158, v90, v90
	v_fmac_f32_e32 v189, v82, v82
	v_fmac_f32_e32 v158, v91, v91
	v_fmac_f32_e32 v189, v83, v83
	v_fmac_f32_e32 v158, v92, v92
	v_fmac_f32_e32 v189, v84, v84
	v_fmac_f32_e32 v158, v93, v93
	v_fmac_f32_e32 v189, v85, v85
	v_fmac_f32_e32 v158, v94, v94
	v_fmac_f32_e32 v189, v86, v86
	v_fmac_f32_e32 v158, v95, v95
	v_fmac_f32_e32 v189, v87, v87
	v_add_f32_e32 v158, v158, v189
	s_waitcnt vmcnt(8)
	v_lshlrev_b32_e32 v136, 16, v218
	v_and_b32_e32 v137, s63, v218
	v_pk_add_f32 v[76:77], v[76:77], v[136:137]
	v_lshlrev_b32_e32 v138, 16, v219
	v_and_b32_e32 v139, s63, v219
	v_pk_add_f32 v[78:79], v[78:79], v[138:139]
	v_lshlrev_b32_e32 v190, 16, v220
	v_and_b32_e32 v191, s63, v220
	v_pk_add_f32 v[72:73], v[72:73], v[190:191]
	v_lshlrev_b32_e32 v136, 16, v221
	v_and_b32_e32 v137, s63, v221
	v_pk_add_f32 v[74:75], v[74:75], v[136:137]
	v_lshlrev_b32_e32 v138, 16, v222
	v_and_b32_e32 v139, s63, v222
	v_pk_add_f32 v[68:69], v[68:69], v[138:139]
	v_lshlrev_b32_e32 v190, 16, v223
	v_and_b32_e32 v191, s63, v223
	v_pk_add_f32 v[70:71], v[70:71], v[190:191]
	v_lshlrev_b32_e32 v136, 16, v224
	v_and_b32_e32 v137, s63, v224
	v_pk_add_f32 v[64:65], v[64:65], v[136:137]
	v_lshlrev_b32_e32 v138, 16, v225
	v_and_b32_e32 v139, s63, v225
	v_pk_add_f32 v[66:67], v[66:67], v[138:139]
	v_mul_f32_e32 v159, v72, v72
	v_mul_f32_e32 v189, v64, v64
	v_fmac_f32_e32 v159, v73, v73
	v_fmac_f32_e32 v189, v65, v65
	v_fmac_f32_e32 v159, v74, v74
	v_fmac_f32_e32 v189, v66, v66
	v_fmac_f32_e32 v159, v75, v75
	v_fmac_f32_e32 v189, v67, v67
	v_fmac_f32_e32 v159, v76, v76
	v_fmac_f32_e32 v189, v68, v68
	v_fmac_f32_e32 v159, v77, v77
	v_fmac_f32_e32 v189, v69, v69
	v_fmac_f32_e32 v159, v78, v78
	v_fmac_f32_e32 v189, v70, v70
	v_fmac_f32_e32 v159, v79, v79
	v_fmac_f32_e32 v189, v71, v71
	v_add_f32_e32 v159, v159, v189
	s_waitcnt vmcnt(6)
	v_lshlrev_b32_e32 v190, 16, v226
	v_and_b32_e32 v191, s63, v226
	v_pk_add_f32 v[60:61], v[60:61], v[190:191]
	v_lshlrev_b32_e32 v136, 16, v227
	v_and_b32_e32 v137, s63, v227
	v_pk_add_f32 v[62:63], v[62:63], v[136:137]
	v_lshlrev_b32_e32 v138, 16, v228
	v_and_b32_e32 v139, s63, v228
	v_pk_add_f32 v[56:57], v[56:57], v[138:139]
	v_lshlrev_b32_e32 v190, 16, v229
	v_and_b32_e32 v191, s63, v229
	v_pk_add_f32 v[58:59], v[58:59], v[190:191]
	v_lshlrev_b32_e32 v136, 16, v230
	v_and_b32_e32 v137, s63, v230
	v_pk_add_f32 v[52:53], v[52:53], v[136:137]
	v_lshlrev_b32_e32 v138, 16, v231
	v_and_b32_e32 v139, s63, v231
	v_pk_add_f32 v[54:55], v[54:55], v[138:139]
	v_lshlrev_b32_e32 v190, 16, v232
	v_and_b32_e32 v191, s63, v232
	v_pk_add_f32 v[48:49], v[48:49], v[190:191]
	v_lshlrev_b32_e32 v136, 16, v233
	v_and_b32_e32 v137, s63, v233
	v_pk_add_f32 v[50:51], v[50:51], v[136:137]
	v_mul_f32_e32 v160, v56, v56
	v_mul_f32_e32 v189, v48, v48
	v_fmac_f32_e32 v160, v57, v57
	v_fmac_f32_e32 v189, v49, v49
	v_fmac_f32_e32 v160, v58, v58
	v_fmac_f32_e32 v189, v50, v50
	v_fmac_f32_e32 v160, v59, v59
	v_fmac_f32_e32 v189, v51, v51
	v_fmac_f32_e32 v160, v60, v60
	v_fmac_f32_e32 v189, v52, v52
	v_fmac_f32_e32 v160, v61, v61
	v_fmac_f32_e32 v189, v53, v53
	v_fmac_f32_e32 v160, v62, v62
	v_fmac_f32_e32 v189, v54, v54
	v_fmac_f32_e32 v160, v63, v63
	v_fmac_f32_e32 v189, v55, v55
	v_add_f32_e32 v160, v160, v189
	s_waitcnt vmcnt(4)
	v_lshlrev_b32_e32 v138, 16, v234
	v_and_b32_e32 v139, s63, v234
	v_pk_add_f32 v[44:45], v[44:45], v[138:139]
	v_lshlrev_b32_e32 v190, 16, v235
	v_and_b32_e32 v191, s63, v235
	v_pk_add_f32 v[46:47], v[46:47], v[190:191]
	v_lshlrev_b32_e32 v136, 16, v236
	v_and_b32_e32 v137, s63, v236
	v_pk_add_f32 v[40:41], v[40:41], v[136:137]
	v_lshlrev_b32_e32 v138, 16, v237
	v_and_b32_e32 v139, s63, v237
	v_pk_add_f32 v[42:43], v[42:43], v[138:139]
	v_lshlrev_b32_e32 v190, 16, v238
	v_and_b32_e32 v191, s63, v238
	v_pk_add_f32 v[36:37], v[36:37], v[190:191]
	v_lshlrev_b32_e32 v136, 16, v239
	v_and_b32_e32 v137, s63, v239
	v_pk_add_f32 v[38:39], v[38:39], v[136:137]
	v_lshlrev_b32_e32 v138, 16, v240
	v_and_b32_e32 v139, s63, v240
	v_pk_add_f32 v[32:33], v[32:33], v[138:139]
	v_lshlrev_b32_e32 v190, 16, v241
	v_and_b32_e32 v191, s63, v241
	v_pk_add_f32 v[34:35], v[34:35], v[190:191]
	v_mul_f32_e32 v161, v40, v40
	v_mul_f32_e32 v189, v32, v32
	v_fmac_f32_e32 v161, v41, v41
	v_fmac_f32_e32 v189, v33, v33
	v_fmac_f32_e32 v161, v42, v42
	v_fmac_f32_e32 v189, v34, v34
	v_fmac_f32_e32 v161, v43, v43
	v_fmac_f32_e32 v189, v35, v35
	v_fmac_f32_e32 v161, v44, v44
	v_fmac_f32_e32 v189, v36, v36
	v_fmac_f32_e32 v161, v45, v45
	v_fmac_f32_e32 v189, v37, v37
	v_fmac_f32_e32 v161, v46, v46
	v_fmac_f32_e32 v189, v38, v38
	v_fmac_f32_e32 v161, v47, v47
	v_fmac_f32_e32 v189, v39, v39
	v_add_f32_e32 v161, v161, v189
	s_waitcnt vmcnt(2)
	v_lshlrev_b32_e32 v136, 16, v172
	v_and_b32_e32 v137, s63, v172
	v_pk_add_f32 v[28:29], v[28:29], v[136:137]
	v_lshlrev_b32_e32 v138, 16, v173
	v_and_b32_e32 v139, s63, v173
	v_pk_add_f32 v[30:31], v[30:31], v[138:139]
	v_lshlrev_b32_e32 v190, 16, v174
	v_and_b32_e32 v191, s63, v174
	v_pk_add_f32 v[24:25], v[24:25], v[190:191]
	v_lshlrev_b32_e32 v136, 16, v175
	v_and_b32_e32 v137, s63, v175
	v_pk_add_f32 v[26:27], v[26:27], v[136:137]
	v_lshlrev_b32_e32 v138, 16, v176
	v_and_b32_e32 v139, s63, v176
	v_pk_add_f32 v[20:21], v[20:21], v[138:139]
	v_lshlrev_b32_e32 v190, 16, v177
	v_and_b32_e32 v191, s63, v177
	v_pk_add_f32 v[22:23], v[22:23], v[190:191]
	v_lshlrev_b32_e32 v136, 16, v178
	v_and_b32_e32 v137, s63, v178
	v_pk_add_f32 v[16:17], v[16:17], v[136:137]
	v_lshlrev_b32_e32 v138, 16, v179
	v_and_b32_e32 v139, s63, v179
	v_pk_add_f32 v[18:19], v[18:19], v[138:139]
	v_mul_f32_e32 v162, v24, v24
	v_mul_f32_e32 v189, v16, v16
	v_fmac_f32_e32 v162, v25, v25
	v_fmac_f32_e32 v189, v17, v17
	v_fmac_f32_e32 v162, v26, v26
	v_fmac_f32_e32 v189, v18, v18
	v_fmac_f32_e32 v162, v27, v27
	v_fmac_f32_e32 v189, v19, v19
	v_fmac_f32_e32 v162, v28, v28
	v_fmac_f32_e32 v189, v20, v20
	v_fmac_f32_e32 v162, v29, v29
	v_fmac_f32_e32 v189, v21, v21
	v_fmac_f32_e32 v162, v30, v30
	v_fmac_f32_e32 v189, v22, v22
	v_fmac_f32_e32 v162, v31, v31
	v_fmac_f32_e32 v189, v23, v23
	v_add_f32_e32 v162, v162, v189
	s_waitcnt vmcnt(0)
	v_lshlrev_b32_e32 v190, 16, v180
	v_and_b32_e32 v191, s63, v180
	v_pk_add_f32 v[12:13], v[12:13], v[190:191]
	v_lshlrev_b32_e32 v136, 16, v181
	v_and_b32_e32 v137, s63, v181
	v_pk_add_f32 v[14:15], v[14:15], v[136:137]
	v_lshlrev_b32_e32 v138, 16, v182
	v_and_b32_e32 v139, s63, v182
	v_pk_add_f32 v[8:9], v[8:9], v[138:139]
	v_lshlrev_b32_e32 v190, 16, v183
	v_and_b32_e32 v191, s63, v183
	v_pk_add_f32 v[10:11], v[10:11], v[190:191]
	v_lshlrev_b32_e32 v136, 16, v184
	v_and_b32_e32 v137, s63, v184
	v_pk_add_f32 v[4:5], v[4:5], v[136:137]
	v_lshlrev_b32_e32 v138, 16, v185
	v_and_b32_e32 v139, s63, v185
	v_pk_add_f32 v[6:7], v[6:7], v[138:139]
	v_lshlrev_b32_e32 v190, 16, v186
	v_and_b32_e32 v191, s63, v186
	v_pk_add_f32 v[0:1], v[0:1], v[190:191]
	v_lshlrev_b32_e32 v136, 16, v187
	v_and_b32_e32 v137, s63, v187
	v_pk_add_f32 v[2:3], v[2:3], v[136:137]
	v_mul_f32_e32 v163, v8, v8
	v_mul_f32_e32 v189, v0, v0
	v_fmac_f32_e32 v163, v9, v9
	v_fmac_f32_e32 v189, v1, v1
	v_fmac_f32_e32 v163, v10, v10
	v_fmac_f32_e32 v189, v2, v2
	v_fmac_f32_e32 v163, v11, v11
	v_fmac_f32_e32 v189, v3, v3
	v_fmac_f32_e32 v163, v12, v12
	v_fmac_f32_e32 v189, v4, v4
	v_fmac_f32_e32 v163, v13, v13
	v_fmac_f32_e32 v189, v5, v5
	v_fmac_f32_e32 v163, v14, v14
	v_fmac_f32_e32 v189, v6, v6
	v_fmac_f32_e32 v163, v15, v15
	v_fmac_f32_e32 v189, v7, v7
	v_add_f32_e32 v163, v163, v189
	ds_bpermute_b32 v136, v134, v156
	ds_bpermute_b32 v137, v134, v157
	ds_bpermute_b32 v138, v134, v158
	ds_bpermute_b32 v139, v134, v159
	ds_bpermute_b32 v188, v134, v160
	ds_bpermute_b32 v189, v134, v161
	ds_bpermute_b32 v190, v134, v162
	ds_bpermute_b32 v191, v134, v163
	s_waitcnt lgkmcnt(0)
	v_add_f32_e32 v156, v156, v136
	v_add_f32_e32 v157, v157, v137
	v_add_f32_e32 v158, v158, v138
	v_add_f32_e32 v159, v159, v139
	v_add_f32_e32 v160, v160, v188
	v_add_f32_e32 v161, v161, v189
	v_add_f32_e32 v162, v162, v190
	v_add_f32_e32 v163, v163, v191
	ds_bpermute_b32 v136, v135, v156
	ds_bpermute_b32 v137, v135, v157
	ds_bpermute_b32 v138, v135, v158
	ds_bpermute_b32 v139, v135, v159
	ds_bpermute_b32 v188, v135, v160
	ds_bpermute_b32 v189, v135, v161
	ds_bpermute_b32 v190, v135, v162
	ds_bpermute_b32 v191, v135, v163
	s_waitcnt lgkmcnt(0)
	v_add_f32_e32 v156, v156, v136
	v_add_f32_e32 v157, v157, v137
	v_add_f32_e32 v158, v158, v138
	v_add_f32_e32 v159, v159, v139
	v_add_f32_e32 v160, v160, v188
	v_add_f32_e32 v161, v161, v189
	v_add_f32_e32 v162, v162, v190
	v_add_f32_e32 v163, v163, v191
	s_and_saveexec_b64 s[66:67], s[64:65]
	global_store_dword v130, v156, s[8:9] sc1
	global_store_dword v130, v157, s[8:9] offset:1024 sc1
	global_store_dword v130, v158, s[8:9] offset:2048 sc1
	global_store_dword v130, v159, s[8:9] offset:3072 sc1
	global_store_dword v130, v160, s[74:75] sc1
	global_store_dword v130, v161, s[74:75] offset:1024 sc1
	global_store_dword v130, v162, s[74:75] offset:2048 sc1
	global_store_dword v130, v163, s[74:75] offset:3072 sc1
	s_or_b64 exec, exec, s[66:67]
	global_load_dwordx4 v[210:213], v132, s[22:23]
	global_load_dwordx4 v[214:217], v132, s[22:23] offset:16
	global_load_dwordx4 v[218:221], v132, s[22:23] offset:128
	global_load_dwordx4 v[222:225], v132, s[22:23] offset:144
	s_waitcnt vmcnt(0)
	s_barrier
	s_barrier
	s_cmpk_gt_u32 s17, 0xff
	s_cbranch_scc1 .Lf11_w1_a
	s_and_saveexec_b64 s[40:41], s[14:15]
	s_cbranch_execz .Lf11_t0_done
	v_mov_b32_e32 v133, 0
	v_mov_b32_e32 v189, 1
	global_atomic_add v133, v189, s[78:79]
	s_mov_b32 s80, 0
